# attention O stores widened to dwordx4 via permlane16_swap pairs
# speedup vs baseline: 1.0134x; 1.0134x over previous
.LBB0_868:
.LBB0_869:
	s_add_i32 s0, 0, 0x23f94
	s_waitcnt vmcnt(0)
	v_mov_b32_e32 v0, s0
	v_mbcnt_lo_u32_b32 v58, -1, 0
	v_mbcnt_hi_u32_b32 v58, -1, v58
	ds_read_b32 v0, v0
	v_lshlrev_b32_e32 v71, 4, v58
	v_and_b32_e32 v59, 15, v58
	s_mov_b32 s1, 0
	v_ashrrev_i32_e32 v70, 4, v58
	s_waitcnt lgkmcnt(0)
	v_readfirstlane_b32 s0, v0
	s_and_b32 s4, s0, 7
	s_mul_i32 s5, s4, 0x1400000
	s_add_u32 s5, s94, s5
	s_addc_u32 s6, s95, 0
	s_lshl_b32 s4, s4, 22
	s_sub_u32 s4, 0, s4
	s_subb_u32 s7, 0, 0
	s_add_u32 s4, s5, s4
	s_addc_u32 s5, s6, s7
	s_lshl_b32 s8, s88, 10
	v_add_u32_e32 v0, s8, v71
	v_ashrrev_i32_e32 v1, 31, v0
	v_lshrrev_b32_e32 v1, 22, v1
	v_add_u32_e32 v1, v0, v1
	v_ashrrev_i32_e32 v1, 10, v1
	v_mul_i32_i24_e32 v2, 0x400, v1
	v_sub_u32_e32 v2, v0, v2
	v_lshrrev_b32_e32 v3, 4, v2
	v_bitop3_b32 v2, v3, v2, 32 bitop3:0x6c
	v_ashrrev_i32_e32 v4, 31, v2
	v_lshrrev_b32_e32 v4, 26, v4
	v_lshlrev_b32_e32 v3, 3, v1
	v_add_u32_e32 v4, v2, v4
	v_and_b32_e32 v3, -16, v3
	v_ashrrev_i32_e32 v5, 6, v4
	v_add_u32_e32 v104, v5, v3
	v_and_b32_e32 v3, 0xc0, v4
	v_lshlrev_b32_e32 v1, 5, v1
	v_sub_u32_e32 v2, v2, v3
	v_mov_b32_e32 v3, 1
	v_and_b32_e32 v1, 32, v1
	v_ashrrev_i16_sdwa v2, v3, sext(v2) dst_sel:DWORD dst_unused:UNUSED_PAD src0_sel:DWORD src1_sel:BYTE_0
	v_add_u32_sdwa v1, v1, sext(v2) dst_sel:DWORD dst_unused:UNUSED_PAD src0_sel:DWORD src1_sel:WORD_0
	v_lshlrev_b32_e32 v2, 10, v104
	v_add_u32_e32 v0, 0x2000, v0
	v_lshl_add_u32 v62, v1, 1, v2
	v_ashrrev_i32_e32 v1, 31, v0
	v_lshrrev_b32_e32 v1, 22, v1
	v_add_u32_e32 v1, v0, v1
	v_ashrrev_i32_e32 v1, 10, v1
	v_mul_i32_i24_e32 v2, 0x400, v1
	v_sub_u32_e32 v0, v0, v2
	v_lshrrev_b32_e32 v2, 4, v0
	s_lshl_b32 s6, s0, 3
	v_bitop3_b32 v0, v2, v0, 32 bitop3:0x6c
	s_and_b32 s6, s6, 56
	s_ashr_i32 s7, s0, 5
	v_ashrrev_i32_e32 v4, 31, v0
	s_add_i32 s9, s6, s7
	v_lshrrev_b32_e32 v4, 26, v4
	s_ashr_i32 s12, s9, 5
	v_lshlrev_b32_e32 v2, 3, v1
	v_add_u32_e32 v4, v0, v4
	s_bfe_u32 s0, s0, 0x20003
	s_lshl_b32 s6, s12, 2
	v_and_b32_e32 v2, -16, v2
	v_ashrrev_i32_e32 v5, 6, v4
	s_or_b32 s6, s6, s0
	v_add_u32_e32 v108, v5, v2
	v_and_b32_e32 v2, 0xffc0, v4
	s_ashr_i32 s7, s6, 31
	v_sub_u32_e32 v0, v0, v2
	s_lshl_b64 s[6:7], s[6:7], 18
	v_lshrrev_b16_e32 v2, 7, v0
	s_add_u32 s10, s94, s6
	v_and_b32_e32 v2, 1, v2
	s_addc_u32 s11, s95, s7
	v_lshlrev_b32_e32 v1, 5, v1
	v_add_u16_e32 v0, v0, v2
	s_add_u32 s6, s10, 0x11400000
	v_and_b32_e32 v1, 32, v1
	v_ashrrev_i16_sdwa v0, v3, sext(v0) dst_sel:DWORD dst_unused:UNUSED_PAD src0_sel:DWORD src1_sel:BYTE_0
	s_addc_u32 s7, s11, 0
	s_lshl_b32 s9, s9, 7
	v_add_u32_sdwa v0, v1, sext(v0) dst_sel:DWORD dst_unused:UNUSED_PAD src0_sel:DWORD src1_sel:WORD_0
	v_lshlrev_b32_e32 v1, 10, v108
	s_lshl_b32 s12, s12, 12
	s_and_b32 s9, s9, 0xf80
	v_lshl_add_u32 v64, v0, 1, v1
	v_lshl_or_b32 v1, s88, 4, v59
	s_or_b32 s9, s12, s9
	v_add_u32_e32 v2, s9, v1
	v_ashrrev_i32_e32 v3, 31, v2
	v_lshlrev_b64 v[2:3], 12, v[2:3]
	s_lshl_b32 s0, s0, 10
	v_lshl_add_u64 v[2:3], s[4:5], 0, v[2:3]
	v_lshlrev_b32_e32 v0, 3, v70
	v_lshl_add_u64 v[2:3], v[2:3], 0, s[0:1]
	s_mov_b64 s[0:1], 0x13000000
	v_ashrrev_i32_e32 v1, 31, v0
	v_lshl_add_u64 v[60:61], v[2:3], 0, s[0:1]
	v_lshl_add_u64 v[0:1], v[0:1], 1, v[60:61]
	s_mov_b64 s[0:1], 0xc00000
	v_lshl_add_u64 v[2:3], v[0:1], 0, s[0:1]
	s_mov_b32 s0, 0xc00000
	v_add_co_u32_e32 v0, vcc, s0, v0
	s_add_i32 s22, s8, 0
	s_nop 0
	v_addc_co_u32_e32 v1, vcc, 0, v1, vcc
	v_mov_b32_e32 v63, 0
	s_mov_b32 m0, s22
	s_add_i32 s21, s22, 0x2000
	global_load_dwordx4 v[72:75], v[2:3], off offset:64
	global_load_dwordx4 v[52:55], v[2:3], off offset:128
	global_load_dwordx4 v[48:51], v[2:3], off offset:192
	global_load_dwordx4 v[44:47], v[2:3], off offset:256
	global_load_dwordx4 v[40:43], v[2:3], off offset:320
	global_load_dwordx4 v[36:39], v[2:3], off offset:384
	global_load_dwordx4 v[32:35], v[2:3], off offset:448
	global_load_dwordx4 v[28:31], v[2:3], off offset:512
	global_load_dwordx4 v[24:27], v[2:3], off offset:576
	global_load_dwordx4 v[20:23], v[2:3], off offset:640
	global_load_dwordx4 v[16:19], v[2:3], off offset:704
	global_load_dwordx4 v[12:15], v[2:3], off offset:768
	global_load_dwordx4 v[8:11], v[2:3], off offset:832
	global_load_dwordx4 v[4:7], v[2:3], off offset:896
	global_load_dwordx4 v[76:79], v[0:1], off
	s_nop 0
	global_load_dwordx4 v[0:3], v[2:3], off offset:960
	v_mov_b32_e32 v65, v63
	global_load_lds_dwordx4 v62, s[6:7]
	v_mov_b32_e32 v240, v62
	s_mov_b32 m0, s21
	v_lshl_add_u64 v[66:67], s[6:7], 0, v[62:63]
	v_lshl_add_u64 v[68:69], s[6:7], 0, v[64:65]
	global_load_lds_dwordx4 v64, s[6:7]
	s_add_i32 s20, s22, 0x4000
	s_mov_b64 s[6:7], 0x80
	s_add_i32 s23, s22, 0x6000
	v_lshl_add_u64 v[56:57], v[66:67], 0, s[6:7]
	s_mov_b32 m0, s20
	s_add_u32 s0, s10, 0x11420000
	global_load_lds_dwordx4 v[56:57], off
	v_lshl_add_u64 v[56:57], v[68:69], 0, s[6:7]
	s_mov_b32 m0, s23
	s_addc_u32 s1, s11, 0
	s_add_i32 s24, s22, 0x8000
	global_load_lds_dwordx4 v[56:57], off
	s_mov_b32 m0, s24
	s_add_i32 s25, s22, 0xa000
	global_load_lds_dwordx4 v62, s[0:1]
	s_mov_b32 m0, s25
	s_mov_b64 s[4:5], 0x180
	global_load_lds_dwordx4 v64, s[0:1]
	s_add_u32 s0, s10, 0x11420080
	s_addc_u32 s1, s11, 0
	s_add_i32 s26, s22, 0xc000
	s_mov_b32 m0, s26
	s_add_i32 s27, s22, 0xe000
	global_load_lds_dwordx4 v62, s[0:1]
	s_mov_b32 m0, s27
	s_add_u32 s8, s10, 0x11c00000
	global_load_lds_dwordx4 v64, s[0:1]
	s_addc_u32 s9, s11, 0
	s_add_i32 s19, s22, 0x10000
	s_mov_b64 s[0:1], 0x100
	v_lshl_add_u64 v[56:57], v[66:67], 0, s[0:1]
	s_mov_b32 m0, s19
	s_add_i32 s13, s22, 0x12000
	s_waitcnt vmcnt(0)
	s_waitcnt vmcnt(0) lgkmcnt(0)
	s_barrier
	global_load_lds_dwordx4 v[56:57], off
	v_lshl_add_u64 v[56:57], v[68:69], 0, s[0:1]
	s_mov_b32 m0, s13
	s_add_i32 s12, s22, 0x14000
	s_add_i32 s14, s22, 0x16000
	global_load_lds_dwordx4 v[56:57], off
	v_lshl_add_u64 v[56:57], v[66:67], 0, s[4:5]
	s_mov_b32 m0, s12
	s_add_u32 s28, s10, 0x11420100
	global_load_lds_dwordx4 v[56:57], off
	v_lshl_add_u64 v[56:57], v[68:69], 0, s[4:5]
	s_mov_b32 m0, s14
	s_addc_u32 s29, s11, 0
	s_add_i32 s15, s22, 0x18000
	global_load_lds_dwordx4 v[56:57], off
	s_mov_b32 m0, s15
	s_add_i32 s16, s22, 0x1a000
	global_load_lds_dwordx4 v62, s[28:29]
	s_mov_b32 m0, s16
	v_and_b32_e32 v57, 48, v58
	global_load_lds_dwordx4 v64, s[28:29]
	s_add_u32 s28, s10, 0x11420180
	s_addc_u32 s29, s11, 0
	s_add_i32 s17, s22, 0x1c000
	s_mov_b32 m0, s17
	s_add_i32 s18, s22, 0x1e000
	global_load_lds_dwordx4 v62, s[28:29]
	s_mov_b32 m0, s18
	v_lshlrev_b32_e32 v58, 2, v58
	global_load_lds_dwordx4 v64, s[28:29]
	v_lshlrev_b32_e32 v56, 6, v59
	v_and_b32_e32 v58, 32, v58
	v_bitop3_b32 v56, v56, v58, v57 bitop3:0x36
	v_and_b32_e32 v57, 0xfffffc00, v71
	v_add3_u32 v65, 0, v56, v57
	v_mov_b32_e32 v71, v65
	ds_read_b128 v[56:59], v71
	ds_read_b128 v[80:83], v71 offset:2048
	s_waitcnt lgkmcnt(0)
	v_mfma_f32_16x16x32_bf16 v[84:87], v[56:59], v[76:79], 0
	ds_read_b128 v[56:59], v71 offset:4096
	ds_read_b128 v[88:91], v71 offset:6144
	ds_read_b128 v[96:99], v71 offset:8192
	ds_read_b128 v[100:103], v71 offset:10240
	s_waitcnt lgkmcnt(0)
	v_mfma_f32_16x16x32_bf16 v[92:95], v[56:59], v[76:79], 0
	v_lshlrev_b32_e32 v56, 9, v104
	ds_read_b128 v[104:107], v71 offset:12288
	v_lshlrev_b32_e32 v57, 9, v108
	ds_read_b128 v[108:111], v71 offset:14336
	ds_read_b128 v[112:115], v71 offset:32768
	ds_read_b128 v[116:119], v71 offset:34816
	ds_read_b128 v[120:123], v71 offset:36864
	ds_read_b128 v[124:127], v71 offset:38912
	ds_read_b128 v[128:131], v71 offset:40960
	ds_read_b128 v[132:135], v71 offset:43008
	ds_read_b128 v[136:139], v71 offset:45056
	ds_read_b128 v[140:143], v71 offset:47104
	v_mfma_f32_16x16x32_bf16 v[80:83], v[80:83], v[76:79], 0
	v_sub_u32_e32 v56, v62, v56
	v_mov_b32_e32 v241, v56
	v_sub_u32_e32 v58, v64, v57
	v_mfma_f32_16x16x32_bf16 v[88:91], v[88:91], v[76:79], 0
	v_mfma_f32_16x16x32_bf16 v[96:99], v[96:99], v[76:79], 0
	v_mfma_f32_16x16x32_bf16 v[100:103], v[100:103], v[76:79], 0
	s_waitcnt lgkmcnt(0)
	v_mfma_f32_16x16x32_bf16 v[104:107], v[104:107], v[76:79], 0
	v_mfma_f32_16x16x32_bf16 v[108:111], v[108:111], v[76:79], 0
	ds_read_b128 v[144:147], v71 offset:15360
	ds_read_b128 v[148:151], v71 offset:13312
	ds_read_b128 v[152:155], v71 offset:11264
	ds_read_b128 v[156:159], v71 offset:9216
	ds_read_b128 v[160:163], v71 offset:7168
	ds_read_b128 v[164:167], v71 offset:5120
	ds_read_b128 v[168:171], v71 offset:3072
	ds_read_b128 v[172:175], v71 offset:1024
	v_mfma_f32_16x16x32_bf16 v[112:115], v[112:115], v[76:79], 0
	v_mfma_f32_16x16x32_bf16 v[116:119], v[116:119], v[76:79], 0
	v_mfma_f32_16x16x32_bf16 v[120:123], v[120:123], v[76:79], 0
	v_mfma_f32_16x16x32_bf16 v[124:127], v[124:127], v[76:79], 0
	v_mfma_f32_16x16x32_bf16 v[128:131], v[128:131], v[76:79], 0
	v_mfma_f32_16x16x32_bf16 v[132:135], v[132:135], v[76:79], 0
	v_mfma_f32_16x16x32_bf16 v[136:139], v[136:139], v[76:79], 0
	v_mfma_f32_16x16x32_bf16 v[76:79], v[140:143], v[76:79], 0
	s_waitcnt lgkmcnt(0)
	v_mfma_f32_16x16x32_bf16 v[84:87], v[172:175], v[72:75], v[84:87]
	v_mfma_f32_16x16x32_bf16 v[80:83], v[168:171], v[72:75], v[80:83]
	v_mfma_f32_16x16x32_bf16 v[92:95], v[164:167], v[72:75], v[92:95]
	v_mfma_f32_16x16x32_bf16 v[88:91], v[160:163], v[72:75], v[88:91]
	v_mfma_f32_16x16x32_bf16 v[96:99], v[156:159], v[72:75], v[96:99]
	v_mfma_f32_16x16x32_bf16 v[100:103], v[152:155], v[72:75], v[100:103]
	ds_read_b128 v[140:143], v71 offset:33792
	ds_read_b128 v[152:155], v71 offset:35840
	ds_read_b128 v[156:159], v71 offset:37888
	ds_read_b128 v[160:163], v71 offset:39936
	v_mfma_f32_16x16x32_bf16 v[104:107], v[148:151], v[72:75], v[104:107]
	ds_read_b128 v[148:151], v71 offset:41984
	ds_read_b128 v[164:167], v71 offset:44032
	ds_read_b128 v[168:171], v71 offset:46080
	ds_read_b128 v[172:175], v71 offset:48128
	v_mfma_f32_16x16x32_bf16 v[108:111], v[144:147], v[72:75], v[108:111]
	s_waitcnt lgkmcnt(0)
	v_mfma_f32_16x16x32_bf16 v[112:115], v[140:143], v[72:75], v[112:115]
	v_mfma_f32_16x16x32_bf16 v[116:119], v[152:155], v[72:75], v[116:119]
	v_mfma_f32_16x16x32_bf16 v[120:123], v[156:159], v[72:75], v[120:123]
	v_mfma_f32_16x16x32_bf16 v[124:127], v[160:163], v[72:75], v[124:127]
	v_mfma_f32_16x16x32_bf16 v[128:131], v[148:151], v[72:75], v[128:131]
	ds_read_b128 v[140:143], v71 offset:30720
	ds_read_b128 v[144:147], v71 offset:28672
	ds_read_b128 v[148:151], v71 offset:26624
	ds_read_b128 v[152:155], v71 offset:24576
	v_mfma_f32_16x16x32_bf16 v[132:135], v[164:167], v[72:75], v[132:135]
	v_mfma_f32_16x16x32_bf16 v[136:139], v[168:171], v[72:75], v[136:139]
	ds_read_b128 v[156:159], v71 offset:22528
	ds_read_b128 v[160:163], v71 offset:20480
	ds_read_b128 v[164:167], v71 offset:18432
	ds_read_b128 v[168:171], v71 offset:16384
	v_mfma_f32_16x16x32_bf16 v[72:75], v[172:175], v[72:75], v[76:79]
	s_waitcnt lgkmcnt(0)
	v_mfma_f32_16x16x32_bf16 v[76:79], v[168:171], v[52:55], v[84:87]
	v_mfma_f32_16x16x32_bf16 v[80:83], v[164:167], v[52:55], v[80:83]
	v_mfma_f32_16x16x32_bf16 v[84:87], v[160:163], v[52:55], v[92:95]
	v_mfma_f32_16x16x32_bf16 v[88:91], v[156:159], v[52:55], v[88:91]
	v_mfma_f32_16x16x32_bf16 v[92:95], v[152:155], v[52:55], v[96:99]
	v_mfma_f32_16x16x32_bf16 v[96:99], v[148:151], v[52:55], v[100:103]
	s_nop 2
	ds_read_b128 v[100:103], v71 offset:49152
	ds_read_b128 v[148:151], v71 offset:51200
	ds_read_b128 v[152:155], v71 offset:53248
	ds_read_b128 v[156:159], v71 offset:55296
	v_mfma_f32_16x16x32_bf16 v[104:107], v[144:147], v[52:55], v[104:107]
	ds_read_b128 v[144:147], v71 offset:57344
	ds_read_b128 v[160:163], v71 offset:59392
	ds_read_b128 v[164:167], v71 offset:61440
	ds_read_b128 v[168:171], v71 offset:63488
	v_mfma_f32_16x16x32_bf16 v[108:111], v[140:143], v[52:55], v[108:111]
	s_waitcnt lgkmcnt(0)
	v_mfma_f32_16x16x32_bf16 v[100:103], v[100:103], v[52:55], v[112:115]
	v_mfma_f32_16x16x32_bf16 v[112:115], v[148:151], v[52:55], v[116:119]
	v_mfma_f32_16x16x32_bf16 v[116:119], v[152:155], v[52:55], v[120:123]
	v_mfma_f32_16x16x32_bf16 v[120:123], v[156:159], v[52:55], v[124:127]
	v_mfma_f32_16x16x32_bf16 v[124:127], v[144:147], v[52:55], v[128:131]
	v_mfma_f32_16x16x32_bf16 v[128:131], v[160:163], v[52:55], v[132:135]
	s_nop 2
	ds_read_b128 v[132:135], v71 offset:31744
	ds_read_b128 v[140:143], v71 offset:29696
	ds_read_b128 v[144:147], v71 offset:27648
	ds_read_b128 v[148:151], v71 offset:25600
	v_mfma_f32_16x16x32_bf16 v[136:139], v[164:167], v[52:55], v[136:139]
	ds_read_b128 v[152:155], v71 offset:23552
	ds_read_b128 v[156:159], v71 offset:21504
	ds_read_b128 v[160:163], v71 offset:19456
	ds_read_b128 v[164:167], v71 offset:17408
	v_mfma_f32_16x16x32_bf16 v[52:55], v[168:171], v[52:55], v[72:75]
	s_waitcnt lgkmcnt(0)
	v_mfma_f32_16x16x32_bf16 v[72:75], v[164:167], v[48:51], v[76:79]
	v_mfma_f32_16x16x32_bf16 v[76:79], v[160:163], v[48:51], v[80:83]
	v_mfma_f32_16x16x32_bf16 v[80:83], v[156:159], v[48:51], v[84:87]
	v_mfma_f32_16x16x32_bf16 v[84:87], v[152:155], v[48:51], v[88:91]
	v_mfma_f32_16x16x32_bf16 v[88:91], v[148:151], v[48:51], v[92:95]
	v_mfma_f32_16x16x32_bf16 v[92:95], v[144:147], v[48:51], v[96:99]
	s_nop 2
	ds_read_b128 v[96:99], v71 offset:50176
	ds_read_b128 v[144:147], v71 offset:52224
	ds_read_b128 v[148:151], v71 offset:54272
	ds_read_b128 v[152:155], v71 offset:56320
	v_mfma_f32_16x16x32_bf16 v[104:107], v[140:143], v[48:51], v[104:107]
	ds_read_b128 v[140:143], v71 offset:58368
	ds_read_b128 v[156:159], v71 offset:60416
	ds_read_b128 v[160:163], v71 offset:62464
	ds_read_b128 v[164:167], v71 offset:64512
	v_mfma_f32_16x16x32_bf16 v[108:111], v[132:135], v[48:51], v[108:111]
	s_waitcnt lgkmcnt(0)
	v_mfma_f32_16x16x32_bf16 v[96:99], v[96:99], v[48:51], v[100:103]
	v_mfma_f32_16x16x32_bf16 v[100:103], v[144:147], v[48:51], v[112:115]
	v_mfma_f32_16x16x32_bf16 v[112:115], v[148:151], v[48:51], v[116:119]
	v_mfma_f32_16x16x32_bf16 v[116:119], v[152:155], v[48:51], v[120:123]
	v_mfma_f32_16x16x32_bf16 v[120:123], v[140:143], v[48:51], v[124:127]
	v_mfma_f32_16x16x32_bf16 v[124:127], v[156:159], v[48:51], v[128:131]
	v_mfma_f32_16x16x32_bf16 v[128:131], v[160:163], v[48:51], v[136:139]
	v_mfma_f32_16x16x32_bf16 v[50:53], v[164:167], v[48:51], v[52:55]
	s_waitcnt vmcnt(0)
	s_waitcnt vmcnt(0)
	s_barrier
	v_add_u32_e32 v48, 0x10000, v65
	v_mov_b32_e32 v49, v48
	ds_read_b128 v[132:135], v49
	ds_read_b128 v[136:139], v49 offset:2048
	s_waitcnt lgkmcnt(0)
	v_mfma_f32_16x16x32_bf16 v[72:75], v[132:135], v[44:47], v[72:75]
	ds_read_b128 v[132:135], v49 offset:4096
	v_mfma_f32_16x16x32_bf16 v[76:79], v[136:139], v[44:47], v[76:79]
	ds_read_b128 v[136:139], v49 offset:6144
	s_waitcnt lgkmcnt(0)
	v_mfma_f32_16x16x32_bf16 v[80:83], v[132:135], v[44:47], v[80:83]
	ds_read_b128 v[132:135], v49 offset:8192
	v_mfma_f32_16x16x32_bf16 v[84:87], v[136:139], v[44:47], v[84:87]
	ds_read_b128 v[136:139], v49 offset:10240
	s_waitcnt lgkmcnt(0)
	v_mfma_f32_16x16x32_bf16 v[88:91], v[132:135], v[44:47], v[88:91]
	ds_read_b128 v[132:135], v49 offset:12288
	ds_read_b128 v[140:143], v49 offset:14336
	v_mfma_f32_16x16x32_bf16 v[92:95], v[136:139], v[44:47], v[92:95]
	ds_read_b128 v[136:139], v49 offset:32768
	ds_read_b128 v[144:147], v49 offset:34816
	ds_read_b128 v[148:151], v49 offset:36864
	ds_read_b128 v[152:155], v49 offset:38912
	s_waitcnt lgkmcnt(0)
	v_mfma_f32_16x16x32_bf16 v[104:107], v[132:135], v[44:47], v[104:107]
	ds_read_b128 v[132:135], v49 offset:40960
	ds_read_b128 v[156:159], v49 offset:43008
	ds_read_b128 v[160:163], v49 offset:45056
	ds_read_b128 v[164:167], v49 offset:47104
	v_mfma_f32_16x16x32_bf16 v[108:111], v[140:143], v[44:47], v[108:111]
	s_add_u32 s100, s10, 0x11400200
	s_addc_u32 s101, s11, 0
	s_mov_b32 m0, s22
	s_nop 0
	global_load_lds_dwordx4 v240, s[100:101]
	v_mfma_f32_16x16x32_bf16 v[96:99], v[136:139], v[44:47], v[96:99]
	v_mfma_f32_16x16x32_bf16 v[100:103], v[144:147], v[44:47], v[100:103]
	v_mfma_f32_16x16x32_bf16 v[112:115], v[148:151], v[44:47], v[112:115]
	v_mfma_f32_16x16x32_bf16 v[116:119], v[152:155], v[44:47], v[116:119]
	s_waitcnt lgkmcnt(0)
	v_mfma_f32_16x16x32_bf16 v[120:123], v[132:135], v[44:47], v[120:123]
	ds_read_b128 v[132:135], v49 offset:15360
	ds_read_b128 v[136:139], v49 offset:13312
	ds_read_b128 v[140:143], v49 offset:11264
	ds_read_b128 v[144:147], v49 offset:9216
	v_mfma_f32_16x16x32_bf16 v[124:127], v[156:159], v[44:47], v[124:127]
	v_mfma_f32_16x16x32_bf16 v[128:131], v[160:163], v[44:47], v[128:131]
	ds_read_b128 v[148:151], v49 offset:7168
	ds_read_b128 v[152:155], v49 offset:5120
	ds_read_b128 v[156:159], v49 offset:3072
	ds_read_b128 v[160:163], v49 offset:1024
	v_mfma_f32_16x16x32_bf16 v[44:47], v[164:167], v[44:47], v[50:53]
	s_add_u32 s100, s10, 0x11410200
	s_addc_u32 s101, s11, 0
	s_mov_b32 m0, s21
	s_nop 0
	global_load_lds_dwordx4 v240, s[100:101]
	s_waitcnt lgkmcnt(0)
	v_mfma_f32_16x16x32_bf16 v[50:53], v[160:163], v[40:43], v[72:75]
	v_mfma_f32_16x16x32_bf16 v[72:75], v[156:159], v[40:43], v[76:79]
	v_mfma_f32_16x16x32_bf16 v[76:79], v[152:155], v[40:43], v[80:83]
	v_mfma_f32_16x16x32_bf16 v[80:83], v[148:151], v[40:43], v[84:87]
	v_mfma_f32_16x16x32_bf16 v[84:87], v[144:147], v[40:43], v[88:91]
	v_mfma_f32_16x16x32_bf16 v[88:91], v[140:143], v[40:43], v[92:95]
	s_nop 2
	ds_read_b128 v[92:95], v49 offset:33792
	ds_read_b128 v[140:143], v49 offset:35840
	ds_read_b128 v[144:147], v49 offset:37888
	ds_read_b128 v[148:151], v49 offset:39936
	v_mfma_f32_16x16x32_bf16 v[104:107], v[136:139], v[40:43], v[104:107]
	ds_read_b128 v[136:139], v49 offset:41984
	ds_read_b128 v[152:155], v49 offset:44032
	ds_read_b128 v[156:159], v49 offset:46080
	ds_read_b128 v[160:163], v49 offset:48128
	v_mfma_f32_16x16x32_bf16 v[108:111], v[132:135], v[40:43], v[108:111]
	s_add_u32 s100, s10, 0x11400280
	s_addc_u32 s101, s11, 0
	s_mov_b32 m0, s20
	s_nop 0
	global_load_lds_dwordx4 v240, s[100:101]
	s_waitcnt lgkmcnt(0)
	v_mfma_f32_16x16x32_bf16 v[92:95], v[92:95], v[40:43], v[96:99]
	v_mfma_f32_16x16x32_bf16 v[96:99], v[140:143], v[40:43], v[100:103]
	v_mfma_f32_16x16x32_bf16 v[100:103], v[144:147], v[40:43], v[112:115]
	v_mfma_f32_16x16x32_bf16 v[112:115], v[148:151], v[40:43], v[116:119]
	v_mfma_f32_16x16x32_bf16 v[116:119], v[136:139], v[40:43], v[120:123]
	v_mfma_f32_16x16x32_bf16 v[120:123], v[152:155], v[40:43], v[124:127]
	s_nop 2
	ds_read_b128 v[124:127], v49 offset:30720
	ds_read_b128 v[132:135], v49 offset:28672
	ds_read_b128 v[136:139], v49 offset:26624
	ds_read_b128 v[140:143], v49 offset:24576
	v_mfma_f32_16x16x32_bf16 v[128:131], v[156:159], v[40:43], v[128:131]
	ds_read_b128 v[144:147], v49 offset:22528
	ds_read_b128 v[148:151], v49 offset:20480
	ds_read_b128 v[152:155], v49 offset:18432
	ds_read_b128 v[156:159], v49 offset:16384
	v_mfma_f32_16x16x32_bf16 v[40:43], v[160:163], v[40:43], v[44:47]
	s_add_u32 s100, s10, 0x11410280
	s_addc_u32 s101, s11, 0
	s_mov_b32 m0, s23
	s_nop 0
	global_load_lds_dwordx4 v240, s[100:101]
	s_waitcnt lgkmcnt(0)
	v_mfma_f32_16x16x32_bf16 v[44:47], v[156:159], v[36:39], v[50:53]
	v_mfma_f32_16x16x32_bf16 v[50:53], v[152:155], v[36:39], v[72:75]
	v_mfma_f32_16x16x32_bf16 v[72:75], v[148:151], v[36:39], v[76:79]
	v_mfma_f32_16x16x32_bf16 v[76:79], v[144:147], v[36:39], v[80:83]
	v_mfma_f32_16x16x32_bf16 v[80:83], v[140:143], v[36:39], v[84:87]
	v_mfma_f32_16x16x32_bf16 v[84:87], v[136:139], v[36:39], v[88:91]
	s_nop 2
	ds_read_b128 v[88:91], v49 offset:49152
	ds_read_b128 v[136:139], v49 offset:51200
	ds_read_b128 v[140:143], v49 offset:53248
	ds_read_b128 v[144:147], v49 offset:55296
	v_mfma_f32_16x16x32_bf16 v[104:107], v[132:135], v[36:39], v[104:107]
	ds_read_b128 v[132:135], v49 offset:57344
	ds_read_b128 v[148:151], v49 offset:59392
	ds_read_b128 v[152:155], v49 offset:61440
	ds_read_b128 v[156:159], v49 offset:63488
	v_mfma_f32_16x16x32_bf16 v[108:111], v[124:127], v[36:39], v[108:111]
	s_add_u32 s100, s10, 0x11420200
	s_addc_u32 s101, s11, 0
	s_mov_b32 m0, s24
	s_nop 0
	global_load_lds_dwordx4 v240, s[100:101]
	s_waitcnt lgkmcnt(0)
	v_mfma_f32_16x16x32_bf16 v[88:91], v[88:91], v[36:39], v[92:95]
	v_mfma_f32_16x16x32_bf16 v[92:95], v[136:139], v[36:39], v[96:99]
	v_mfma_f32_16x16x32_bf16 v[96:99], v[140:143], v[36:39], v[100:103]
	v_mfma_f32_16x16x32_bf16 v[100:103], v[144:147], v[36:39], v[112:115]
	v_mfma_f32_16x16x32_bf16 v[112:115], v[132:135], v[36:39], v[116:119]
	v_mfma_f32_16x16x32_bf16 v[116:119], v[148:151], v[36:39], v[120:123]
	s_nop 2
	ds_read_b128 v[120:123], v49 offset:31744
	ds_read_b128 v[124:127], v49 offset:29696
	ds_read_b128 v[132:135], v49 offset:27648
	ds_read_b128 v[136:139], v49 offset:25600
	v_mfma_f32_16x16x32_bf16 v[128:131], v[152:155], v[36:39], v[128:131]
	ds_read_b128 v[140:143], v49 offset:23552
	ds_read_b128 v[144:147], v49 offset:21504
	ds_read_b128 v[148:151], v49 offset:19456
	ds_read_b128 v[152:155], v49 offset:17408
	v_mfma_f32_16x16x32_bf16 v[36:39], v[156:159], v[36:39], v[40:43]
	s_add_u32 s100, s10, 0x11430200
	s_addc_u32 s101, s11, 0
	s_mov_b32 m0, s25
	s_nop 0
	global_load_lds_dwordx4 v240, s[100:101]
	s_waitcnt lgkmcnt(0)
	v_mfma_f32_16x16x32_bf16 v[40:43], v[152:155], v[32:35], v[44:47]
	v_mfma_f32_16x16x32_bf16 v[44:47], v[148:151], v[32:35], v[50:53]
	v_mfma_f32_16x16x32_bf16 v[50:53], v[144:147], v[32:35], v[72:75]
	v_mfma_f32_16x16x32_bf16 v[72:75], v[140:143], v[32:35], v[76:79]
	v_mfma_f32_16x16x32_bf16 v[76:79], v[136:139], v[32:35], v[80:83]
	v_mfma_f32_16x16x32_bf16 v[80:83], v[132:135], v[32:35], v[84:87]
	s_nop 2
	ds_read_b128 v[84:87], v49 offset:50176
	ds_read_b128 v[132:135], v49 offset:52224
	ds_read_b128 v[136:139], v49 offset:54272
	ds_read_b128 v[140:143], v49 offset:56320
	v_mfma_f32_16x16x32_bf16 v[104:107], v[124:127], v[32:35], v[104:107]
	ds_read_b128 v[124:127], v49 offset:58368
	ds_read_b128 v[144:147], v49 offset:60416
	ds_read_b128 v[148:151], v49 offset:62464
	ds_read_b128 v[152:155], v49 offset:64512
	v_mfma_f32_16x16x32_bf16 v[108:111], v[120:123], v[32:35], v[108:111]
	s_add_u32 s100, s10, 0x11420280
	s_addc_u32 s101, s11, 0
	s_mov_b32 m0, s26
	s_nop 0
	global_load_lds_dwordx4 v240, s[100:101]
	s_waitcnt lgkmcnt(0)
	v_mfma_f32_16x16x32_bf16 v[84:87], v[84:87], v[32:35], v[88:91]
	v_mfma_f32_16x16x32_bf16 v[88:91], v[132:135], v[32:35], v[92:95]
	v_mfma_f32_16x16x32_bf16 v[92:95], v[136:139], v[32:35], v[96:99]
	v_mfma_f32_16x16x32_bf16 v[96:99], v[140:143], v[32:35], v[100:103]
	v_mfma_f32_16x16x32_bf16 v[100:103], v[124:127], v[32:35], v[112:115]
	v_mfma_f32_16x16x32_bf16 v[112:115], v[144:147], v[32:35], v[116:119]
	v_mfma_f32_16x16x32_bf16 v[116:119], v[148:151], v[32:35], v[128:131]
	v_mfma_f32_16x16x32_bf16 v[32:35], v[152:155], v[32:35], v[36:39]
	s_add_u32 s100, s10, 0x11430280
	s_addc_u32 s101, s11, 0
	s_mov_b32 m0, s27
	s_nop 0
	global_load_lds_dwordx4 v240, s[100:101]
	s_nop 0
	s_waitcnt vmcnt(0)
	s_waitcnt vmcnt(0)
	s_barrier
	v_mov_b32_e32 v49, v65
	ds_read_b128 v[36:39], v49
	ds_read_b128 v[66:69], v49 offset:2048
	s_waitcnt lgkmcnt(0)
	v_mfma_f32_16x16x32_bf16 v[36:39], v[36:39], v[28:31], v[40:43]
	s_nop 2
	ds_read_b128 v[40:43], v49 offset:4096
	v_mfma_f32_16x16x32_bf16 v[44:47], v[66:69], v[28:31], v[44:47]
	ds_read_b128 v[66:69], v49 offset:6144
	s_waitcnt lgkmcnt(0)
	v_mfma_f32_16x16x32_bf16 v[40:43], v[40:43], v[28:31], v[50:53]
	s_nop 2
	ds_read_b128 v[50:53], v49 offset:8192
	v_mfma_f32_16x16x32_bf16 v[66:69], v[66:69], v[28:31], v[72:75]
	s_nop 2
	ds_read_b128 v[72:75], v49 offset:10240
	s_waitcnt lgkmcnt(0)
	v_mfma_f32_16x16x32_bf16 v[50:53], v[50:53], v[28:31], v[76:79]
	s_nop 2
	ds_read_b128 v[76:79], v49 offset:12288
	ds_read_b128 v[120:123], v49 offset:14336
	v_mfma_f32_16x16x32_bf16 v[72:75], v[72:75], v[28:31], v[80:83]
	s_nop 2
	ds_read_b128 v[80:83], v49 offset:32768
	ds_read_b128 v[124:127], v49 offset:34816
	ds_read_b128 v[128:131], v49 offset:36864
	ds_read_b128 v[132:135], v49 offset:38912
	s_waitcnt lgkmcnt(0)
	v_mfma_f32_16x16x32_bf16 v[76:79], v[76:79], v[28:31], v[104:107]
	s_nop 2
	ds_read_b128 v[104:107], v49 offset:40960
	ds_read_b128 v[136:139], v49 offset:43008
	ds_read_b128 v[140:143], v49 offset:45056
	ds_read_b128 v[144:147], v49 offset:47104
	v_mfma_f32_16x16x32_bf16 v[108:111], v[120:123], v[28:31], v[108:111]
	s_add_u32 s100, s10, 0x11400300
	s_addc_u32 s101, s11, 0
	s_mov_b32 m0, s19
	s_nop 0
	global_load_lds_dwordx4 v240, s[100:101]
	v_mfma_f32_16x16x32_bf16 v[80:83], v[80:83], v[28:31], v[84:87]
	v_mfma_f32_16x16x32_bf16 v[84:87], v[124:127], v[28:31], v[88:91]
	v_mfma_f32_16x16x32_bf16 v[88:91], v[128:131], v[28:31], v[92:95]
	v_mfma_f32_16x16x32_bf16 v[92:95], v[132:135], v[28:31], v[96:99]
	s_waitcnt lgkmcnt(0)
	v_mfma_f32_16x16x32_bf16 v[96:99], v[104:107], v[28:31], v[100:103]
	v_mfma_f32_16x16x32_bf16 v[100:103], v[136:139], v[28:31], v[112:115]
	ds_read_b128 v[104:107], v49 offset:15360
	s_nop 1
	ds_read_b128 v[112:115], v49 offset:13312
	ds_read_b128 v[120:123], v49 offset:11264
	ds_read_b128 v[124:127], v49 offset:9216
	v_mfma_f32_16x16x32_bf16 v[116:119], v[140:143], v[28:31], v[116:119]
	ds_read_b128 v[128:131], v49 offset:7168
	ds_read_b128 v[132:135], v49 offset:5120
	ds_read_b128 v[136:139], v49 offset:3072
	ds_read_b128 v[140:143], v49 offset:1024
	v_mfma_f32_16x16x32_bf16 v[28:31], v[144:147], v[28:31], v[32:35]
	s_add_u32 s100, s10, 0x11410300
	s_addc_u32 s101, s11, 0
	s_mov_b32 m0, s13
	s_nop 0
	global_load_lds_dwordx4 v240, s[100:101]
	s_waitcnt lgkmcnt(0)
	v_mfma_f32_16x16x32_bf16 v[32:35], v[140:143], v[24:27], v[36:39]
	v_mfma_f32_16x16x32_bf16 v[36:39], v[136:139], v[24:27], v[44:47]
	v_mfma_f32_16x16x32_bf16 v[40:43], v[132:135], v[24:27], v[40:43]
	v_mfma_f32_16x16x32_bf16 v[44:47], v[128:131], v[24:27], v[66:69]
	v_mfma_f32_16x16x32_bf16 v[50:53], v[124:127], v[24:27], v[50:53]
	v_mfma_f32_16x16x32_bf16 v[66:69], v[120:123], v[24:27], v[72:75]
	s_nop 2
	ds_read_b128 v[72:75], v49 offset:33792
	ds_read_b128 v[120:123], v49 offset:35840
	ds_read_b128 v[124:127], v49 offset:37888
	ds_read_b128 v[128:131], v49 offset:39936
	v_mfma_f32_16x16x32_bf16 v[76:79], v[112:115], v[24:27], v[76:79]
	ds_read_b128 v[112:115], v49 offset:41984
	ds_read_b128 v[132:135], v49 offset:44032
	ds_read_b128 v[136:139], v49 offset:46080
	ds_read_b128 v[140:143], v49 offset:48128
	v_mfma_f32_16x16x32_bf16 v[104:107], v[104:107], v[24:27], v[108:111]
	s_add_u32 s100, s10, 0x11400380
	s_addc_u32 s101, s11, 0
	s_mov_b32 m0, s12
	s_nop 0
	global_load_lds_dwordx4 v240, s[100:101]
	s_waitcnt lgkmcnt(0)
	v_mfma_f32_16x16x32_bf16 v[72:75], v[72:75], v[24:27], v[80:83]
	v_mfma_f32_16x16x32_bf16 v[80:83], v[120:123], v[24:27], v[84:87]
	v_mfma_f32_16x16x32_bf16 v[84:87], v[124:127], v[24:27], v[88:91]
	v_mfma_f32_16x16x32_bf16 v[88:91], v[128:131], v[24:27], v[92:95]
	v_mfma_f32_16x16x32_bf16 v[92:95], v[112:115], v[24:27], v[96:99]
	v_mfma_f32_16x16x32_bf16 v[96:99], v[132:135], v[24:27], v[100:103]
	s_nop 2
	ds_read_b128 v[100:103], v49 offset:30720
	ds_read_b128 v[108:111], v49 offset:28672
	ds_read_b128 v[112:115], v49 offset:26624
	ds_read_b128 v[120:123], v49 offset:24576
	v_mfma_f32_16x16x32_bf16 v[116:119], v[136:139], v[24:27], v[116:119]
	ds_read_b128 v[124:127], v49 offset:22528
	ds_read_b128 v[128:131], v49 offset:20480
	ds_read_b128 v[132:135], v49 offset:18432
	ds_read_b128 v[136:139], v49 offset:16384
	v_mfma_f32_16x16x32_bf16 v[24:27], v[140:143], v[24:27], v[28:31]
	s_add_u32 s100, s10, 0x11410380
	s_addc_u32 s101, s11, 0
	s_mov_b32 m0, s14
	s_nop 0
	global_load_lds_dwordx4 v240, s[100:101]
	s_waitcnt lgkmcnt(0)
	v_mfma_f32_16x16x32_bf16 v[28:31], v[136:139], v[20:23], v[32:35]
	v_mfma_f32_16x16x32_bf16 v[32:35], v[132:135], v[20:23], v[36:39]
	v_mfma_f32_16x16x32_bf16 v[36:39], v[128:131], v[20:23], v[40:43]
	v_mfma_f32_16x16x32_bf16 v[40:43], v[124:127], v[20:23], v[44:47]
	v_mfma_f32_16x16x32_bf16 v[44:47], v[120:123], v[20:23], v[50:53]
	v_mfma_f32_16x16x32_bf16 v[50:53], v[112:115], v[20:23], v[66:69]
	s_nop 2
	ds_read_b128 v[66:69], v49 offset:49152
	ds_read_b128 v[112:115], v49 offset:51200
	ds_read_b128 v[120:123], v49 offset:53248
	ds_read_b128 v[124:127], v49 offset:55296
	v_mfma_f32_16x16x32_bf16 v[76:79], v[108:111], v[20:23], v[76:79]
	ds_read_b128 v[108:111], v49 offset:57344
	ds_read_b128 v[128:131], v49 offset:59392
	ds_read_b128 v[132:135], v49 offset:61440
	ds_read_b128 v[136:139], v49 offset:63488
	v_mfma_f32_16x16x32_bf16 v[100:103], v[100:103], v[20:23], v[104:107]
	s_add_u32 s100, s10, 0x11420300
	s_addc_u32 s101, s11, 0
	s_mov_b32 m0, s15
	s_nop 0
	global_load_lds_dwordx4 v240, s[100:101]
	s_waitcnt lgkmcnt(0)
	v_mfma_f32_16x16x32_bf16 v[66:69], v[66:69], v[20:23], v[72:75]
	v_mfma_f32_16x16x32_bf16 v[72:75], v[112:115], v[20:23], v[80:83]
	v_mfma_f32_16x16x32_bf16 v[80:83], v[120:123], v[20:23], v[84:87]
	v_mfma_f32_16x16x32_bf16 v[84:87], v[124:127], v[20:23], v[88:91]
	v_mfma_f32_16x16x32_bf16 v[88:91], v[108:111], v[20:23], v[92:95]
	v_mfma_f32_16x16x32_bf16 v[92:95], v[128:131], v[20:23], v[96:99]
	s_nop 2
	ds_read_b128 v[96:99], v49 offset:31744
	ds_read_b128 v[104:107], v49 offset:29696
	ds_read_b128 v[108:111], v49 offset:27648
	ds_read_b128 v[112:115], v49 offset:25600
	v_mfma_f32_16x16x32_bf16 v[116:119], v[132:135], v[20:23], v[116:119]
	ds_read_b128 v[120:123], v49 offset:23552
	ds_read_b128 v[124:127], v49 offset:21504
	ds_read_b128 v[128:131], v49 offset:19456
	ds_read_b128 v[132:135], v49 offset:17408
	v_mfma_f32_16x16x32_bf16 v[20:23], v[136:139], v[20:23], v[24:27]
	s_add_u32 s100, s10, 0x11430300
	s_addc_u32 s101, s11, 0
	s_mov_b32 m0, s16
	s_nop 0
	global_load_lds_dwordx4 v240, s[100:101]
	s_waitcnt lgkmcnt(0)
	v_mfma_f32_16x16x32_bf16 v[24:27], v[132:135], v[16:19], v[28:31]
	v_mfma_f32_16x16x32_bf16 v[28:31], v[128:131], v[16:19], v[32:35]
	v_mfma_f32_16x16x32_bf16 v[32:35], v[124:127], v[16:19], v[36:39]
	v_mfma_f32_16x16x32_bf16 v[36:39], v[120:123], v[16:19], v[40:43]
	v_mfma_f32_16x16x32_bf16 v[40:43], v[112:115], v[16:19], v[44:47]
	v_mfma_f32_16x16x32_bf16 v[50:53], v[108:111], v[16:19], v[50:53]
	s_nop 1
	ds_read_b128 v[44:47], v49 offset:50176
	ds_read_b128 v[108:111], v49 offset:52224
	ds_read_b128 v[112:115], v49 offset:54272
	ds_read_b128 v[120:123], v49 offset:56320
	v_mfma_f32_16x16x32_bf16 v[76:79], v[104:107], v[16:19], v[76:79]
	ds_read_b128 v[104:107], v49 offset:58368
	ds_read_b128 v[124:127], v49 offset:60416
	ds_read_b128 v[128:131], v49 offset:62464
	ds_read_b128 v[132:135], v49 offset:64512
	v_mfma_f32_16x16x32_bf16 v[96:99], v[96:99], v[16:19], v[100:103]
	s_add_u32 s100, s10, 0x11420380
	s_addc_u32 s101, s11, 0
	s_mov_b32 m0, s17
	s_nop 0
	global_load_lds_dwordx4 v240, s[100:101]
	s_waitcnt lgkmcnt(0)
	v_mfma_f32_16x16x32_bf16 v[66:69], v[44:47], v[16:19], v[66:69]
	v_mfma_f32_16x16x32_bf16 v[72:75], v[108:111], v[16:19], v[72:75]
	v_mfma_f32_16x16x32_bf16 v[80:83], v[112:115], v[16:19], v[80:83]
	v_mfma_f32_16x16x32_bf16 v[84:87], v[120:123], v[16:19], v[84:87]
	v_mfma_f32_16x16x32_bf16 v[88:91], v[104:107], v[16:19], v[88:91]
	v_mfma_f32_16x16x32_bf16 v[92:95], v[124:127], v[16:19], v[92:95]
	v_mfma_f32_16x16x32_bf16 v[100:103], v[128:131], v[16:19], v[116:119]
	v_mfma_f32_16x16x32_bf16 v[16:19], v[132:135], v[16:19], v[20:23]
	s_add_u32 s100, s10, 0x11430380
	s_addc_u32 s101, s11, 0
	s_mov_b32 m0, s18
	s_nop 0
	global_load_lds_dwordx4 v240, s[100:101]
	s_waitcnt vmcnt(0)
	s_waitcnt vmcnt(0)
	s_barrier
	v_mov_b32_e32 v49, v48
	ds_read_b128 v[20:23], v49
	ds_read_b128 v[104:107], v49 offset:2048
	s_waitcnt lgkmcnt(0)
	v_mfma_f32_16x16x32_bf16 v[20:23], v[20:23], v[12:15], v[24:27]
	s_nop 2
	ds_read_b128 v[24:27], v49 offset:4096
	v_mfma_f32_16x16x32_bf16 v[28:31], v[104:107], v[12:15], v[28:31]
	ds_read_b128 v[104:107], v49 offset:6144
	s_waitcnt lgkmcnt(0)
	v_mfma_f32_16x16x32_bf16 v[24:27], v[24:27], v[12:15], v[32:35]
	s_nop 2
	ds_read_b128 v[32:35], v49 offset:8192
	v_mfma_f32_16x16x32_bf16 v[36:39], v[104:107], v[12:15], v[36:39]
	ds_read_b128 v[104:107], v49 offset:10240
	s_waitcnt lgkmcnt(0)
	v_mfma_f32_16x16x32_bf16 v[32:35], v[32:35], v[12:15], v[40:43]
	s_nop 2
	ds_read_b128 v[40:43], v49 offset:12288
	ds_read_b128 v[108:111], v49 offset:14336
	v_mfma_f32_16x16x32_bf16 v[50:53], v[104:107], v[12:15], v[50:53]
	ds_read_b128 v[104:107], v49 offset:32768
	ds_read_b128 v[112:115], v49 offset:34816
	ds_read_b128 v[116:119], v49 offset:36864
	ds_read_b128 v[120:123], v49 offset:38912
	s_waitcnt lgkmcnt(0)
	v_mfma_f32_16x16x32_bf16 v[40:43], v[40:43], v[12:15], v[76:79]
	s_nop 2
	ds_read_b128 v[76:79], v49 offset:40960
	ds_read_b128 v[124:127], v49 offset:43008
	ds_read_b128 v[128:131], v49 offset:45056
	ds_read_b128 v[132:135], v49 offset:47104
	v_mfma_f32_16x16x32_bf16 v[96:99], v[108:111], v[12:15], v[96:99]
	s_add_u32 s100, s10, 0x11c00000
	s_addc_u32 s101, s11, 0
	s_mov_b32 m0, s22
	s_nop 0
	global_load_lds_dwordx4 v241, s[100:101]
	v_mfma_f32_16x16x32_bf16 v[66:69], v[104:107], v[12:15], v[66:69]
	v_mfma_f32_16x16x32_bf16 v[72:75], v[112:115], v[12:15], v[72:75]
	v_mfma_f32_16x16x32_bf16 v[80:83], v[116:119], v[12:15], v[80:83]
	v_mfma_f32_16x16x32_bf16 v[84:87], v[120:123], v[12:15], v[84:87]
	s_waitcnt lgkmcnt(0)
	v_mfma_f32_16x16x32_bf16 v[76:79], v[76:79], v[12:15], v[88:91]
	v_mfma_f32_16x16x32_bf16 v[88:91], v[124:127], v[12:15], v[92:95]
	s_nop 2
	ds_read_b128 v[92:95], v49 offset:15360
	ds_read_b128 v[104:107], v49 offset:13312
	ds_read_b128 v[108:111], v49 offset:11264
	ds_read_b128 v[112:115], v49 offset:9216
	v_mfma_f32_16x16x32_bf16 v[100:103], v[128:131], v[12:15], v[100:103]
	ds_read_b128 v[116:119], v49 offset:7168
	ds_read_b128 v[120:123], v49 offset:5120
	ds_read_b128 v[124:127], v49 offset:3072
	ds_read_b128 v[128:131], v49 offset:1024
	v_mfma_f32_16x16x32_bf16 v[12:15], v[132:135], v[12:15], v[16:19]
	s_add_u32 s100, s10, 0x11c08000
	s_addc_u32 s101, s11, 0
	s_mov_b32 m0, s21
	s_nop 0
	global_load_lds_dwordx4 v241, s[100:101]
	s_waitcnt lgkmcnt(0)
	v_mfma_f32_16x16x32_bf16 v[16:19], v[128:131], v[8:11], v[20:23]
	v_mfma_f32_16x16x32_bf16 v[20:23], v[124:127], v[8:11], v[28:31]
	v_mfma_f32_16x16x32_bf16 v[24:27], v[120:123], v[8:11], v[24:27]
	v_mfma_f32_16x16x32_bf16 v[28:31], v[116:119], v[8:11], v[36:39]
	v_mfma_f32_16x16x32_bf16 v[32:35], v[112:115], v[8:11], v[32:35]
	v_mfma_f32_16x16x32_bf16 v[36:39], v[108:111], v[8:11], v[50:53]
	s_nop 2
	ds_read_b128 v[50:53], v49 offset:33792
	ds_read_b128 v[108:111], v49 offset:35840
	ds_read_b128 v[112:115], v49 offset:37888
	ds_read_b128 v[116:119], v49 offset:39936
	v_mfma_f32_16x16x32_bf16 v[40:43], v[104:107], v[8:11], v[40:43]
	ds_read_b128 v[104:107], v49 offset:41984
	ds_read_b128 v[120:123], v49 offset:44032
	ds_read_b128 v[124:127], v49 offset:46080
	ds_read_b128 v[128:131], v49 offset:48128
	v_mfma_f32_16x16x32_bf16 v[92:95], v[92:95], v[8:11], v[96:99]
	s_add_u32 s100, s10, 0x11c00080
	s_addc_u32 s101, s11, 0
	s_mov_b32 m0, s20
	s_nop 0
	global_load_lds_dwordx4 v241, s[100:101]
	s_waitcnt lgkmcnt(0)
	v_mfma_f32_16x16x32_bf16 v[50:53], v[50:53], v[8:11], v[66:69]
	v_mfma_f32_16x16x32_bf16 v[66:69], v[108:111], v[8:11], v[72:75]
	v_mfma_f32_16x16x32_bf16 v[72:75], v[112:115], v[8:11], v[80:83]
	v_mfma_f32_16x16x32_bf16 v[80:83], v[116:119], v[8:11], v[84:87]
	v_mfma_f32_16x16x32_bf16 v[76:79], v[104:107], v[8:11], v[76:79]
	v_mfma_f32_16x16x32_bf16 v[84:87], v[120:123], v[8:11], v[88:91]
	s_nop 2
	ds_read_b128 v[88:91], v49 offset:30720
	ds_read_b128 v[96:99], v49 offset:28672
	ds_read_b128 v[104:107], v49 offset:26624
	ds_read_b128 v[108:111], v49 offset:24576
	v_mfma_f32_16x16x32_bf16 v[100:103], v[124:127], v[8:11], v[100:103]
	ds_read_b128 v[112:115], v49 offset:22528
	ds_read_b128 v[116:119], v49 offset:20480
	ds_read_b128 v[120:123], v49 offset:18432
	ds_read_b128 v[124:127], v49 offset:16384
	v_mfma_f32_16x16x32_bf16 v[8:11], v[128:131], v[8:11], v[12:15]
	s_add_u32 s100, s10, 0x11c08080
	s_addc_u32 s101, s11, 0
	s_mov_b32 m0, s23
	s_nop 0
	global_load_lds_dwordx4 v241, s[100:101]
	s_waitcnt lgkmcnt(0)
	v_mfma_f32_16x16x32_bf16 v[12:15], v[124:127], v[4:7], v[16:19]
	v_mfma_f32_16x16x32_bf16 v[16:19], v[120:123], v[4:7], v[20:23]
	v_mfma_f32_16x16x32_bf16 v[20:23], v[116:119], v[4:7], v[24:27]
	v_mfma_f32_16x16x32_bf16 v[24:27], v[112:115], v[4:7], v[28:31]
	v_mfma_f32_16x16x32_bf16 v[28:31], v[108:111], v[4:7], v[32:35]
	v_mfma_f32_16x16x32_bf16 v[32:35], v[104:107], v[4:7], v[36:39]
	s_nop 2
	ds_read_b128 v[36:39], v49 offset:49152
	ds_read_b128 v[104:107], v49 offset:51200
	ds_read_b128 v[108:111], v49 offset:53248
	ds_read_b128 v[112:115], v49 offset:55296
	v_mfma_f32_16x16x32_bf16 v[96:99], v[96:99], v[4:7], v[40:43]
	s_nop 2
	ds_read_b128 v[40:43], v49 offset:57344
	ds_read_b128 v[116:119], v49 offset:59392
	ds_read_b128 v[120:123], v49 offset:61440
	ds_read_b128 v[124:127], v49 offset:63488
	v_mfma_f32_16x16x32_bf16 v[88:91], v[88:91], v[4:7], v[92:95]
	s_add_u32 s100, s10, 0x11c10000
	s_addc_u32 s101, s11, 0
	s_mov_b32 m0, s24
	s_nop 0
	global_load_lds_dwordx4 v241, s[100:101]
	s_waitcnt lgkmcnt(0)
	v_mfma_f32_16x16x32_bf16 v[50:53], v[36:39], v[4:7], v[50:53]
	v_mfma_f32_16x16x32_bf16 v[66:69], v[104:107], v[4:7], v[66:69]
	v_mfma_f32_16x16x32_bf16 v[72:75], v[108:111], v[4:7], v[72:75]
	v_mfma_f32_16x16x32_bf16 v[80:83], v[112:115], v[4:7], v[80:83]
	v_mfma_f32_16x16x32_bf16 v[76:79], v[40:43], v[4:7], v[76:79]
	ds_read_b128 v[92:95], v49 offset:31744
	ds_read_b128 v[36:39], v49 offset:29696
	ds_read_b128 v[40:43], v49 offset:27648
	ds_read_b128 v[104:107], v49 offset:25600
	v_mfma_f32_16x16x32_bf16 v[84:87], v[116:119], v[4:7], v[84:87]
	v_mfma_f32_16x16x32_bf16 v[100:103], v[120:123], v[4:7], v[100:103]
	ds_read_b128 v[108:111], v49 offset:23552
	ds_read_b128 v[112:115], v49 offset:21504
	ds_read_b128 v[116:119], v49 offset:19456
	ds_read_b128 v[120:123], v49 offset:17408
	v_mfma_f32_16x16x32_bf16 v[124:127], v[124:127], v[4:7], v[8:11]
	s_add_u32 s100, s10, 0x11c18000
	s_addc_u32 s101, s11, 0
	s_mov_b32 m0, s25
	s_nop 0
	global_load_lds_dwordx4 v241, s[100:101]
	s_waitcnt lgkmcnt(0)
	v_mfma_f32_16x16x32_bf16 v[120:123], v[120:123], v[0:3], v[12:15]
	v_mfma_f32_16x16x32_bf16 v[116:119], v[116:119], v[0:3], v[16:19]
	ds_read_b128 v[4:7], v49 offset:50176
	ds_read_b128 v[8:11], v49 offset:52224
	ds_read_b128 v[12:15], v49 offset:54272
	ds_read_b128 v[16:19], v49 offset:56320
	v_mfma_f32_16x16x32_bf16 v[36:39], v[36:39], v[0:3], v[96:99]
	s_nop 2
	ds_read_b128 v[96:99], v49 offset:58368
	ds_read_b128 v[128:131], v49 offset:60416
	ds_read_b128 v[132:135], v49 offset:62464
	ds_read_b128 v[136:139], v49 offset:64512
	v_mfma_f32_16x16x32_bf16 v[112:115], v[112:115], v[0:3], v[20:23]
	v_mfma_f32_16x16x32_bf16 v[108:111], v[108:111], v[0:3], v[24:27]
	v_mfma_f32_16x16x32_bf16 v[104:107], v[104:107], v[0:3], v[28:31]
	v_mfma_f32_16x16x32_bf16 v[40:43], v[40:43], v[0:3], v[32:35]
	v_mfma_f32_16x16x32_bf16 v[32:35], v[92:95], v[0:3], v[88:91]
	s_add_u32 s100, s10, 0x11c10080
	s_addc_u32 s101, s11, 0
	s_mov_b32 m0, s26
	s_nop 0
	global_load_lds_dwordx4 v241, s[100:101]
	s_waitcnt lgkmcnt(0)
	v_mfma_f32_16x16x32_bf16 v[28:31], v[4:7], v[0:3], v[50:53]
	v_mfma_f32_16x16x32_bf16 v[24:27], v[8:11], v[0:3], v[66:69]
	v_mfma_f32_16x16x32_bf16 v[20:23], v[12:15], v[0:3], v[72:75]
	v_mfma_f32_16x16x32_bf16 v[16:19], v[16:19], v[0:3], v[80:83]
	v_mfma_f32_16x16x32_bf16 v[12:15], v[96:99], v[0:3], v[76:79]
	v_mfma_f32_16x16x32_bf16 v[8:11], v[128:131], v[0:3], v[84:87]
	v_mfma_f32_16x16x32_bf16 v[4:7], v[132:135], v[0:3], v[100:103]
	v_mfma_f32_16x16x32_bf16 v[0:3], v[136:139], v[0:3], v[124:127]
	s_add_u32 s100, s10, 0x11c18080
	s_addc_u32 s101, s11, 0
	s_mov_b32 m0, s27
	s_nop 0
	global_load_lds_dwordx4 v241, s[100:101]
	v_max_f32_e32 v49, v123, v123
	v_max_f32_e32 v50, v122, v122
	v_max_f32_e32 v49, v50, v49
	v_max_f32_e32 v50, v117, v117
	v_max_f32_e32 v51, v116, v116
	v_max_f32_e32 v50, v51, v50
	v_max_f32_e32 v51, v119, v119
	v_max_f32_e32 v52, v118, v118
	v_max3_f32 v49, v120, v121, v49
	v_max_f32_e32 v51, v52, v51
	v_max3_f32 v49, v49, v50, v51
	v_max_f32_e32 v50, v113, v113
	v_max_f32_e32 v51, v112, v112
	v_max_f32_e32 v50, v51, v50
	v_max_f32_e32 v51, v115, v115
	v_max_f32_e32 v52, v114, v114
	v_max_f32_e32 v51, v52, v51
	v_max3_f32 v49, v49, v50, v51
	v_max_f32_e32 v50, v109, v109
	v_max_f32_e32 v51, v108, v108
	v_max_f32_e32 v50, v51, v50
	v_max_f32_e32 v51, v111, v111
	v_max_f32_e32 v52, v110, v110
	v_max_f32_e32 v51, v52, v51
	v_max3_f32 v49, v49, v50, v51
	v_max_f32_e32 v50, v105, v105
	v_max_f32_e32 v51, v104, v104
	v_max_f32_e32 v50, v51, v50
	v_max_f32_e32 v51, v107, v107
	v_max_f32_e32 v52, v106, v106
	v_max_f32_e32 v51, v52, v51
	v_max3_f32 v49, v49, v50, v51
	v_max_f32_e32 v50, v41, v41
	v_max_f32_e32 v51, v40, v40
	v_max_f32_e32 v50, v51, v50
	v_max_f32_e32 v51, v43, v43
	v_max_f32_e32 v52, v42, v42
	v_max_f32_e32 v51, v52, v51
	v_max3_f32 v49, v49, v50, v51
	v_max_f32_e32 v50, v37, v37
	v_max_f32_e32 v51, v36, v36
	v_max_f32_e32 v50, v51, v50
	v_max_f32_e32 v51, v39, v39
	v_max_f32_e32 v52, v38, v38
	v_max_f32_e32 v51, v52, v51
	v_max3_f32 v49, v49, v50, v51
	v_max_f32_e32 v50, v33, v33
	v_max_f32_e32 v51, v32, v32
	v_max_f32_e32 v50, v51, v50
	v_max_f32_e32 v51, v35, v35
	v_max_f32_e32 v52, v34, v34
	v_max_f32_e32 v51, v52, v51
	v_max3_f32 v49, v49, v50, v51
	v_max_f32_e32 v50, v29, v29
	v_max_f32_e32 v51, v28, v28
	v_max_f32_e32 v50, v51, v50
	v_max_f32_e32 v51, v31, v31
	v_max_f32_e32 v52, v30, v30
	v_max_f32_e32 v51, v52, v51
	v_max3_f32 v49, v49, v50, v51
	v_max_f32_e32 v50, v25, v25
	v_max_f32_e32 v51, v24, v24
	v_max_f32_e32 v50, v51, v50
	v_max_f32_e32 v51, v27, v27
	v_max_f32_e32 v52, v26, v26
	v_max_f32_e32 v51, v52, v51
	v_max3_f32 v49, v49, v50, v51
	v_max_f32_e32 v50, v21, v21
	v_max_f32_e32 v51, v20, v20
	v_max_f32_e32 v50, v51, v50
	v_max_f32_e32 v51, v23, v23
	v_max_f32_e32 v52, v22, v22
	v_max_f32_e32 v51, v52, v51
	v_max3_f32 v49, v49, v50, v51
	v_max_f32_e32 v50, v17, v17
	v_max_f32_e32 v51, v16, v16
	v_max_f32_e32 v50, v51, v50
	v_max_f32_e32 v51, v19, v19
	v_max_f32_e32 v52, v18, v18
	v_max_f32_e32 v51, v52, v51
	v_max3_f32 v49, v49, v50, v51
	v_max_f32_e32 v50, v13, v13
	v_max_f32_e32 v51, v12, v12
	v_max_f32_e32 v50, v51, v50
	v_max_f32_e32 v51, v15, v15
	v_max_f32_e32 v52, v14, v14
	v_max_f32_e32 v51, v52, v51
	v_max3_f32 v49, v49, v50, v51
	v_max_f32_e32 v50, v9, v9
	v_max_f32_e32 v51, v8, v8
	v_max_f32_e32 v50, v51, v50
	v_max_f32_e32 v51, v11, v11
	v_max_f32_e32 v52, v10, v10
	v_max_f32_e32 v51, v52, v51
	v_max3_f32 v49, v49, v50, v51
	v_max_f32_e32 v50, v5, v5
	v_max_f32_e32 v51, v4, v4
	v_max_f32_e32 v50, v51, v50
	v_max_f32_e32 v51, v7, v7
	v_max_f32_e32 v52, v6, v6
	v_max_f32_e32 v51, v52, v51
	v_max3_f32 v49, v49, v50, v51
	v_max_f32_e32 v50, v1, v1
	v_max_f32_e32 v51, v0, v0
	v_max_f32_e32 v50, v51, v50
	v_max_f32_e32 v51, v3, v3
	v_max_f32_e32 v52, v2, v2
	v_max_f32_e32 v51, v52, v51
	v_max3_f32 v49, v49, v50, v51
	v_mbcnt_lo_u32_b32 v50, -1, 0
	v_mbcnt_hi_u32_b32 v50, -1, v50
	v_and_b32_e32 v52, 64, v50
	v_xor_b32_e32 v51, 16, v50
	v_add_u32_e32 v52, 64, v52
	v_cmp_lt_i32_e32 vcc, v51, v52
	s_nop 1
	v_cndmask_b32_e32 v51, v50, v51, vcc
	v_lshlrev_b32_e32 v51, 2, v51
	v_mov_b32_e32 v53, v49
	s_nop 1
	v_permlane16_swap_b32_e32 v53, v49
	s_waitcnt lgkmcnt(0)
	v_max_f32_e32 v53, v53, v53
	v_max_f32_e32 v49, v49, v53
	v_xor_b32_e32 v53, 32, v50
	v_cmp_lt_i32_e32 vcc, v53, v52
	s_nop 1
	v_cndmask_b32_e32 v50, v50, v53, vcc
	v_lshlrev_b32_e32 v50, 2, v50
	v_mov_b32_e32 v52, v49
	s_nop 1
	v_permlane32_swap_b32_e32 v52, v49
	s_waitcnt lgkmcnt(0)
	v_max_f32_e32 v52, v52, v52
	v_max_f32_e32 v49, v49, v52
	v_sub_f32_e32 v52, v120, v49
	v_exp_f32_e32 v52, v52
	v_sub_f32_e32 v53, v121, v49
	v_exp_f32_e32 v53, v53
	v_sub_f32_e32 v54, v122, v49
	v_exp_f32_e32 v54, v54
	v_sub_f32_e32 v55, v123, v49
	v_exp_f32_e32 v55, v55
	v_sub_f32_e32 v59, v116, v49
	v_add_f32_e32 v57, 0, v52
	v_exp_f32_e32 v59, v59
	v_sub_f32_e32 v62, v117, v49
	v_add_f32_e32 v57, v53, v57
	v_exp_f32_e32 v62, v62
	v_sub_f32_e32 v63, v118, v49
	v_add_f32_e32 v57, v54, v57
	v_exp_f32_e32 v63, v63
	v_sub_f32_e32 v64, v119, v49
	v_add_f32_e32 v57, v55, v57
	v_exp_f32_e32 v64, v64
	v_sub_f32_e32 v66, v112, v49
	v_add_f32_e32 v57, v59, v57
	v_exp_f32_e32 v66, v66
	v_sub_f32_e32 v67, v113, v49
	v_add_f32_e32 v57, v62, v57
	v_exp_f32_e32 v67, v67
	v_sub_f32_e32 v68, v114, v49
	v_add_f32_e32 v57, v63, v57
	v_exp_f32_e32 v68, v68
	v_sub_f32_e32 v69, v115, v49
	v_add_f32_e32 v57, v64, v57
	v_exp_f32_e32 v69, v69
	v_sub_f32_e32 v71, v108, v49
	v_add_f32_e32 v57, v66, v57
	v_exp_f32_e32 v71, v71
	v_sub_f32_e32 v72, v109, v49
	v_add_f32_e32 v57, v67, v57
	v_exp_f32_e32 v72, v72
	v_sub_f32_e32 v73, v110, v49
	v_add_f32_e32 v57, v68, v57
	v_exp_f32_e32 v73, v73
	v_sub_f32_e32 v74, v111, v49
	v_add_f32_e32 v57, v69, v57
	v_exp_f32_e32 v74, v74
	v_sub_f32_e32 v75, v104, v49
	v_add_f32_e32 v57, v71, v57
	v_exp_f32_e32 v75, v75
	v_sub_f32_e32 v76, v105, v49
	v_add_f32_e32 v57, v72, v57
	v_exp_f32_e32 v76, v76
	v_sub_f32_e32 v77, v106, v49
	v_add_f32_e32 v57, v73, v57
	v_exp_f32_e32 v77, v77
	v_sub_f32_e32 v78, v107, v49
	v_add_f32_e32 v57, v74, v57
	v_exp_f32_e32 v78, v78
	v_sub_f32_e32 v40, v40, v49
	v_add_f32_e32 v57, v75, v57
	v_exp_f32_e32 v40, v40
	v_sub_f32_e32 v41, v41, v49
	v_add_f32_e32 v57, v76, v57
	v_exp_f32_e32 v41, v41
	v_sub_f32_e32 v42, v42, v49
	v_add_f32_e32 v57, v77, v57
	v_exp_f32_e32 v42, v42
	v_sub_f32_e32 v43, v43, v49
	v_add_f32_e32 v57, v78, v57
	v_exp_f32_e32 v43, v43
	v_sub_f32_e32 v36, v36, v49
	v_add_f32_e32 v57, v40, v57
	v_exp_f32_e32 v36, v36
	v_sub_f32_e32 v37, v37, v49
	v_add_f32_e32 v57, v41, v57
	v_exp_f32_e32 v37, v37
	v_sub_f32_e32 v38, v38, v49
	v_add_f32_e32 v57, v42, v57
	v_exp_f32_e32 v38, v38
	v_sub_f32_e32 v39, v39, v49
	v_add_f32_e32 v57, v43, v57
	v_exp_f32_e32 v39, v39
	v_sub_f32_e32 v32, v32, v49
	v_add_f32_e32 v57, v36, v57
	v_exp_f32_e32 v32, v32
	v_sub_f32_e32 v33, v33, v49
	v_add_f32_e32 v57, v37, v57
	v_exp_f32_e32 v33, v33
	v_sub_f32_e32 v34, v34, v49
	v_add_f32_e32 v57, v38, v57
	v_exp_f32_e32 v34, v34
	v_sub_f32_e32 v35, v35, v49
	v_add_f32_e32 v57, v39, v57
	v_exp_f32_e32 v35, v35
	v_sub_f32_e32 v28, v28, v49
	v_add_f32_e32 v57, v32, v57
	v_exp_f32_e32 v79, v28
	v_sub_f32_e32 v28, v29, v49
	v_add_f32_e32 v57, v33, v57
	v_exp_f32_e32 v80, v28
	v_sub_f32_e32 v28, v30, v49
	v_add_f32_e32 v57, v34, v57
	v_exp_f32_e32 v81, v28
	v_sub_f32_e32 v28, v31, v49
	v_add_f32_e32 v57, v35, v57
	v_exp_f32_e32 v82, v28
	v_sub_f32_e32 v24, v24, v49
	v_add_f32_e32 v28, v79, v57
	v_exp_f32_e32 v57, v24
	v_sub_f32_e32 v24, v25, v49
	v_add_f32_e32 v28, v80, v28
	v_exp_f32_e32 v83, v24
	v_sub_f32_e32 v24, v26, v49
	v_add_f32_e32 v28, v81, v28
	v_exp_f32_e32 v84, v24
	v_sub_f32_e32 v24, v27, v49
	v_add_f32_e32 v28, v82, v28
	v_exp_f32_e32 v85, v24
	v_sub_f32_e32 v20, v20, v49
	v_add_f32_e32 v24, v57, v28
	v_exp_f32_e32 v86, v20
	v_sub_f32_e32 v20, v21, v49
	v_add_f32_e32 v24, v83, v24
	v_exp_f32_e32 v87, v20
	v_sub_f32_e32 v20, v22, v49
	v_add_f32_e32 v24, v84, v24
	v_exp_f32_e32 v88, v20
	v_sub_f32_e32 v20, v23, v49
	v_add_f32_e32 v24, v85, v24
	v_exp_f32_e32 v89, v20
	v_sub_f32_e32 v16, v16, v49
	v_add_f32_e32 v20, v86, v24
	v_exp_f32_e32 v90, v16
	v_sub_f32_e32 v16, v17, v49
	v_add_f32_e32 v20, v87, v20
	v_exp_f32_e32 v91, v16
	v_sub_f32_e32 v16, v18, v49
	v_add_f32_e32 v20, v88, v20
	v_exp_f32_e32 v92, v16
	v_sub_f32_e32 v16, v19, v49
	v_add_f32_e32 v20, v89, v20
	v_exp_f32_e32 v93, v16
	v_sub_f32_e32 v12, v12, v49
	v_add_f32_e32 v16, v90, v20
	v_exp_f32_e32 v94, v12
	v_sub_f32_e32 v12, v13, v49
	v_add_f32_e32 v16, v91, v16
	v_exp_f32_e32 v95, v12
	v_sub_f32_e32 v12, v14, v49
	v_add_f32_e32 v16, v92, v16
	v_exp_f32_e32 v96, v12
	v_sub_f32_e32 v12, v15, v49
	v_add_f32_e32 v16, v93, v16
	v_exp_f32_e32 v97, v12
	v_sub_f32_e32 v8, v8, v49
	v_add_f32_e32 v12, v94, v16
	v_exp_f32_e32 v98, v8
	v_sub_f32_e32 v8, v9, v49
	v_add_f32_e32 v12, v95, v12
	v_exp_f32_e32 v99, v8
	v_sub_f32_e32 v8, v10, v49
	v_add_f32_e32 v12, v96, v12
	v_exp_f32_e32 v100, v8
	v_sub_f32_e32 v8, v11, v49
	v_add_f32_e32 v12, v97, v12
	v_exp_f32_e32 v11, v8
	v_sub_f32_e32 v4, v4, v49
	v_add_f32_e32 v8, v98, v12
	v_exp_f32_e32 v101, v4
	v_sub_f32_e32 v4, v5, v49
	v_add_f32_e32 v8, v99, v8
	v_exp_f32_e32 v102, v4
	v_sub_f32_e32 v4, v6, v49
	v_add_f32_e32 v8, v100, v8
	v_exp_f32_e32 v103, v4
	v_sub_f32_e32 v4, v7, v49
	v_add_f32_e32 v8, v11, v8
	v_exp_f32_e32 v104, v4
	v_sub_f32_e32 v0, v0, v49
	v_add_f32_e32 v4, v101, v8
	v_exp_f32_e32 v105, v0
	v_sub_f32_e32 v0, v1, v49
	v_add_f32_e32 v4, v102, v4
	v_exp_f32_e32 v106, v0
	v_sub_f32_e32 v0, v2, v49
	v_add_f32_e32 v4, v103, v4
	v_exp_f32_e32 v107, v0
	v_sub_f32_e32 v0, v3, v49
	v_add_f32_e32 v4, v104, v4
	v_exp_f32_e32 v3, v0
	v_add_f32_e32 v0, v105, v4
	v_add_f32_e32 v0, v106, v0
	v_add_f32_e32 v0, v107, v0
	v_add_f32_e32 v0, v3, v0
	v_mov_b32_e32 v1, v0
	s_nop 1
	v_permlane16_swap_b32_e32 v1, v0
	v_cvt_pk_bf16_f32 v28, v52, v53
	v_cvt_pk_bf16_f32 v29, v54, v55
	v_cvt_pk_bf16_f32 v30, v59, v62
	v_cvt_pk_bf16_f32 v31, v63, v64
	s_waitcnt lgkmcnt(0)
	v_add_f32_e32 v0, v0, v1
	v_mov_b32_e32 v1, v0
	s_nop 1
	v_permlane32_swap_b32_e32 v1, v0
	v_cvt_pk_bf16_f32 v20, v66, v67
	v_cvt_pk_bf16_f32 v21, v68, v69
	v_cvt_pk_bf16_f32 v22, v71, v72
	v_cvt_pk_bf16_f32 v23, v73, v74
	s_waitcnt lgkmcnt(0)
	v_add_f32_e32 v49, v0, v1
	v_cvt_pk_bf16_f32 v24, v75, v76
	v_cvt_pk_bf16_f32 v25, v77, v78
	v_cvt_pk_bf16_f32 v26, v40, v41
	v_cvt_pk_bf16_f32 v27, v42, v43
	v_cvt_pk_bf16_f32 v16, v36, v37
	v_cvt_pk_bf16_f32 v17, v38, v39
	v_cvt_pk_bf16_f32 v18, v32, v33
	v_cvt_pk_bf16_f32 v19, v34, v35
	v_cvt_pk_bf16_f32 v12, v79, v80
	v_cvt_pk_bf16_f32 v13, v81, v82
	v_cvt_pk_bf16_f32 v14, v57, v83
	v_cvt_pk_bf16_f32 v15, v84, v85
	v_cvt_pk_bf16_f32 v4, v86, v87
	v_cvt_pk_bf16_f32 v5, v88, v89
	v_cvt_pk_bf16_f32 v6, v90, v91
	v_cvt_pk_bf16_f32 v7, v92, v93
	v_cvt_pk_bf16_f32 v8, v94, v95
	v_cvt_pk_bf16_f32 v9, v96, v97
	v_cvt_pk_bf16_f32 v10, v98, v99
	v_cvt_pk_bf16_f32 v11, v100, v11
	v_cvt_pk_bf16_f32 v0, v101, v102
	v_cvt_pk_bf16_f32 v1, v103, v104
	v_cvt_pk_bf16_f32 v2, v105, v106
	v_cvt_pk_bf16_f32 v3, v107, v3
	s_waitcnt vmcnt(0)
	s_waitcnt vmcnt(0)
	s_barrier
	v_mov_b32_e32 v64, v65
	v_div_scale_f32 v62, vcc, 1.0, v49, 1.0
	v_lshlrev_b32_e32 v54, 2, v70
	v_ashrrev_i32_e32 v55, 31, v54
	ds_read_b128 v[32:35], v64
	ds_read_b128 v[36:39], v64 offset:2048
	v_div_scale_f32 v57, s[0:1], v49, v49, 1.0
	v_rcp_f32_e32 v59, v57
	s_waitcnt lgkmcnt(0)
	v_mfma_f32_16x16x32_bf16 v[44:47], v[32:35], v[28:31], 0
	v_fma_f32 v40, -v57, v59, 1.0
	v_fmac_f32_e32 v59, v40, v59
	ds_read_b128 v[40:43], v64 offset:4096
	ds_read_b128 v[32:35], v64 offset:6144
	v_mul_f32_e32 v63, v62, v59
	v_fma_f32 v66, -v57, v63, v62
	v_fmac_f32_e32 v63, v66, v59
	v_mfma_f32_16x16x32_bf16 v[50:53], v[36:39], v[28:31], 0
	v_fma_f32 v36, -v57, v63, v62
	ds_read_b128 v[66:69], v64 offset:8192
	ds_read_b128 v[70:73], v64 offset:10240
	v_div_fmas_f32 v36, v36, v59, v63
	s_waitcnt lgkmcnt(0)
	v_mfma_f32_16x16x32_bf16 v[74:77], v[32:35], v[28:31], 0
	v_lshl_add_u64 v[34:35], v[54:55], 1, v[60:61]
	ds_read_b128 v[60:63], v64 offset:12288
	ds_read_b128 v[78:81], v64 offset:14336
	ds_read_b128 v[82:85], v64 offset:32768
	ds_read_b128 v[86:89], v64 offset:34816
	ds_read_b128 v[90:93], v64 offset:36864
	ds_read_b128 v[94:97], v64 offset:38912
	ds_read_b128 v[98:101], v64 offset:40960
	ds_read_b128 v[102:105], v64 offset:43008
	ds_read_b128 v[106:109], v64 offset:45056
	ds_read_b128 v[110:113], v64 offset:47104
	s_mov_b64 s[0:1], 0x1000000
	v_mfma_f32_16x16x32_bf16 v[38:41], v[40:43], v[28:31], 0
	v_div_fixup_f32 v36, v36, v49, 1.0
	v_lshl_add_u64 v[32:33], v[34:35], 0, s[0:1]
	v_mfma_f32_16x16x32_bf16 v[66:69], v[66:69], v[28:31], 0
	v_mfma_f32_16x16x32_bf16 v[70:73], v[70:73], v[28:31], 0
	s_waitcnt lgkmcnt(0)
	v_mfma_f32_16x16x32_bf16 v[60:63], v[60:63], v[28:31], 0
	v_mfma_f32_16x16x32_bf16 v[78:81], v[78:81], v[28:31], 0
	s_add_u32 s100, s10, 0x11c00100
	s_addc_u32 s101, s11, 0
	s_mov_b32 m0, s19
	s_nop 0
	global_load_lds_dwordx4 v241, s[100:101]
	ds_read_b128 v[114:117], v64 offset:30720
	ds_read_b128 v[118:121], v64 offset:28672
	ds_read_b128 v[122:125], v64 offset:26624
	ds_read_b128 v[126:129], v64 offset:24576
	ds_read_b128 v[130:133], v64 offset:22528
	ds_read_b128 v[134:137], v64 offset:20480
	ds_read_b128 v[138:141], v64 offset:18432
	ds_read_b128 v[142:145], v64 offset:16384
	v_mfma_f32_16x16x32_bf16 v[82:85], v[82:85], v[28:31], 0
	v_mfma_f32_16x16x32_bf16 v[86:89], v[86:89], v[28:31], 0
	v_mfma_f32_16x16x32_bf16 v[90:93], v[90:93], v[28:31], 0
	v_mfma_f32_16x16x32_bf16 v[94:97], v[94:97], v[28:31], 0
	v_mfma_f32_16x16x32_bf16 v[98:101], v[98:101], v[28:31], 0
	v_mfma_f32_16x16x32_bf16 v[102:105], v[102:105], v[28:31], 0
	v_mfma_f32_16x16x32_bf16 v[106:109], v[106:109], v[28:31], 0
	v_mfma_f32_16x16x32_bf16 v[110:113], v[110:113], v[28:31], 0
	s_add_u32 s100, s10, 0x11c08100
	s_addc_u32 s101, s11, 0
	s_mov_b32 m0, s13
	s_nop 0
	global_load_lds_dwordx4 v241, s[100:101]
	s_waitcnt lgkmcnt(0)
	v_mfma_f32_16x16x32_bf16 v[42:45], v[142:145], v[24:27], v[44:47]
	v_mfma_f32_16x16x32_bf16 v[50:53], v[138:141], v[24:27], v[50:53]
	v_mfma_f32_16x16x32_bf16 v[38:41], v[134:137], v[24:27], v[38:41]
	v_mfma_f32_16x16x32_bf16 v[74:77], v[130:133], v[24:27], v[74:77]
	v_mfma_f32_16x16x32_bf16 v[66:69], v[126:129], v[24:27], v[66:69]
	v_mfma_f32_16x16x32_bf16 v[70:73], v[122:125], v[24:27], v[70:73]
	ds_read_b128 v[122:125], v64 offset:49152
	ds_read_b128 v[126:129], v64 offset:51200
	ds_read_b128 v[130:133], v64 offset:53248
	ds_read_b128 v[134:137], v64 offset:55296
	v_mfma_f32_16x16x32_bf16 v[60:63], v[118:121], v[24:27], v[60:63]
	ds_read_b128 v[118:121], v64 offset:57344
	ds_read_b128 v[138:141], v64 offset:59392
	ds_read_b128 v[142:145], v64 offset:61440
	ds_read_b128 v[146:149], v64 offset:63488
	v_mfma_f32_16x16x32_bf16 v[78:81], v[114:117], v[24:27], v[78:81]
	s_add_u32 s100, s10, 0x11c00180
	s_addc_u32 s101, s11, 0
	s_mov_b32 m0, s12
	s_nop 0
	global_load_lds_dwordx4 v241, s[100:101]
	s_waitcnt lgkmcnt(0)
	v_mfma_f32_16x16x32_bf16 v[82:85], v[122:125], v[24:27], v[82:85]
	v_mfma_f32_16x16x32_bf16 v[86:89], v[126:129], v[24:27], v[86:89]
	v_mfma_f32_16x16x32_bf16 v[90:93], v[130:133], v[24:27], v[90:93]
	v_mfma_f32_16x16x32_bf16 v[94:97], v[134:137], v[24:27], v[94:97]
	v_mfma_f32_16x16x32_bf16 v[98:101], v[118:121], v[24:27], v[98:101]
	ds_read_b128 v[114:117], v64 offset:15360
	ds_read_b128 v[118:121], v64 offset:13312
	ds_read_b128 v[122:125], v64 offset:11264
	ds_read_b128 v[126:129], v64 offset:9216
	v_mfma_f32_16x16x32_bf16 v[102:105], v[138:141], v[24:27], v[102:105]
	v_mfma_f32_16x16x32_bf16 v[106:109], v[142:145], v[24:27], v[106:109]
	ds_read_b128 v[130:133], v64 offset:7168
	ds_read_b128 v[134:137], v64 offset:5120
	ds_read_b128 v[138:141], v64 offset:3072
	ds_read_b128 v[142:145], v64 offset:1024
	v_mfma_f32_16x16x32_bf16 v[110:113], v[146:149], v[24:27], v[110:113]
	s_add_u32 s100, s10, 0x11c08180
	s_addc_u32 s101, s11, 0
	s_mov_b32 m0, s14
	s_nop 0
	global_load_lds_dwordx4 v241, s[100:101]
	s_waitcnt lgkmcnt(0)
	v_mfma_f32_16x16x32_bf16 v[42:45], v[142:145], v[20:23], v[42:45]
	v_mfma_f32_16x16x32_bf16 v[50:53], v[138:141], v[20:23], v[50:53]
	v_mfma_f32_16x16x32_bf16 v[38:41], v[134:137], v[20:23], v[38:41]
	v_mfma_f32_16x16x32_bf16 v[74:77], v[130:133], v[20:23], v[74:77]
	v_mfma_f32_16x16x32_bf16 v[66:69], v[126:129], v[20:23], v[66:69]
	v_mfma_f32_16x16x32_bf16 v[70:73], v[122:125], v[20:23], v[70:73]
	ds_read_b128 v[122:125], v64 offset:33792
	ds_read_b128 v[126:129], v64 offset:35840
	ds_read_b128 v[130:133], v64 offset:37888
	ds_read_b128 v[134:137], v64 offset:39936
	v_mfma_f32_16x16x32_bf16 v[60:63], v[118:121], v[20:23], v[60:63]
	ds_read_b128 v[118:121], v64 offset:41984
	ds_read_b128 v[138:141], v64 offset:44032
	ds_read_b128 v[142:145], v64 offset:46080
	ds_read_b128 v[146:149], v64 offset:48128
	v_mfma_f32_16x16x32_bf16 v[78:81], v[114:117], v[20:23], v[78:81]
	s_add_u32 s100, s10, 0x11c10100
	s_addc_u32 s101, s11, 0
	s_mov_b32 m0, s15
	s_nop 0
	global_load_lds_dwordx4 v241, s[100:101]
	s_waitcnt lgkmcnt(0)
	v_mfma_f32_16x16x32_bf16 v[82:85], v[122:125], v[20:23], v[82:85]
	v_mfma_f32_16x16x32_bf16 v[86:89], v[126:129], v[20:23], v[86:89]
	v_mfma_f32_16x16x32_bf16 v[90:93], v[130:133], v[20:23], v[90:93]
	v_mfma_f32_16x16x32_bf16 v[94:97], v[134:137], v[20:23], v[94:97]
	v_mfma_f32_16x16x32_bf16 v[98:101], v[118:121], v[20:23], v[98:101]
	ds_read_b128 v[114:117], v64 offset:31744
	ds_read_b128 v[118:121], v64 offset:29696
	ds_read_b128 v[122:125], v64 offset:27648
	ds_read_b128 v[126:129], v64 offset:25600
	v_mfma_f32_16x16x32_bf16 v[102:105], v[138:141], v[20:23], v[102:105]
	v_mfma_f32_16x16x32_bf16 v[106:109], v[142:145], v[20:23], v[106:109]
	ds_read_b128 v[130:133], v64 offset:23552
	ds_read_b128 v[134:137], v64 offset:21504
	ds_read_b128 v[138:141], v64 offset:19456
	ds_read_b128 v[142:145], v64 offset:17408
	v_mfma_f32_16x16x32_bf16 v[110:113], v[146:149], v[20:23], v[110:113]
	s_add_u32 s100, s10, 0x11c18100
	s_addc_u32 s101, s11, 0
	s_mov_b32 m0, s16
	s_nop 0
	global_load_lds_dwordx4 v241, s[100:101]
	s_waitcnt lgkmcnt(0)
	v_mfma_f32_16x16x32_bf16 v[42:45], v[142:145], v[16:19], v[42:45]
	v_mfma_f32_16x16x32_bf16 v[50:53], v[138:141], v[16:19], v[50:53]
	v_mfma_f32_16x16x32_bf16 v[38:41], v[134:137], v[16:19], v[38:41]
	v_mfma_f32_16x16x32_bf16 v[74:77], v[130:133], v[16:19], v[74:77]
	v_mfma_f32_16x16x32_bf16 v[66:69], v[126:129], v[16:19], v[66:69]
	v_mfma_f32_16x16x32_bf16 v[70:73], v[122:125], v[16:19], v[70:73]
	ds_read_b128 v[122:125], v64 offset:50176
	ds_read_b128 v[126:129], v64 offset:52224
	ds_read_b128 v[130:133], v64 offset:54272
	ds_read_b128 v[134:137], v64 offset:56320
	v_mfma_f32_16x16x32_bf16 v[60:63], v[118:121], v[16:19], v[60:63]
	ds_read_b128 v[118:121], v64 offset:58368
	ds_read_b128 v[138:141], v64 offset:60416
	ds_read_b128 v[142:145], v64 offset:62464
	ds_read_b128 v[146:149], v64 offset:64512
	v_mfma_f32_16x16x32_bf16 v[78:81], v[114:117], v[16:19], v[78:81]
	s_add_u32 s100, s10, 0x11c10180
	s_addc_u32 s101, s11, 0
	s_mov_b32 m0, s17
	s_nop 0
	global_load_lds_dwordx4 v241, s[100:101]
	s_waitcnt lgkmcnt(0)
	v_mfma_f32_16x16x32_bf16 v[82:85], v[122:125], v[16:19], v[82:85]
	v_mfma_f32_16x16x32_bf16 v[86:89], v[126:129], v[16:19], v[86:89]
	v_mfma_f32_16x16x32_bf16 v[90:93], v[130:133], v[16:19], v[90:93]
	v_mfma_f32_16x16x32_bf16 v[94:97], v[134:137], v[16:19], v[94:97]
	v_mfma_f32_16x16x32_bf16 v[98:101], v[118:121], v[16:19], v[98:101]
	v_mfma_f32_16x16x32_bf16 v[102:105], v[138:141], v[16:19], v[102:105]
	v_mfma_f32_16x16x32_bf16 v[106:109], v[142:145], v[16:19], v[106:109]
	v_mfma_f32_16x16x32_bf16 v[110:113], v[146:149], v[16:19], v[110:113]
	s_add_u32 s100, s10, 0x11c18180
	s_addc_u32 s101, s11, 0
	s_mov_b32 m0, s18
	s_nop 0
	global_load_lds_dwordx4 v241, s[100:101]
	s_waitcnt vmcnt(0)
	s_waitcnt vmcnt(0)
	s_barrier
	v_mov_b32_e32 v37, v48
	ds_read_b128 v[114:117], v37
	ds_read_b128 v[118:121], v37 offset:2048
	s_waitcnt lgkmcnt(0)
	v_mfma_f32_16x16x32_bf16 v[42:45], v[114:117], v[12:15], v[42:45]
	ds_read_b128 v[114:117], v37 offset:4096
	v_mfma_f32_16x16x32_bf16 v[50:53], v[118:121], v[12:15], v[50:53]
	ds_read_b128 v[118:121], v37 offset:6144
	s_waitcnt lgkmcnt(0)
	v_mfma_f32_16x16x32_bf16 v[38:41], v[114:117], v[12:15], v[38:41]
	ds_read_b128 v[114:117], v37 offset:8192
	v_mfma_f32_16x16x32_bf16 v[74:77], v[118:121], v[12:15], v[74:77]
	ds_read_b128 v[118:121], v37 offset:10240
	s_waitcnt lgkmcnt(0)
	v_mfma_f32_16x16x32_bf16 v[66:69], v[114:117], v[12:15], v[66:69]
	ds_read_b128 v[114:117], v37 offset:12288
	ds_read_b128 v[122:125], v37 offset:14336
	v_mfma_f32_16x16x32_bf16 v[70:73], v[118:121], v[12:15], v[70:73]
	ds_read_b128 v[118:121], v37 offset:32768
	ds_read_b128 v[126:129], v37 offset:34816
	ds_read_b128 v[130:133], v37 offset:36864
	ds_read_b128 v[134:137], v37 offset:38912
	s_waitcnt lgkmcnt(0)
	v_mfma_f32_16x16x32_bf16 v[60:63], v[114:117], v[12:15], v[60:63]
	ds_read_b128 v[114:117], v37 offset:40960
	ds_read_b128 v[138:141], v37 offset:43008
	ds_read_b128 v[142:145], v37 offset:45056
	ds_read_b128 v[146:149], v37 offset:47104
	v_mfma_f32_16x16x32_bf16 v[78:81], v[122:125], v[12:15], v[78:81]
	s_add_u32 s100, s10, 0x11c20000
	s_addc_u32 s101, s11, 0
	s_mov_b32 m0, s22
	s_nop 0
	global_load_lds_dwordx4 v241, s[100:101]
	v_mfma_f32_16x16x32_bf16 v[82:85], v[118:121], v[12:15], v[82:85]
	v_mfma_f32_16x16x32_bf16 v[86:89], v[126:129], v[12:15], v[86:89]
	v_mfma_f32_16x16x32_bf16 v[90:93], v[130:133], v[12:15], v[90:93]
	v_mfma_f32_16x16x32_bf16 v[94:97], v[134:137], v[12:15], v[94:97]
	s_waitcnt lgkmcnt(0)
	v_mfma_f32_16x16x32_bf16 v[98:101], v[114:117], v[12:15], v[98:101]
	ds_read_b128 v[114:117], v37 offset:30720
	ds_read_b128 v[118:121], v37 offset:28672
	ds_read_b128 v[122:125], v37 offset:26624
	ds_read_b128 v[126:129], v37 offset:24576
	v_mfma_f32_16x16x32_bf16 v[102:105], v[138:141], v[12:15], v[102:105]
	v_mfma_f32_16x16x32_bf16 v[106:109], v[142:145], v[12:15], v[106:109]
	ds_read_b128 v[130:133], v37 offset:22528
	ds_read_b128 v[134:137], v37 offset:20480
	ds_read_b128 v[138:141], v37 offset:18432
	ds_read_b128 v[142:145], v37 offset:16384
	v_mfma_f32_16x16x32_bf16 v[110:113], v[146:149], v[12:15], v[110:113]
	s_add_u32 s100, s10, 0x11c28000
	s_addc_u32 s101, s11, 0
	s_mov_b32 m0, s21
	s_nop 0
	global_load_lds_dwordx4 v241, s[100:101]
	s_waitcnt lgkmcnt(0)
	v_mfma_f32_16x16x32_bf16 v[42:45], v[142:145], v[8:11], v[42:45]
	v_mfma_f32_16x16x32_bf16 v[50:53], v[138:141], v[8:11], v[50:53]
	v_mfma_f32_16x16x32_bf16 v[38:41], v[134:137], v[8:11], v[38:41]
	v_mfma_f32_16x16x32_bf16 v[74:77], v[130:133], v[8:11], v[74:77]
	v_mfma_f32_16x16x32_bf16 v[66:69], v[126:129], v[8:11], v[66:69]
	v_mfma_f32_16x16x32_bf16 v[70:73], v[122:125], v[8:11], v[70:73]
	ds_read_b128 v[122:125], v37 offset:49152
	ds_read_b128 v[126:129], v37 offset:51200
	ds_read_b128 v[130:133], v37 offset:53248
	ds_read_b128 v[134:137], v37 offset:55296
	v_mfma_f32_16x16x32_bf16 v[60:63], v[118:121], v[8:11], v[60:63]
	ds_read_b128 v[118:121], v37 offset:57344
	ds_read_b128 v[138:141], v37 offset:59392
	ds_read_b128 v[142:145], v37 offset:61440
	ds_read_b128 v[146:149], v37 offset:63488
	v_mfma_f32_16x16x32_bf16 v[78:81], v[114:117], v[8:11], v[78:81]
	s_add_u32 s100, s10, 0x11c20080
	s_addc_u32 s101, s11, 0
	s_mov_b32 m0, s20
	s_nop 0
	global_load_lds_dwordx4 v241, s[100:101]
	s_waitcnt lgkmcnt(0)
	v_mfma_f32_16x16x32_bf16 v[82:85], v[122:125], v[8:11], v[82:85]
	v_mfma_f32_16x16x32_bf16 v[86:89], v[126:129], v[8:11], v[86:89]
	v_mfma_f32_16x16x32_bf16 v[90:93], v[130:133], v[8:11], v[90:93]
	v_mfma_f32_16x16x32_bf16 v[94:97], v[134:137], v[8:11], v[94:97]
	v_mfma_f32_16x16x32_bf16 v[98:101], v[118:121], v[8:11], v[98:101]
	ds_read_b128 v[114:117], v37 offset:15360
	ds_read_b128 v[118:121], v37 offset:13312
	ds_read_b128 v[122:125], v37 offset:11264
	ds_read_b128 v[126:129], v37 offset:9216
	v_mfma_f32_16x16x32_bf16 v[102:105], v[138:141], v[8:11], v[102:105]
	v_mfma_f32_16x16x32_bf16 v[106:109], v[142:145], v[8:11], v[106:109]
	ds_read_b128 v[130:133], v37 offset:7168
	ds_read_b128 v[134:137], v37 offset:5120
	ds_read_b128 v[138:141], v37 offset:3072
	ds_read_b128 v[142:145], v37 offset:1024
	v_mfma_f32_16x16x32_bf16 v[110:113], v[146:149], v[8:11], v[110:113]
	s_add_u32 s100, s10, 0x11c28080
	s_addc_u32 s101, s11, 0
	s_mov_b32 m0, s23
	s_nop 0
	global_load_lds_dwordx4 v241, s[100:101]
	s_waitcnt lgkmcnt(0)
	v_mfma_f32_16x16x32_bf16 v[42:45], v[142:145], v[4:7], v[42:45]
	v_mfma_f32_16x16x32_bf16 v[50:53], v[138:141], v[4:7], v[50:53]
	v_mfma_f32_16x16x32_bf16 v[38:41], v[134:137], v[4:7], v[38:41]
	v_mfma_f32_16x16x32_bf16 v[74:77], v[130:133], v[4:7], v[74:77]
	v_mfma_f32_16x16x32_bf16 v[66:69], v[126:129], v[4:7], v[66:69]
	v_mfma_f32_16x16x32_bf16 v[70:73], v[122:125], v[4:7], v[70:73]
	ds_read_b128 v[122:125], v37 offset:33792
	ds_read_b128 v[126:129], v37 offset:35840
	ds_read_b128 v[130:133], v37 offset:37888
	ds_read_b128 v[134:137], v37 offset:39936
	v_mfma_f32_16x16x32_bf16 v[60:63], v[118:121], v[4:7], v[60:63]
	ds_read_b128 v[118:121], v37 offset:41984
	ds_read_b128 v[138:141], v37 offset:44032
	ds_read_b128 v[142:145], v37 offset:46080
	ds_read_b128 v[146:149], v37 offset:48128
	v_mfma_f32_16x16x32_bf16 v[78:81], v[114:117], v[4:7], v[78:81]
	s_add_u32 s100, s10, 0x11c30000
	s_addc_u32 s101, s11, 0
	s_mov_b32 m0, s24
	s_nop 0
	global_load_lds_dwordx4 v241, s[100:101]
	s_waitcnt lgkmcnt(0)
	v_mfma_f32_16x16x32_bf16 v[82:85], v[122:125], v[4:7], v[82:85]
	v_mfma_f32_16x16x32_bf16 v[86:89], v[126:129], v[4:7], v[86:89]
	v_mfma_f32_16x16x32_bf16 v[90:93], v[130:133], v[4:7], v[90:93]
	v_mfma_f32_16x16x32_bf16 v[94:97], v[134:137], v[4:7], v[94:97]
	v_mfma_f32_16x16x32_bf16 v[98:101], v[118:121], v[4:7], v[98:101]
	ds_read_b128 v[114:117], v37 offset:31744
	ds_read_b128 v[118:121], v37 offset:29696
	ds_read_b128 v[122:125], v37 offset:27648
	ds_read_b128 v[126:129], v37 offset:25600
	v_mfma_f32_16x16x32_bf16 v[102:105], v[138:141], v[4:7], v[102:105]
	v_mfma_f32_16x16x32_bf16 v[106:109], v[142:145], v[4:7], v[106:109]
	ds_read_b128 v[130:133], v37 offset:23552
	ds_read_b128 v[134:137], v37 offset:21504
	ds_read_b128 v[138:141], v37 offset:19456
	ds_read_b128 v[142:145], v37 offset:17408
	v_mfma_f32_16x16x32_bf16 v[110:113], v[146:149], v[4:7], v[110:113]
	s_add_u32 s100, s10, 0x11c38000
	s_addc_u32 s101, s11, 0
	s_mov_b32 m0, s25
	s_nop 0
	global_load_lds_dwordx4 v241, s[100:101]
	s_waitcnt lgkmcnt(0)
	v_mfma_f32_16x16x32_bf16 v[42:45], v[142:145], v[0:3], v[42:45]
	v_mfma_f32_16x16x32_bf16 v[50:53], v[138:141], v[0:3], v[50:53]
	v_mfma_f32_16x16x32_bf16 v[38:41], v[134:137], v[0:3], v[38:41]
	v_mfma_f32_16x16x32_bf16 v[74:77], v[130:133], v[0:3], v[74:77]
	v_mfma_f32_16x16x32_bf16 v[66:69], v[126:129], v[0:3], v[66:69]
	v_mfma_f32_16x16x32_bf16 v[70:73], v[122:125], v[0:3], v[70:73]
	ds_read_b128 v[122:125], v37 offset:50176
	ds_read_b128 v[126:129], v37 offset:52224
	ds_read_b128 v[130:133], v37 offset:54272
	ds_read_b128 v[134:137], v37 offset:56320
	v_mfma_f32_16x16x32_bf16 v[60:63], v[118:121], v[0:3], v[60:63]
	ds_read_b128 v[118:121], v37 offset:58368
	ds_read_b128 v[138:141], v37 offset:60416
	ds_read_b128 v[142:145], v37 offset:62464
	ds_read_b128 v[146:149], v37 offset:64512
	v_mfma_f32_16x16x32_bf16 v[78:81], v[114:117], v[0:3], v[78:81]
	s_add_u32 s100, s10, 0x11c30080
	s_addc_u32 s101, s11, 0
	s_mov_b32 m0, s26
	s_nop 0
	global_load_lds_dwordx4 v241, s[100:101]
	s_waitcnt lgkmcnt(0)
	v_mfma_f32_16x16x32_bf16 v[82:85], v[122:125], v[0:3], v[82:85]
	v_mfma_f32_16x16x32_bf16 v[86:89], v[126:129], v[0:3], v[86:89]
	v_mfma_f32_16x16x32_bf16 v[90:93], v[130:133], v[0:3], v[90:93]
	v_mfma_f32_16x16x32_bf16 v[94:97], v[134:137], v[0:3], v[94:97]
	v_mfma_f32_16x16x32_bf16 v[98:101], v[118:121], v[0:3], v[98:101]
	v_mfma_f32_16x16x32_bf16 v[102:105], v[138:141], v[0:3], v[102:105]
	v_mfma_f32_16x16x32_bf16 v[106:109], v[142:145], v[0:3], v[106:109]
	v_mfma_f32_16x16x32_bf16 v[110:113], v[146:149], v[0:3], v[110:113]
	s_add_u32 s100, s10, 0x11c38080
	s_addc_u32 s101, s11, 0
	s_mov_b32 m0, s27
	s_nop 0
	global_load_lds_dwordx4 v241, s[100:101]
	s_mov_b32 s0, 0x1000000
	v_add_co_u32_e32 v34, vcc, s0, v34
	v_addc_co_u32_e32 v35, vcc, 0, v35, vcc
	v_mbcnt_lo_u32_b32 v212, -1, 0
	v_mbcnt_hi_u32_b32 v212, -1, v212
	v_lshrrev_b32_e32 v212, 4, v212
	v_and_b32_e32 v212, 1, v212
	v_mul_u32_u24_e32 v212, 24, v212
	v_mov_b32_e32 v213, 0
	v_lshl_add_u64 v[214:215], v[32:33], 0, v[212:213]
	v_mul_f32_e32 v200, v36, v42
	v_mul_f32_e32 v204, v36, v43
	v_cvt_pk_bf16_f32 v200, v200, v204
	v_mul_f32_e32 v201, v36, v44
	v_mul_f32_e32 v204, v36, v45
	v_cvt_pk_bf16_f32 v201, v201, v204
	v_mul_f32_e32 v202, v36, v50
	v_mul_f32_e32 v204, v36, v51
	v_cvt_pk_bf16_f32 v202, v202, v204
	v_mul_f32_e32 v203, v36, v52
	v_mul_f32_e32 v204, v36, v53
	v_cvt_pk_bf16_f32 v203, v203, v204
	s_nop 1
	v_permlane16_swap_b32_e32 v200, v202
	v_permlane16_swap_b32_e32 v201, v203
	global_store_dwordx4 v[214:215], v[200:203], off offset:0
	v_mul_f32_e32 v206, v36, v38
	v_mul_f32_e32 v210, v36, v39
	v_cvt_pk_bf16_f32 v206, v206, v210
	v_mul_f32_e32 v207, v36, v40
	v_mul_f32_e32 v210, v36, v41
	v_cvt_pk_bf16_f32 v207, v207, v210
	v_mul_f32_e32 v208, v36, v74
	v_mul_f32_e32 v210, v36, v75
	v_cvt_pk_bf16_f32 v208, v208, v210
	v_mul_f32_e32 v209, v36, v76
	v_mul_f32_e32 v210, v36, v77
	v_cvt_pk_bf16_f32 v209, v209, v210
	s_nop 1
	v_permlane16_swap_b32_e32 v206, v208
	v_permlane16_swap_b32_e32 v207, v209
	global_store_dwordx4 v[214:215], v[206:209], off offset:64
	v_mul_f32_e32 v200, v36, v66
	v_mul_f32_e32 v204, v36, v67
	v_cvt_pk_bf16_f32 v200, v200, v204
	v_mul_f32_e32 v201, v36, v68
	v_mul_f32_e32 v204, v36, v69
	v_cvt_pk_bf16_f32 v201, v201, v204
	v_mul_f32_e32 v202, v36, v70
	v_mul_f32_e32 v204, v36, v71
	v_cvt_pk_bf16_f32 v202, v202, v204
	v_mul_f32_e32 v203, v36, v72
	v_mul_f32_e32 v204, v36, v73
	v_cvt_pk_bf16_f32 v203, v203, v204
	s_nop 1
	v_permlane16_swap_b32_e32 v200, v202
	v_permlane16_swap_b32_e32 v201, v203
	global_store_dwordx4 v[214:215], v[200:203], off offset:128
	v_mul_f32_e32 v206, v36, v60
	v_mul_f32_e32 v210, v36, v61
	v_cvt_pk_bf16_f32 v206, v206, v210
	v_mul_f32_e32 v207, v36, v62
	v_mul_f32_e32 v210, v36, v63
	v_cvt_pk_bf16_f32 v207, v207, v210
	v_mul_f32_e32 v208, v36, v78
	v_mul_f32_e32 v210, v36, v79
	v_cvt_pk_bf16_f32 v208, v208, v210
	v_mul_f32_e32 v209, v36, v80
	v_mul_f32_e32 v210, v36, v81
	v_cvt_pk_bf16_f32 v209, v209, v210
	s_nop 1
	v_permlane16_swap_b32_e32 v206, v208
	v_permlane16_swap_b32_e32 v207, v209
	global_store_dwordx4 v[214:215], v[206:209], off offset:192
	v_mul_f32_e32 v200, v36, v82
	v_mul_f32_e32 v204, v36, v83
	v_cvt_pk_bf16_f32 v200, v200, v204
	v_mul_f32_e32 v201, v36, v84
	v_mul_f32_e32 v204, v36, v85
	v_cvt_pk_bf16_f32 v201, v201, v204
	v_mul_f32_e32 v202, v36, v86
	v_mul_f32_e32 v204, v36, v87
	v_cvt_pk_bf16_f32 v202, v202, v204
	v_mul_f32_e32 v203, v36, v88
	v_mul_f32_e32 v204, v36, v89
	v_cvt_pk_bf16_f32 v203, v203, v204
	s_nop 1
	v_permlane16_swap_b32_e32 v200, v202
	v_permlane16_swap_b32_e32 v201, v203
	global_store_dwordx4 v[214:215], v[200:203], off offset:256
	v_mul_f32_e32 v206, v36, v90
	v_mul_f32_e32 v210, v36, v91
	v_cvt_pk_bf16_f32 v206, v206, v210
	v_mul_f32_e32 v207, v36, v92
	v_mul_f32_e32 v210, v36, v93
	v_cvt_pk_bf16_f32 v207, v207, v210
	v_mul_f32_e32 v208, v36, v94
	v_mul_f32_e32 v210, v36, v95
	v_cvt_pk_bf16_f32 v208, v208, v210
	v_mul_f32_e32 v209, v36, v96
	v_mul_f32_e32 v210, v36, v97
	v_cvt_pk_bf16_f32 v209, v209, v210
	s_nop 1
	v_permlane16_swap_b32_e32 v206, v208
	v_permlane16_swap_b32_e32 v207, v209
	global_store_dwordx4 v[214:215], v[206:209], off offset:320
	v_mul_f32_e32 v200, v36, v98
	v_mul_f32_e32 v204, v36, v99
	v_cvt_pk_bf16_f32 v200, v200, v204
	v_mul_f32_e32 v201, v36, v100
	v_mul_f32_e32 v204, v36, v101
	v_cvt_pk_bf16_f32 v201, v201, v204
	v_mul_f32_e32 v202, v36, v102
	v_mul_f32_e32 v204, v36, v103
	v_cvt_pk_bf16_f32 v202, v202, v204
	v_mul_f32_e32 v203, v36, v104
	v_mul_f32_e32 v204, v36, v105
	v_cvt_pk_bf16_f32 v203, v203, v204
	s_nop 1
	v_permlane16_swap_b32_e32 v200, v202
	v_permlane16_swap_b32_e32 v201, v203
	global_store_dwordx4 v[214:215], v[200:203], off offset:384
	v_mul_f32_e32 v206, v36, v106
	v_mul_f32_e32 v210, v36, v107
	v_cvt_pk_bf16_f32 v206, v206, v210
	v_mul_f32_e32 v207, v36, v108
	v_mul_f32_e32 v210, v36, v109
	v_cvt_pk_bf16_f32 v207, v207, v210
	v_mul_f32_e32 v208, v36, v110
	v_mul_f32_e32 v210, v36, v111
	v_cvt_pk_bf16_f32 v208, v208, v210
	v_mul_f32_e32 v209, v36, v112
	v_mul_f32_e32 v210, v36, v113
	v_cvt_pk_bf16_f32 v209, v209, v210
	s_nop 1
	v_permlane16_swap_b32_e32 v206, v208
	v_permlane16_swap_b32_e32 v207, v209
	global_store_dwordx4 v[214:215], v[206:209], off offset:448
	s_waitcnt vmcnt(0)
	s_waitcnt vmcnt(0)
	s_barrier
	ds_read_b128 v[38:41], v65
	ds_read_b128 v[42:45], v65 offset:2048
	ds_read_b128 v[50:53], v65 offset:4096
	ds_read_b128 v[54:57], v65 offset:6144
	ds_read_b128 v[58:61], v65 offset:8192
	ds_read_b128 v[66:69], v65 offset:10240
	ds_read_b128 v[70:73], v65 offset:12288
	ds_read_b128 v[74:77], v65 offset:14336
	ds_read_b128 v[78:81], v65 offset:32768
	ds_read_b128 v[82:85], v65 offset:34816
	ds_read_b128 v[86:89], v65 offset:36864
	ds_read_b128 v[90:93], v65 offset:38912
	ds_read_b128 v[94:97], v65 offset:40960
	ds_read_b128 v[98:101], v65 offset:43008
	ds_read_b128 v[102:105], v65 offset:45056
	ds_read_b128 v[106:109], v65 offset:47104
	s_waitcnt lgkmcnt(0)
	v_mfma_f32_16x16x32_bf16 v[38:41], v[38:41], v[28:31], 0
	v_mfma_f32_16x16x32_bf16 v[42:45], v[42:45], v[28:31], 0
	v_mfma_f32_16x16x32_bf16 v[50:53], v[50:53], v[28:31], 0
	v_mfma_f32_16x16x32_bf16 v[54:57], v[54:57], v[28:31], 0
	v_mfma_f32_16x16x32_bf16 v[58:61], v[58:61], v[28:31], 0
	v_mfma_f32_16x16x32_bf16 v[66:69], v[66:69], v[28:31], 0
	v_mfma_f32_16x16x32_bf16 v[70:73], v[70:73], v[28:31], 0
	v_mfma_f32_16x16x32_bf16 v[74:77], v[74:77], v[28:31], 0
	s_add_u32 s100, s10, 0x11c20100
	s_addc_u32 s101, s11, 0
	s_mov_b32 m0, s19
	s_nop 0
	global_load_lds_dwordx4 v241, s[100:101]
	ds_read_b128 v[110:113], v65 offset:30720
	ds_read_b128 v[114:117], v65 offset:28672
	ds_read_b128 v[118:121], v65 offset:26624
	ds_read_b128 v[122:125], v65 offset:24576
	ds_read_b128 v[126:129], v65 offset:22528
	ds_read_b128 v[130:133], v65 offset:20480
	ds_read_b128 v[134:137], v65 offset:18432
	ds_read_b128 v[138:141], v65 offset:16384
	v_mfma_f32_16x16x32_bf16 v[78:81], v[78:81], v[28:31], 0
	v_mfma_f32_16x16x32_bf16 v[82:85], v[82:85], v[28:31], 0
	v_mfma_f32_16x16x32_bf16 v[86:89], v[86:89], v[28:31], 0
	v_mfma_f32_16x16x32_bf16 v[90:93], v[90:93], v[28:31], 0
	v_mfma_f32_16x16x32_bf16 v[94:97], v[94:97], v[28:31], 0
	v_mfma_f32_16x16x32_bf16 v[98:101], v[98:101], v[28:31], 0
	v_mfma_f32_16x16x32_bf16 v[102:105], v[102:105], v[28:31], 0
	v_mfma_f32_16x16x32_bf16 v[28:31], v[106:109], v[28:31], 0
	s_add_u32 s100, s10, 0x11c28100
	s_addc_u32 s101, s11, 0
	s_mov_b32 m0, s13
	s_nop 0
	global_load_lds_dwordx4 v241, s[100:101]
	s_waitcnt lgkmcnt(0)
	v_mfma_f32_16x16x32_bf16 v[38:41], v[138:141], v[24:27], v[38:41]
	v_mfma_f32_16x16x32_bf16 v[42:45], v[134:137], v[24:27], v[42:45]
	v_mfma_f32_16x16x32_bf16 v[50:53], v[130:133], v[24:27], v[50:53]
	v_mfma_f32_16x16x32_bf16 v[54:57], v[126:129], v[24:27], v[54:57]
	v_mfma_f32_16x16x32_bf16 v[58:61], v[122:125], v[24:27], v[58:61]
	v_mfma_f32_16x16x32_bf16 v[66:69], v[118:121], v[24:27], v[66:69]
	ds_read_b128 v[106:109], v65 offset:49152
	ds_read_b128 v[118:121], v65 offset:51200
	ds_read_b128 v[122:125], v65 offset:53248
	ds_read_b128 v[126:129], v65 offset:55296
	v_mfma_f32_16x16x32_bf16 v[70:73], v[114:117], v[24:27], v[70:73]
	ds_read_b128 v[114:117], v65 offset:57344
	ds_read_b128 v[130:133], v65 offset:59392
	ds_read_b128 v[134:137], v65 offset:61440
	ds_read_b128 v[138:141], v65 offset:63488
	v_mfma_f32_16x16x32_bf16 v[74:77], v[110:113], v[24:27], v[74:77]
	s_add_u32 s100, s10, 0x11c20180
	s_addc_u32 s101, s11, 0
	s_mov_b32 m0, s12
	s_nop 0
	global_load_lds_dwordx4 v241, s[100:101]
	s_waitcnt lgkmcnt(0)
	v_mfma_f32_16x16x32_bf16 v[78:81], v[106:109], v[24:27], v[78:81]
	v_mfma_f32_16x16x32_bf16 v[82:85], v[118:121], v[24:27], v[82:85]
	v_mfma_f32_16x16x32_bf16 v[86:89], v[122:125], v[24:27], v[86:89]
	v_mfma_f32_16x16x32_bf16 v[90:93], v[126:129], v[24:27], v[90:93]
	v_mfma_f32_16x16x32_bf16 v[94:97], v[114:117], v[24:27], v[94:97]
	ds_read_b128 v[106:109], v65 offset:15360
	ds_read_b128 v[110:113], v65 offset:13312
	ds_read_b128 v[114:117], v65 offset:11264
	ds_read_b128 v[118:121], v65 offset:9216
	v_mfma_f32_16x16x32_bf16 v[98:101], v[130:133], v[24:27], v[98:101]
	v_mfma_f32_16x16x32_bf16 v[102:105], v[134:137], v[24:27], v[102:105]
	ds_read_b128 v[122:125], v65 offset:7168
	ds_read_b128 v[126:129], v65 offset:5120
	ds_read_b128 v[130:133], v65 offset:3072
	ds_read_b128 v[134:137], v65 offset:1024
	v_mfma_f32_16x16x32_bf16 v[24:27], v[138:141], v[24:27], v[28:31]
	s_add_u32 s100, s10, 0x11c28180
	s_addc_u32 s101, s11, 0
	s_mov_b32 m0, s14
	s_nop 0
	global_load_lds_dwordx4 v241, s[100:101]
	s_waitcnt lgkmcnt(0)
	v_mfma_f32_16x16x32_bf16 v[28:31], v[134:137], v[20:23], v[38:41]
	v_mfma_f32_16x16x32_bf16 v[38:41], v[130:133], v[20:23], v[42:45]
	v_mfma_f32_16x16x32_bf16 v[42:45], v[126:129], v[20:23], v[50:53]
	v_mfma_f32_16x16x32_bf16 v[50:53], v[122:125], v[20:23], v[54:57]
	v_mfma_f32_16x16x32_bf16 v[54:57], v[118:121], v[20:23], v[58:61]
	v_mfma_f32_16x16x32_bf16 v[58:61], v[114:117], v[20:23], v[66:69]
	s_nop 2
	ds_read_b128 v[66:69], v65 offset:33792
	ds_read_b128 v[114:117], v65 offset:35840
	ds_read_b128 v[118:121], v65 offset:37888
	ds_read_b128 v[122:125], v65 offset:39936
	v_mfma_f32_16x16x32_bf16 v[70:73], v[110:113], v[20:23], v[70:73]
	ds_read_b128 v[110:113], v65 offset:41984
	ds_read_b128 v[126:129], v65 offset:44032
	ds_read_b128 v[130:133], v65 offset:46080
	ds_read_b128 v[134:137], v65 offset:48128
	v_mfma_f32_16x16x32_bf16 v[74:77], v[106:109], v[20:23], v[74:77]
	s_add_u32 s100, s10, 0x11c30100
	s_addc_u32 s101, s11, 0
	s_mov_b32 m0, s15
	s_nop 0
	global_load_lds_dwordx4 v241, s[100:101]
	s_waitcnt lgkmcnt(0)
	v_mfma_f32_16x16x32_bf16 v[66:69], v[66:69], v[20:23], v[78:81]
	v_mfma_f32_16x16x32_bf16 v[78:81], v[114:117], v[20:23], v[82:85]
	v_mfma_f32_16x16x32_bf16 v[82:85], v[118:121], v[20:23], v[86:89]
	v_mfma_f32_16x16x32_bf16 v[86:89], v[122:125], v[20:23], v[90:93]
	v_mfma_f32_16x16x32_bf16 v[90:93], v[110:113], v[20:23], v[94:97]
	v_mfma_f32_16x16x32_bf16 v[94:97], v[126:129], v[20:23], v[98:101]
	s_nop 2
	ds_read_b128 v[98:101], v65 offset:31744
	ds_read_b128 v[106:109], v65 offset:29696
	ds_read_b128 v[110:113], v65 offset:27648
	ds_read_b128 v[114:117], v65 offset:25600
	v_mfma_f32_16x16x32_bf16 v[102:105], v[130:133], v[20:23], v[102:105]
	ds_read_b128 v[118:121], v65 offset:23552
	ds_read_b128 v[122:125], v65 offset:21504
	ds_read_b128 v[126:129], v65 offset:19456
	ds_read_b128 v[130:133], v65 offset:17408
	v_mfma_f32_16x16x32_bf16 v[20:23], v[134:137], v[20:23], v[24:27]
	s_add_u32 s100, s10, 0x11c38100
	s_addc_u32 s101, s11, 0
	s_mov_b32 m0, s16
	s_nop 0
	global_load_lds_dwordx4 v241, s[100:101]
	s_waitcnt lgkmcnt(0)
	v_mfma_f32_16x16x32_bf16 v[24:27], v[130:133], v[16:19], v[28:31]
	v_mfma_f32_16x16x32_bf16 v[28:31], v[126:129], v[16:19], v[38:41]
	v_mfma_f32_16x16x32_bf16 v[38:41], v[122:125], v[16:19], v[42:45]
	v_mfma_f32_16x16x32_bf16 v[42:45], v[118:121], v[16:19], v[50:53]
	v_mfma_f32_16x16x32_bf16 v[50:53], v[114:117], v[16:19], v[54:57]
	v_mfma_f32_16x16x32_bf16 v[54:57], v[110:113], v[16:19], v[58:61]
	s_nop 2
	ds_read_b128 v[58:61], v65 offset:50176
	ds_read_b128 v[110:113], v65 offset:52224
	ds_read_b128 v[114:117], v65 offset:54272
	ds_read_b128 v[118:121], v65 offset:56320
	v_mfma_f32_16x16x32_bf16 v[70:73], v[106:109], v[16:19], v[70:73]
	ds_read_b128 v[106:109], v65 offset:58368
	ds_read_b128 v[122:125], v65 offset:60416
	ds_read_b128 v[126:129], v65 offset:62464
	ds_read_b128 v[62:65], v65 offset:64512
	v_mfma_f32_16x16x32_bf16 v[74:77], v[98:101], v[16:19], v[74:77]
	s_add_u32 s100, s10, 0x11c30180
	s_addc_u32 s101, s11, 0
	s_mov_b32 m0, s17
	s_nop 0
	global_load_lds_dwordx4 v241, s[100:101]
	s_waitcnt lgkmcnt(0)
	v_mfma_f32_16x16x32_bf16 v[58:61], v[58:61], v[16:19], v[66:69]
	v_mfma_f32_16x16x32_bf16 v[66:69], v[110:113], v[16:19], v[78:81]
	v_mfma_f32_16x16x32_bf16 v[78:81], v[114:117], v[16:19], v[82:85]
	v_mfma_f32_16x16x32_bf16 v[82:85], v[118:121], v[16:19], v[86:89]
	v_mfma_f32_16x16x32_bf16 v[86:89], v[106:109], v[16:19], v[90:93]
	v_mfma_f32_16x16x32_bf16 v[90:93], v[122:125], v[16:19], v[94:97]
	v_mfma_f32_16x16x32_bf16 v[94:97], v[126:129], v[16:19], v[102:105]
	v_mfma_f32_16x16x32_bf16 v[16:19], v[62:65], v[16:19], v[20:23]
	s_add_u32 s100, s10, 0x11c38180
	s_addc_u32 s101, s11, 0
	s_mov_b32 m0, s18
	s_nop 0
	global_load_lds_dwordx4 v241, s[100:101]
	s_waitcnt vmcnt(0)
	s_waitcnt vmcnt(0)
	s_barrier
	s_nop 0
	ds_read_b128 v[20:23], v48
	ds_read_b128 v[62:65], v48 offset:2048
	s_waitcnt lgkmcnt(1)
	v_mfma_f32_16x16x32_bf16 v[20:23], v[20:23], v[12:15], v[24:27]
	s_nop 2
	ds_read_b128 v[24:27], v48 offset:4096
	s_waitcnt lgkmcnt(1)
	v_mfma_f32_16x16x32_bf16 v[28:31], v[62:65], v[12:15], v[28:31]
	ds_read_b128 v[62:65], v48 offset:6144
	s_waitcnt lgkmcnt(1)
	v_mfma_f32_16x16x32_bf16 v[24:27], v[24:27], v[12:15], v[38:41]
	s_nop 2
	ds_read_b128 v[38:41], v48 offset:8192
	s_waitcnt lgkmcnt(1)
	v_mfma_f32_16x16x32_bf16 v[42:45], v[62:65], v[12:15], v[42:45]
	ds_read_b128 v[62:65], v48 offset:10240
	s_waitcnt lgkmcnt(1)
	v_mfma_f32_16x16x32_bf16 v[38:41], v[38:41], v[12:15], v[50:53]
	s_nop 2
	ds_read_b128 v[50:53], v48 offset:12288
	ds_read_b128 v[98:101], v48 offset:14336
	s_waitcnt lgkmcnt(2)
	v_mfma_f32_16x16x32_bf16 v[54:57], v[62:65], v[12:15], v[54:57]
	ds_read_b128 v[62:65], v48 offset:32768
	ds_read_b128 v[102:105], v48 offset:34816
	ds_read_b128 v[106:109], v48 offset:36864
	ds_read_b128 v[110:113], v48 offset:38912
	s_waitcnt lgkmcnt(5)
	v_mfma_f32_16x16x32_bf16 v[50:53], v[50:53], v[12:15], v[70:73]
	s_nop 2
	ds_read_b128 v[70:73], v48 offset:40960
	ds_read_b128 v[114:117], v48 offset:43008
	ds_read_b128 v[118:121], v48 offset:45056
	ds_read_b128 v[122:125], v48 offset:47104
	s_waitcnt lgkmcnt(8)
	v_mfma_f32_16x16x32_bf16 v[74:77], v[98:101], v[12:15], v[74:77]
	s_waitcnt lgkmcnt(7)
	v_mfma_f32_16x16x32_bf16 v[58:61], v[62:65], v[12:15], v[58:61]
	s_waitcnt lgkmcnt(6)
	v_mfma_f32_16x16x32_bf16 v[62:65], v[102:105], v[12:15], v[66:69]
	s_waitcnt lgkmcnt(5)
	v_mfma_f32_16x16x32_bf16 v[66:69], v[106:109], v[12:15], v[78:81]
	s_waitcnt lgkmcnt(4)
	v_mfma_f32_16x16x32_bf16 v[78:81], v[110:113], v[12:15], v[82:85]
	s_waitcnt lgkmcnt(3)
	v_mfma_f32_16x16x32_bf16 v[70:73], v[70:73], v[12:15], v[86:89]
	s_waitcnt lgkmcnt(2)
	v_mfma_f32_16x16x32_bf16 v[82:85], v[114:117], v[12:15], v[90:93]
	s_nop 0
	ds_read_b128 v[86:89], v48 offset:30720
	s_nop 0
	ds_read_b128 v[90:93], v48 offset:28672
	ds_read_b128 v[98:101], v48 offset:26624
	ds_read_b128 v[102:105], v48 offset:24576
	s_waitcnt lgkmcnt(5)
	v_mfma_f32_16x16x32_bf16 v[94:97], v[118:121], v[12:15], v[94:97]
	ds_read_b128 v[106:109], v48 offset:22528
	ds_read_b128 v[110:113], v48 offset:20480
	ds_read_b128 v[114:117], v48 offset:18432
	ds_read_b128 v[118:121], v48 offset:16384
	s_waitcnt lgkmcnt(8)
	v_mfma_f32_16x16x32_bf16 v[12:15], v[122:125], v[12:15], v[16:19]
	s_waitcnt lgkmcnt(0)
	v_mfma_f32_16x16x32_bf16 v[16:19], v[118:121], v[8:11], v[20:23]
	v_mfma_f32_16x16x32_bf16 v[20:23], v[114:117], v[8:11], v[28:31]
	v_mfma_f32_16x16x32_bf16 v[24:27], v[110:113], v[8:11], v[24:27]
	v_mfma_f32_16x16x32_bf16 v[28:31], v[106:109], v[8:11], v[42:45]
	v_mfma_f32_16x16x32_bf16 v[38:41], v[102:105], v[8:11], v[38:41]
	v_mfma_f32_16x16x32_bf16 v[42:45], v[98:101], v[8:11], v[54:57]
	s_nop 2
	ds_read_b128 v[54:57], v48 offset:49152
	ds_read_b128 v[98:101], v48 offset:51200
	ds_read_b128 v[102:105], v48 offset:53248
	ds_read_b128 v[106:109], v48 offset:55296
	v_mfma_f32_16x16x32_bf16 v[50:53], v[90:93], v[8:11], v[50:53]
	ds_read_b128 v[90:93], v48 offset:57344
	ds_read_b128 v[110:113], v48 offset:59392
	ds_read_b128 v[114:117], v48 offset:61440
	ds_read_b128 v[118:121], v48 offset:63488
	v_mfma_f32_16x16x32_bf16 v[74:77], v[86:89], v[8:11], v[74:77]
	s_waitcnt lgkmcnt(7)
	v_mfma_f32_16x16x32_bf16 v[54:57], v[54:57], v[8:11], v[58:61]
	s_waitcnt lgkmcnt(6)
	v_mfma_f32_16x16x32_bf16 v[58:61], v[98:101], v[8:11], v[62:65]
	s_waitcnt lgkmcnt(5)
	v_mfma_f32_16x16x32_bf16 v[62:65], v[102:105], v[8:11], v[66:69]
	s_waitcnt lgkmcnt(4)
	v_mfma_f32_16x16x32_bf16 v[66:69], v[106:109], v[8:11], v[78:81]
	s_waitcnt lgkmcnt(3)
	v_mfma_f32_16x16x32_bf16 v[70:73], v[90:93], v[8:11], v[70:73]
	s_waitcnt lgkmcnt(2)
	v_mfma_f32_16x16x32_bf16 v[78:81], v[110:113], v[8:11], v[82:85]
	s_nop 2
	ds_read_b128 v[82:85], v48 offset:15360
	ds_read_b128 v[86:89], v48 offset:13312
	ds_read_b128 v[90:93], v48 offset:11264
	ds_read_b128 v[98:101], v48 offset:9216
	s_waitcnt lgkmcnt(5)
	v_mfma_f32_16x16x32_bf16 v[94:97], v[114:117], v[8:11], v[94:97]
	ds_read_b128 v[102:105], v48 offset:7168
	ds_read_b128 v[106:109], v48 offset:5120
	ds_read_b128 v[110:113], v48 offset:3072
	ds_read_b128 v[114:117], v48 offset:1024
	s_waitcnt lgkmcnt(8)
	v_mfma_f32_16x16x32_bf16 v[8:11], v[118:121], v[8:11], v[12:15]
	s_waitcnt lgkmcnt(0)
	v_mfma_f32_16x16x32_bf16 v[12:15], v[114:117], v[4:7], v[16:19]
	v_mfma_f32_16x16x32_bf16 v[16:19], v[110:113], v[4:7], v[20:23]
	v_mfma_f32_16x16x32_bf16 v[20:23], v[106:109], v[4:7], v[24:27]
	v_mfma_f32_16x16x32_bf16 v[24:27], v[102:105], v[4:7], v[28:31]
	v_mfma_f32_16x16x32_bf16 v[28:31], v[98:101], v[4:7], v[38:41]
	v_mfma_f32_16x16x32_bf16 v[38:41], v[90:93], v[4:7], v[42:45]
	s_nop 2
	ds_read_b128 v[42:45], v48 offset:33792
	ds_read_b128 v[90:93], v48 offset:35840
	ds_read_b128 v[98:101], v48 offset:37888
	ds_read_b128 v[102:105], v48 offset:39936
	v_mfma_f32_16x16x32_bf16 v[50:53], v[86:89], v[4:7], v[50:53]
	ds_read_b128 v[86:89], v48 offset:41984
	ds_read_b128 v[106:109], v48 offset:44032
	ds_read_b128 v[110:113], v48 offset:46080
	ds_read_b128 v[114:117], v48 offset:48128
	v_mfma_f32_16x16x32_bf16 v[74:77], v[82:85], v[4:7], v[74:77]
	s_waitcnt lgkmcnt(7)
	v_mfma_f32_16x16x32_bf16 v[42:45], v[42:45], v[4:7], v[54:57]
	s_waitcnt lgkmcnt(6)
	v_mfma_f32_16x16x32_bf16 v[54:57], v[90:93], v[4:7], v[58:61]
	s_waitcnt lgkmcnt(5)
	v_mfma_f32_16x16x32_bf16 v[58:61], v[98:101], v[4:7], v[62:65]
	s_waitcnt lgkmcnt(4)
	v_mfma_f32_16x16x32_bf16 v[62:65], v[102:105], v[4:7], v[66:69]
	s_waitcnt lgkmcnt(3)
	v_mfma_f32_16x16x32_bf16 v[66:69], v[86:89], v[4:7], v[70:73]
	s_waitcnt lgkmcnt(2)
	v_mfma_f32_16x16x32_bf16 v[70:73], v[106:109], v[4:7], v[78:81]
	s_nop 2
	ds_read_b128 v[78:81], v48 offset:31744
	ds_read_b128 v[82:85], v48 offset:29696
	ds_read_b128 v[86:89], v48 offset:27648
	ds_read_b128 v[90:93], v48 offset:25600
	s_waitcnt lgkmcnt(5)
	v_mfma_f32_16x16x32_bf16 v[94:97], v[110:113], v[4:7], v[94:97]
	ds_read_b128 v[98:101], v48 offset:23552
	ds_read_b128 v[102:105], v48 offset:21504
	ds_read_b128 v[106:109], v48 offset:19456
	ds_read_b128 v[110:113], v48 offset:17408
	s_waitcnt lgkmcnt(8)
	v_mfma_f32_16x16x32_bf16 v[4:7], v[114:117], v[4:7], v[8:11]
	s_waitcnt lgkmcnt(0)
	v_mfma_f32_16x16x32_bf16 v[8:11], v[110:113], v[0:3], v[12:15]
	v_mfma_f32_16x16x32_bf16 v[12:15], v[106:109], v[0:3], v[16:19]
	v_mfma_f32_16x16x32_bf16 v[16:19], v[102:105], v[0:3], v[20:23]
	v_mfma_f32_16x16x32_bf16 v[20:23], v[98:101], v[0:3], v[24:27]
	v_mfma_f32_16x16x32_bf16 v[24:27], v[90:93], v[0:3], v[28:31]
	v_mfma_f32_16x16x32_bf16 v[28:31], v[86:89], v[0:3], v[38:41]
	s_nop 2
	ds_read_b128 v[38:41], v48 offset:50176
	ds_read_b128 v[86:89], v48 offset:52224
	ds_read_b128 v[90:93], v48 offset:54272
	ds_read_b128 v[98:101], v48 offset:56320
	v_mfma_f32_16x16x32_bf16 v[50:53], v[82:85], v[0:3], v[50:53]
	ds_read_b128 v[82:85], v48 offset:58368
	ds_read_b128 v[102:105], v48 offset:60416
	ds_read_b128 v[106:109], v48 offset:62464
	ds_read_b128 v[46:49], v48 offset:64512
	v_mfma_f32_16x16x32_bf16 v[74:77], v[78:81], v[0:3], v[74:77]
	s_waitcnt lgkmcnt(7)
	v_mfma_f32_16x16x32_bf16 v[38:41], v[38:41], v[0:3], v[42:45]
	s_waitcnt lgkmcnt(6)
	v_mfma_f32_16x16x32_bf16 v[42:45], v[86:89], v[0:3], v[54:57]
	s_waitcnt lgkmcnt(5)
	v_mfma_f32_16x16x32_bf16 v[54:57], v[90:93], v[0:3], v[58:61]
	s_waitcnt lgkmcnt(4)
	v_mfma_f32_16x16x32_bf16 v[58:61], v[98:101], v[0:3], v[62:65]
	s_waitcnt lgkmcnt(3)
	v_mfma_f32_16x16x32_bf16 v[62:65], v[82:85], v[0:3], v[66:69]
	s_waitcnt lgkmcnt(2)
	v_mfma_f32_16x16x32_bf16 v[66:69], v[102:105], v[0:3], v[70:73]
	s_waitcnt lgkmcnt(1)
	v_mfma_f32_16x16x32_bf16 v[70:73], v[106:109], v[0:3], v[94:97]
	s_waitcnt lgkmcnt(0)
	v_mfma_f32_16x16x32_bf16 v[0:3], v[46:49], v[0:3], v[4:7]
	s_nop 2
	v_mul_f32_e32 v200, v36, v8
	v_mul_f32_e32 v204, v36, v9
	v_cvt_pk_bf16_f32 v200, v200, v204
	v_mul_f32_e32 v201, v36, v10
	v_mul_f32_e32 v204, v36, v11
	v_cvt_pk_bf16_f32 v201, v201, v204
	v_mul_f32_e32 v202, v36, v12
	v_mul_f32_e32 v204, v36, v13
	v_cvt_pk_bf16_f32 v202, v202, v204
	v_mul_f32_e32 v203, v36, v14
	v_mul_f32_e32 v204, v36, v15
	v_cvt_pk_bf16_f32 v203, v203, v204
	s_nop 1
	v_permlane16_swap_b32_e32 v200, v202
	v_permlane16_swap_b32_e32 v201, v203
	global_store_dwordx4 v[214:215], v[200:203], off offset:512
	v_mul_f32_e32 v206, v36, v16
	v_mul_f32_e32 v210, v36, v17
	v_cvt_pk_bf16_f32 v206, v206, v210
	v_mul_f32_e32 v207, v36, v18
	v_mul_f32_e32 v210, v36, v19
	v_cvt_pk_bf16_f32 v207, v207, v210
	v_mul_f32_e32 v208, v36, v20
	v_mul_f32_e32 v210, v36, v21
	v_cvt_pk_bf16_f32 v208, v208, v210
	v_mul_f32_e32 v209, v36, v22
	v_mul_f32_e32 v210, v36, v23
	v_cvt_pk_bf16_f32 v209, v209, v210
	s_nop 1
	v_permlane16_swap_b32_e32 v206, v208
	v_permlane16_swap_b32_e32 v207, v209
	global_store_dwordx4 v[214:215], v[206:209], off offset:576
	v_mul_f32_e32 v200, v36, v24
	v_mul_f32_e32 v204, v36, v25
	v_cvt_pk_bf16_f32 v200, v200, v204
	v_mul_f32_e32 v201, v36, v26
	v_mul_f32_e32 v204, v36, v27
	v_cvt_pk_bf16_f32 v201, v201, v204
	v_mul_f32_e32 v202, v36, v28
	v_mul_f32_e32 v204, v36, v29
	v_cvt_pk_bf16_f32 v202, v202, v204
	v_mul_f32_e32 v203, v36, v30
	v_mul_f32_e32 v204, v36, v31
	v_cvt_pk_bf16_f32 v203, v203, v204
	s_nop 1
	v_permlane16_swap_b32_e32 v200, v202
	v_permlane16_swap_b32_e32 v201, v203
	global_store_dwordx4 v[214:215], v[200:203], off offset:640
	v_mul_f32_e32 v206, v36, v50
	v_mul_f32_e32 v210, v36, v51
	v_cvt_pk_bf16_f32 v206, v206, v210
	v_mul_f32_e32 v207, v36, v52
	v_mul_f32_e32 v210, v36, v53
	v_cvt_pk_bf16_f32 v207, v207, v210
	v_mul_f32_e32 v208, v36, v74
	v_mul_f32_e32 v210, v36, v75
	v_cvt_pk_bf16_f32 v208, v208, v210
	v_mul_f32_e32 v209, v36, v76
	v_mul_f32_e32 v210, v36, v77
	v_cvt_pk_bf16_f32 v209, v209, v210
	s_nop 1
	v_permlane16_swap_b32_e32 v206, v208
	v_permlane16_swap_b32_e32 v207, v209
	global_store_dwordx4 v[214:215], v[206:209], off offset:704
	v_mul_f32_e32 v200, v36, v38
	v_mul_f32_e32 v204, v36, v39
	v_cvt_pk_bf16_f32 v200, v200, v204
	v_mul_f32_e32 v201, v36, v40
	v_mul_f32_e32 v204, v36, v41
	v_cvt_pk_bf16_f32 v201, v201, v204
	v_mul_f32_e32 v202, v36, v42
	v_mul_f32_e32 v204, v36, v43
	v_cvt_pk_bf16_f32 v202, v202, v204
	v_mul_f32_e32 v203, v36, v44
	v_mul_f32_e32 v204, v36, v45
	v_cvt_pk_bf16_f32 v203, v203, v204
	s_nop 1
	v_permlane16_swap_b32_e32 v200, v202
	v_permlane16_swap_b32_e32 v201, v203
	global_store_dwordx4 v[214:215], v[200:203], off offset:768
	v_mul_f32_e32 v206, v36, v54
	v_mul_f32_e32 v210, v36, v55
	v_cvt_pk_bf16_f32 v206, v206, v210
	v_mul_f32_e32 v207, v36, v56
	v_mul_f32_e32 v210, v36, v57
	v_cvt_pk_bf16_f32 v207, v207, v210
	v_mul_f32_e32 v208, v36, v58
	v_mul_f32_e32 v210, v36, v59
	v_cvt_pk_bf16_f32 v208, v208, v210
	v_mul_f32_e32 v209, v36, v60
	v_mul_f32_e32 v210, v36, v61
	v_cvt_pk_bf16_f32 v209, v209, v210
	s_nop 1
	v_permlane16_swap_b32_e32 v206, v208
	v_permlane16_swap_b32_e32 v207, v209
	global_store_dwordx4 v[214:215], v[206:209], off offset:832
	v_mul_f32_e32 v200, v36, v62
	v_mul_f32_e32 v204, v36, v63
	v_cvt_pk_bf16_f32 v200, v200, v204
	v_mul_f32_e32 v201, v36, v64
	v_mul_f32_e32 v204, v36, v65
	v_cvt_pk_bf16_f32 v201, v201, v204
	v_mul_f32_e32 v202, v36, v66
	v_mul_f32_e32 v204, v36, v67
	v_cvt_pk_bf16_f32 v202, v202, v204
	v_mul_f32_e32 v203, v36, v68
	v_mul_f32_e32 v204, v36, v69
	v_cvt_pk_bf16_f32 v203, v203, v204
	s_nop 1
	v_permlane16_swap_b32_e32 v200, v202
	v_permlane16_swap_b32_e32 v201, v203
	global_store_dwordx4 v[214:215], v[200:203], off offset:896
	v_mul_f32_e32 v206, v36, v70
	v_mul_f32_e32 v210, v36, v71
	v_cvt_pk_bf16_f32 v206, v206, v210
	v_mul_f32_e32 v207, v36, v72
	v_mul_f32_e32 v210, v36, v73
	v_cvt_pk_bf16_f32 v207, v207, v210
	v_mul_f32_e32 v208, v36, v0
	v_mul_f32_e32 v210, v36, v1
	v_cvt_pk_bf16_f32 v208, v208, v210
	v_mul_f32_e32 v209, v36, v2
	v_mul_f32_e32 v210, v36, v3
	v_cvt_pk_bf16_f32 v209, v209, v210
	s_nop 1
	v_permlane16_swap_b32_e32 v206, v208
	v_permlane16_swap_b32_e32 v207, v209
	global_store_dwordx4 v[214:215], v[206:209], off offset:960
	s_waitcnt vmcnt(0)
	s_barrier

.LBB0_1739:
.LBB0_1740:
	s_add_i32 s0, 0, 0x23f94
	s_waitcnt vmcnt(0)
	v_mov_b32_e32 v0, s0
	v_mbcnt_lo_u32_b32 v58, -1, 0
	v_mbcnt_hi_u32_b32 v58, -1, v58
	ds_read_b32 v0, v0
	v_lshlrev_b32_e32 v71, 4, v58
	v_and_b32_e32 v59, 15, v58
	s_mov_b32 s1, 0
	v_ashrrev_i32_e32 v70, 4, v58
	s_waitcnt lgkmcnt(0)
	v_readfirstlane_b32 s0, v0
	s_and_b32 s4, s0, 7
	s_mul_i32 s5, s4, 0x1400000
	s_add_u32 s5, s94, s5
	s_addc_u32 s6, s95, 0
	s_lshl_b32 s4, s4, 22
	s_sub_u32 s4, 0, s4
	s_subb_u32 s7, 0, 0
	s_add_u32 s4, s5, s4
	s_addc_u32 s5, s6, s7
	s_lshl_b32 s8, s88, 10
	v_add_u32_e32 v0, s8, v71
	v_ashrrev_i32_e32 v1, 31, v0
	v_lshrrev_b32_e32 v1, 22, v1
	v_add_u32_e32 v1, v0, v1
	v_ashrrev_i32_e32 v1, 10, v1
	v_mul_i32_i24_e32 v2, 0x400, v1
	v_sub_u32_e32 v2, v0, v2
	v_lshrrev_b32_e32 v3, 4, v2
	v_bitop3_b32 v2, v3, v2, 32 bitop3:0x6c
	v_ashrrev_i32_e32 v4, 31, v2
	v_lshrrev_b32_e32 v4, 26, v4
	v_lshlrev_b32_e32 v3, 3, v1
	v_add_u32_e32 v4, v2, v4
	v_and_b32_e32 v3, -16, v3
	v_ashrrev_i32_e32 v5, 6, v4
	v_add_u32_e32 v104, v5, v3
	v_and_b32_e32 v3, 0xc0, v4
	v_lshlrev_b32_e32 v1, 5, v1
	v_sub_u32_e32 v2, v2, v3
	v_mov_b32_e32 v3, 1
	v_and_b32_e32 v1, 32, v1
	v_ashrrev_i16_sdwa v2, v3, sext(v2) dst_sel:DWORD dst_unused:UNUSED_PAD src0_sel:DWORD src1_sel:BYTE_0
	v_add_u32_sdwa v1, v1, sext(v2) dst_sel:DWORD dst_unused:UNUSED_PAD src0_sel:DWORD src1_sel:WORD_0
	v_lshlrev_b32_e32 v2, 10, v104
	v_add_u32_e32 v0, 0x2000, v0
	v_lshl_add_u32 v62, v1, 1, v2
	v_ashrrev_i32_e32 v1, 31, v0
	v_lshrrev_b32_e32 v1, 22, v1
	v_add_u32_e32 v1, v0, v1
	v_ashrrev_i32_e32 v1, 10, v1
	v_mul_i32_i24_e32 v2, 0x400, v1
	v_sub_u32_e32 v0, v0, v2
	v_lshrrev_b32_e32 v2, 4, v0
	s_lshl_b32 s6, s0, 3
	v_bitop3_b32 v0, v2, v0, 32 bitop3:0x6c
	s_and_b32 s6, s6, 56
	s_ashr_i32 s7, s0, 5
	v_ashrrev_i32_e32 v4, 31, v0
	s_add_i32 s9, s6, s7
	v_lshrrev_b32_e32 v4, 26, v4
	s_ashr_i32 s12, s9, 5
	v_lshlrev_b32_e32 v2, 3, v1
	v_add_u32_e32 v4, v0, v4
	s_bfe_u32 s0, s0, 0x20003
	s_lshl_b32 s6, s12, 2
	v_and_b32_e32 v2, -16, v2
	v_ashrrev_i32_e32 v5, 6, v4
	s_or_b32 s6, s6, s0
	v_add_u32_e32 v108, v5, v2
	v_and_b32_e32 v2, 0xffc0, v4
	s_ashr_i32 s7, s6, 31
	v_sub_u32_e32 v0, v0, v2
	s_lshl_b64 s[6:7], s[6:7], 18
	v_lshrrev_b16_e32 v2, 7, v0
	s_add_u32 s10, s94, s6
	v_and_b32_e32 v2, 1, v2
	s_addc_u32 s11, s95, s7
	v_lshlrev_b32_e32 v1, 5, v1
	v_add_u16_e32 v0, v0, v2
	s_add_u32 s6, s10, 0x11600000
	v_and_b32_e32 v1, 32, v1
	v_ashrrev_i16_sdwa v0, v3, sext(v0) dst_sel:DWORD dst_unused:UNUSED_PAD src0_sel:DWORD src1_sel:BYTE_0
	s_addc_u32 s7, s11, 0
	s_lshl_b32 s9, s9, 7
	v_add_u32_sdwa v0, v1, sext(v0) dst_sel:DWORD dst_unused:UNUSED_PAD src0_sel:DWORD src1_sel:WORD_0
	v_lshlrev_b32_e32 v1, 10, v108
	s_lshl_b32 s12, s12, 12
	s_and_b32 s9, s9, 0xf80
	v_lshl_add_u32 v64, v0, 1, v1
	v_lshl_or_b32 v1, s88, 4, v59
	s_or_b32 s9, s12, s9
	v_add_u32_e32 v2, s9, v1
	v_ashrrev_i32_e32 v3, 31, v2
	v_lshlrev_b64 v[2:3], 12, v[2:3]
	s_lshl_b32 s0, s0, 10
	v_lshl_add_u64 v[2:3], s[4:5], 0, v[2:3]
	v_lshlrev_b32_e32 v0, 3, v70
	v_lshl_add_u64 v[2:3], v[2:3], 0, s[0:1]
	s_mov_b64 s[0:1], 0x13000000
	v_ashrrev_i32_e32 v1, 31, v0
	v_lshl_add_u64 v[60:61], v[2:3], 0, s[0:1]
	v_lshl_add_u64 v[0:1], v[0:1], 1, v[60:61]
	s_mov_b64 s[0:1], 0xc00000
	v_lshl_add_u64 v[2:3], v[0:1], 0, s[0:1]
	s_mov_b32 s0, 0xc00000
	v_add_co_u32_e32 v0, vcc, s0, v0
	s_add_i32 s22, s8, 0
	s_nop 0
	v_addc_co_u32_e32 v1, vcc, 0, v1, vcc
	v_mov_b32_e32 v63, 0
	s_mov_b32 m0, s22
	s_add_i32 s21, s22, 0x2000
	global_load_dwordx4 v[72:75], v[2:3], off offset:64
	global_load_dwordx4 v[52:55], v[2:3], off offset:128
	global_load_dwordx4 v[48:51], v[2:3], off offset:192
	global_load_dwordx4 v[44:47], v[2:3], off offset:256
	global_load_dwordx4 v[40:43], v[2:3], off offset:320
	global_load_dwordx4 v[36:39], v[2:3], off offset:384
	global_load_dwordx4 v[32:35], v[2:3], off offset:448
	global_load_dwordx4 v[28:31], v[2:3], off offset:512
	global_load_dwordx4 v[24:27], v[2:3], off offset:576
	global_load_dwordx4 v[20:23], v[2:3], off offset:640
	global_load_dwordx4 v[16:19], v[2:3], off offset:704
	global_load_dwordx4 v[12:15], v[2:3], off offset:768
	global_load_dwordx4 v[8:11], v[2:3], off offset:832
	global_load_dwordx4 v[4:7], v[2:3], off offset:896
	global_load_dwordx4 v[76:79], v[0:1], off
	s_nop 0
	global_load_dwordx4 v[0:3], v[2:3], off offset:960
	v_mov_b32_e32 v65, v63
	global_load_lds_dwordx4 v62, s[6:7]
	v_mov_b32_e32 v240, v62
	s_mov_b32 m0, s21
	v_lshl_add_u64 v[66:67], s[6:7], 0, v[62:63]
	v_lshl_add_u64 v[68:69], s[6:7], 0, v[64:65]
	global_load_lds_dwordx4 v64, s[6:7]
	s_add_i32 s20, s22, 0x4000
	s_mov_b64 s[6:7], 0x80
	s_add_i32 s23, s22, 0x6000
	v_lshl_add_u64 v[56:57], v[66:67], 0, s[6:7]
	s_mov_b32 m0, s20
	s_add_u32 s0, s10, 0x11620000
	global_load_lds_dwordx4 v[56:57], off
	v_lshl_add_u64 v[56:57], v[68:69], 0, s[6:7]
	s_mov_b32 m0, s23
	s_addc_u32 s1, s11, 0
	s_add_i32 s24, s22, 0x8000
	global_load_lds_dwordx4 v[56:57], off
	s_mov_b32 m0, s24
	s_add_i32 s25, s22, 0xa000
	global_load_lds_dwordx4 v62, s[0:1]
	s_mov_b32 m0, s25
	s_mov_b64 s[4:5], 0x180
	global_load_lds_dwordx4 v64, s[0:1]
	s_add_u32 s0, s10, 0x11620080
	s_addc_u32 s1, s11, 0
	s_add_i32 s26, s22, 0xc000
	s_mov_b32 m0, s26
	s_add_i32 s27, s22, 0xe000
	global_load_lds_dwordx4 v62, s[0:1]
	s_mov_b32 m0, s27
	s_add_u32 s8, s10, 0x11e00000
	global_load_lds_dwordx4 v64, s[0:1]
	s_addc_u32 s9, s11, 0
	s_add_i32 s19, s22, 0x10000
	s_mov_b64 s[0:1], 0x100
	v_lshl_add_u64 v[56:57], v[66:67], 0, s[0:1]
	s_mov_b32 m0, s19
	s_add_i32 s13, s22, 0x12000
	s_waitcnt vmcnt(0)
	s_waitcnt vmcnt(0) lgkmcnt(0)
	s_barrier
	global_load_lds_dwordx4 v[56:57], off
	v_lshl_add_u64 v[56:57], v[68:69], 0, s[0:1]
	s_mov_b32 m0, s13
	s_add_i32 s12, s22, 0x14000
	s_add_i32 s14, s22, 0x16000
	global_load_lds_dwordx4 v[56:57], off
	v_lshl_add_u64 v[56:57], v[66:67], 0, s[4:5]
	s_mov_b32 m0, s12
	s_add_u32 s28, s10, 0x11620100
	global_load_lds_dwordx4 v[56:57], off
	v_lshl_add_u64 v[56:57], v[68:69], 0, s[4:5]
	s_mov_b32 m0, s14
	s_addc_u32 s29, s11, 0
	s_add_i32 s15, s22, 0x18000
	global_load_lds_dwordx4 v[56:57], off
	s_mov_b32 m0, s15
	s_add_i32 s16, s22, 0x1a000
	global_load_lds_dwordx4 v62, s[28:29]
	s_mov_b32 m0, s16
	v_and_b32_e32 v57, 48, v58
	global_load_lds_dwordx4 v64, s[28:29]
	s_add_u32 s28, s10, 0x11620180
	s_addc_u32 s29, s11, 0
	s_add_i32 s17, s22, 0x1c000
	s_mov_b32 m0, s17
	s_add_i32 s18, s22, 0x1e000
	global_load_lds_dwordx4 v62, s[28:29]
	s_mov_b32 m0, s18
	v_lshlrev_b32_e32 v58, 2, v58
	global_load_lds_dwordx4 v64, s[28:29]
	v_lshlrev_b32_e32 v56, 6, v59
	v_and_b32_e32 v58, 32, v58
	v_bitop3_b32 v56, v56, v58, v57 bitop3:0x36
	v_and_b32_e32 v57, 0xfffffc00, v71
	v_add3_u32 v65, 0, v56, v57
	v_mov_b32_e32 v71, v65
	ds_read_b128 v[56:59], v71
	ds_read_b128 v[80:83], v71 offset:2048
	s_waitcnt lgkmcnt(0)
	v_mfma_f32_16x16x32_bf16 v[84:87], v[56:59], v[76:79], 0
	ds_read_b128 v[56:59], v71 offset:4096
	ds_read_b128 v[88:91], v71 offset:6144
	ds_read_b128 v[96:99], v71 offset:8192
	ds_read_b128 v[100:103], v71 offset:10240
	s_waitcnt lgkmcnt(0)
	v_mfma_f32_16x16x32_bf16 v[92:95], v[56:59], v[76:79], 0
	v_lshlrev_b32_e32 v56, 9, v104
	ds_read_b128 v[104:107], v71 offset:12288
	v_lshlrev_b32_e32 v57, 9, v108
	ds_read_b128 v[108:111], v71 offset:14336
	ds_read_b128 v[112:115], v71 offset:32768
	ds_read_b128 v[116:119], v71 offset:34816
	ds_read_b128 v[120:123], v71 offset:36864
	ds_read_b128 v[124:127], v71 offset:38912
	ds_read_b128 v[128:131], v71 offset:40960
	ds_read_b128 v[132:135], v71 offset:43008
	ds_read_b128 v[136:139], v71 offset:45056
	ds_read_b128 v[140:143], v71 offset:47104
	v_mfma_f32_16x16x32_bf16 v[80:83], v[80:83], v[76:79], 0
	v_sub_u32_e32 v56, v62, v56
	v_mov_b32_e32 v241, v56
	v_sub_u32_e32 v58, v64, v57
	v_mfma_f32_16x16x32_bf16 v[88:91], v[88:91], v[76:79], 0
	v_mfma_f32_16x16x32_bf16 v[96:99], v[96:99], v[76:79], 0
	v_mfma_f32_16x16x32_bf16 v[100:103], v[100:103], v[76:79], 0
	s_waitcnt lgkmcnt(0)
	v_mfma_f32_16x16x32_bf16 v[104:107], v[104:107], v[76:79], 0
	v_mfma_f32_16x16x32_bf16 v[108:111], v[108:111], v[76:79], 0
	ds_read_b128 v[144:147], v71 offset:15360
	ds_read_b128 v[148:151], v71 offset:13312
	ds_read_b128 v[152:155], v71 offset:11264
	ds_read_b128 v[156:159], v71 offset:9216
	ds_read_b128 v[160:163], v71 offset:7168
	ds_read_b128 v[164:167], v71 offset:5120
	ds_read_b128 v[168:171], v71 offset:3072
	ds_read_b128 v[172:175], v71 offset:1024
	v_mfma_f32_16x16x32_bf16 v[112:115], v[112:115], v[76:79], 0
	v_mfma_f32_16x16x32_bf16 v[116:119], v[116:119], v[76:79], 0
	v_mfma_f32_16x16x32_bf16 v[120:123], v[120:123], v[76:79], 0
	v_mfma_f32_16x16x32_bf16 v[124:127], v[124:127], v[76:79], 0
	v_mfma_f32_16x16x32_bf16 v[128:131], v[128:131], v[76:79], 0
	v_mfma_f32_16x16x32_bf16 v[132:135], v[132:135], v[76:79], 0
	v_mfma_f32_16x16x32_bf16 v[136:139], v[136:139], v[76:79], 0
	v_mfma_f32_16x16x32_bf16 v[76:79], v[140:143], v[76:79], 0
	s_waitcnt lgkmcnt(0)
	v_mfma_f32_16x16x32_bf16 v[84:87], v[172:175], v[72:75], v[84:87]
	v_mfma_f32_16x16x32_bf16 v[80:83], v[168:171], v[72:75], v[80:83]
	v_mfma_f32_16x16x32_bf16 v[92:95], v[164:167], v[72:75], v[92:95]
	v_mfma_f32_16x16x32_bf16 v[88:91], v[160:163], v[72:75], v[88:91]
	v_mfma_f32_16x16x32_bf16 v[96:99], v[156:159], v[72:75], v[96:99]
	v_mfma_f32_16x16x32_bf16 v[100:103], v[152:155], v[72:75], v[100:103]
	ds_read_b128 v[140:143], v71 offset:33792
	ds_read_b128 v[152:155], v71 offset:35840
	ds_read_b128 v[156:159], v71 offset:37888
	ds_read_b128 v[160:163], v71 offset:39936
	v_mfma_f32_16x16x32_bf16 v[104:107], v[148:151], v[72:75], v[104:107]
	ds_read_b128 v[148:151], v71 offset:41984
	ds_read_b128 v[164:167], v71 offset:44032
	ds_read_b128 v[168:171], v71 offset:46080
	ds_read_b128 v[172:175], v71 offset:48128
	v_mfma_f32_16x16x32_bf16 v[108:111], v[144:147], v[72:75], v[108:111]
	s_waitcnt lgkmcnt(0)
	v_mfma_f32_16x16x32_bf16 v[112:115], v[140:143], v[72:75], v[112:115]
	v_mfma_f32_16x16x32_bf16 v[116:119], v[152:155], v[72:75], v[116:119]
	v_mfma_f32_16x16x32_bf16 v[120:123], v[156:159], v[72:75], v[120:123]
	v_mfma_f32_16x16x32_bf16 v[124:127], v[160:163], v[72:75], v[124:127]
	v_mfma_f32_16x16x32_bf16 v[128:131], v[148:151], v[72:75], v[128:131]
	ds_read_b128 v[140:143], v71 offset:30720
	ds_read_b128 v[144:147], v71 offset:28672
	ds_read_b128 v[148:151], v71 offset:26624
	ds_read_b128 v[152:155], v71 offset:24576
	v_mfma_f32_16x16x32_bf16 v[132:135], v[164:167], v[72:75], v[132:135]
	v_mfma_f32_16x16x32_bf16 v[136:139], v[168:171], v[72:75], v[136:139]
	ds_read_b128 v[156:159], v71 offset:22528
	ds_read_b128 v[160:163], v71 offset:20480
	ds_read_b128 v[164:167], v71 offset:18432
	ds_read_b128 v[168:171], v71 offset:16384
	v_mfma_f32_16x16x32_bf16 v[72:75], v[172:175], v[72:75], v[76:79]
	s_waitcnt lgkmcnt(0)
	v_mfma_f32_16x16x32_bf16 v[76:79], v[168:171], v[52:55], v[84:87]
	v_mfma_f32_16x16x32_bf16 v[80:83], v[164:167], v[52:55], v[80:83]
	v_mfma_f32_16x16x32_bf16 v[84:87], v[160:163], v[52:55], v[92:95]
	v_mfma_f32_16x16x32_bf16 v[88:91], v[156:159], v[52:55], v[88:91]
	v_mfma_f32_16x16x32_bf16 v[92:95], v[152:155], v[52:55], v[96:99]
	v_mfma_f32_16x16x32_bf16 v[96:99], v[148:151], v[52:55], v[100:103]
	s_nop 2
	ds_read_b128 v[100:103], v71 offset:49152
	ds_read_b128 v[148:151], v71 offset:51200
	ds_read_b128 v[152:155], v71 offset:53248
	ds_read_b128 v[156:159], v71 offset:55296
	v_mfma_f32_16x16x32_bf16 v[104:107], v[144:147], v[52:55], v[104:107]
	ds_read_b128 v[144:147], v71 offset:57344
	ds_read_b128 v[160:163], v71 offset:59392
	ds_read_b128 v[164:167], v71 offset:61440
	ds_read_b128 v[168:171], v71 offset:63488
	v_mfma_f32_16x16x32_bf16 v[108:111], v[140:143], v[52:55], v[108:111]
	s_waitcnt lgkmcnt(0)
	v_mfma_f32_16x16x32_bf16 v[100:103], v[100:103], v[52:55], v[112:115]
	v_mfma_f32_16x16x32_bf16 v[112:115], v[148:151], v[52:55], v[116:119]
	v_mfma_f32_16x16x32_bf16 v[116:119], v[152:155], v[52:55], v[120:123]
	v_mfma_f32_16x16x32_bf16 v[120:123], v[156:159], v[52:55], v[124:127]
	v_mfma_f32_16x16x32_bf16 v[124:127], v[144:147], v[52:55], v[128:131]
	v_mfma_f32_16x16x32_bf16 v[128:131], v[160:163], v[52:55], v[132:135]
	s_nop 2
	ds_read_b128 v[132:135], v71 offset:31744
	ds_read_b128 v[140:143], v71 offset:29696
	ds_read_b128 v[144:147], v71 offset:27648
	ds_read_b128 v[148:151], v71 offset:25600
	v_mfma_f32_16x16x32_bf16 v[136:139], v[164:167], v[52:55], v[136:139]
	ds_read_b128 v[152:155], v71 offset:23552
	ds_read_b128 v[156:159], v71 offset:21504
	ds_read_b128 v[160:163], v71 offset:19456
	ds_read_b128 v[164:167], v71 offset:17408
	v_mfma_f32_16x16x32_bf16 v[52:55], v[168:171], v[52:55], v[72:75]
	s_waitcnt lgkmcnt(0)
	v_mfma_f32_16x16x32_bf16 v[72:75], v[164:167], v[48:51], v[76:79]
	v_mfma_f32_16x16x32_bf16 v[76:79], v[160:163], v[48:51], v[80:83]
	v_mfma_f32_16x16x32_bf16 v[80:83], v[156:159], v[48:51], v[84:87]
	v_mfma_f32_16x16x32_bf16 v[84:87], v[152:155], v[48:51], v[88:91]
	v_mfma_f32_16x16x32_bf16 v[88:91], v[148:151], v[48:51], v[92:95]
	v_mfma_f32_16x16x32_bf16 v[92:95], v[144:147], v[48:51], v[96:99]
	s_nop 2
	ds_read_b128 v[96:99], v71 offset:50176
	ds_read_b128 v[144:147], v71 offset:52224
	ds_read_b128 v[148:151], v71 offset:54272
	ds_read_b128 v[152:155], v71 offset:56320
	v_mfma_f32_16x16x32_bf16 v[104:107], v[140:143], v[48:51], v[104:107]
	ds_read_b128 v[140:143], v71 offset:58368
	ds_read_b128 v[156:159], v71 offset:60416
	ds_read_b128 v[160:163], v71 offset:62464
	ds_read_b128 v[164:167], v71 offset:64512
	v_mfma_f32_16x16x32_bf16 v[108:111], v[132:135], v[48:51], v[108:111]
	s_waitcnt lgkmcnt(0)
	v_mfma_f32_16x16x32_bf16 v[96:99], v[96:99], v[48:51], v[100:103]
	v_mfma_f32_16x16x32_bf16 v[100:103], v[144:147], v[48:51], v[112:115]
	v_mfma_f32_16x16x32_bf16 v[112:115], v[148:151], v[48:51], v[116:119]
	v_mfma_f32_16x16x32_bf16 v[116:119], v[152:155], v[48:51], v[120:123]
	v_mfma_f32_16x16x32_bf16 v[120:123], v[140:143], v[48:51], v[124:127]
	v_mfma_f32_16x16x32_bf16 v[124:127], v[156:159], v[48:51], v[128:131]
	v_mfma_f32_16x16x32_bf16 v[128:131], v[160:163], v[48:51], v[136:139]
	v_mfma_f32_16x16x32_bf16 v[50:53], v[164:167], v[48:51], v[52:55]
	s_waitcnt vmcnt(0)
	s_waitcnt vmcnt(0)
	s_barrier
	v_add_u32_e32 v48, 0x10000, v65
	v_mov_b32_e32 v49, v48
	ds_read_b128 v[132:135], v49
	ds_read_b128 v[136:139], v49 offset:2048
	s_waitcnt lgkmcnt(0)
	v_mfma_f32_16x16x32_bf16 v[72:75], v[132:135], v[44:47], v[72:75]
	ds_read_b128 v[132:135], v49 offset:4096
	v_mfma_f32_16x16x32_bf16 v[76:79], v[136:139], v[44:47], v[76:79]
	ds_read_b128 v[136:139], v49 offset:6144
	s_waitcnt lgkmcnt(0)
	v_mfma_f32_16x16x32_bf16 v[80:83], v[132:135], v[44:47], v[80:83]
	ds_read_b128 v[132:135], v49 offset:8192
	v_mfma_f32_16x16x32_bf16 v[84:87], v[136:139], v[44:47], v[84:87]
	ds_read_b128 v[136:139], v49 offset:10240
	s_waitcnt lgkmcnt(0)
	v_mfma_f32_16x16x32_bf16 v[88:91], v[132:135], v[44:47], v[88:91]
	ds_read_b128 v[132:135], v49 offset:12288
	ds_read_b128 v[140:143], v49 offset:14336
	v_mfma_f32_16x16x32_bf16 v[92:95], v[136:139], v[44:47], v[92:95]
	ds_read_b128 v[136:139], v49 offset:32768
	ds_read_b128 v[144:147], v49 offset:34816
	ds_read_b128 v[148:151], v49 offset:36864
	ds_read_b128 v[152:155], v49 offset:38912
	s_waitcnt lgkmcnt(0)
	v_mfma_f32_16x16x32_bf16 v[104:107], v[132:135], v[44:47], v[104:107]
	ds_read_b128 v[132:135], v49 offset:40960
	ds_read_b128 v[156:159], v49 offset:43008
	ds_read_b128 v[160:163], v49 offset:45056
	ds_read_b128 v[164:167], v49 offset:47104
	v_mfma_f32_16x16x32_bf16 v[108:111], v[140:143], v[44:47], v[108:111]
	s_add_u32 s100, s10, 0x11600200
	s_addc_u32 s101, s11, 0
	s_mov_b32 m0, s22
	s_nop 0
	global_load_lds_dwordx4 v240, s[100:101]
	v_mfma_f32_16x16x32_bf16 v[96:99], v[136:139], v[44:47], v[96:99]
	v_mfma_f32_16x16x32_bf16 v[100:103], v[144:147], v[44:47], v[100:103]
	v_mfma_f32_16x16x32_bf16 v[112:115], v[148:151], v[44:47], v[112:115]
	v_mfma_f32_16x16x32_bf16 v[116:119], v[152:155], v[44:47], v[116:119]
	s_waitcnt lgkmcnt(0)
	v_mfma_f32_16x16x32_bf16 v[120:123], v[132:135], v[44:47], v[120:123]
	ds_read_b128 v[132:135], v49 offset:15360
	ds_read_b128 v[136:139], v49 offset:13312
	ds_read_b128 v[140:143], v49 offset:11264
	ds_read_b128 v[144:147], v49 offset:9216
	v_mfma_f32_16x16x32_bf16 v[124:127], v[156:159], v[44:47], v[124:127]
	v_mfma_f32_16x16x32_bf16 v[128:131], v[160:163], v[44:47], v[128:131]
	ds_read_b128 v[148:151], v49 offset:7168
	ds_read_b128 v[152:155], v49 offset:5120
	ds_read_b128 v[156:159], v49 offset:3072
	ds_read_b128 v[160:163], v49 offset:1024
	v_mfma_f32_16x16x32_bf16 v[44:47], v[164:167], v[44:47], v[50:53]
	s_add_u32 s100, s10, 0x11610200
	s_addc_u32 s101, s11, 0
	s_mov_b32 m0, s21
	s_nop 0
	global_load_lds_dwordx4 v240, s[100:101]
	s_waitcnt lgkmcnt(0)
	v_mfma_f32_16x16x32_bf16 v[50:53], v[160:163], v[40:43], v[72:75]
	v_mfma_f32_16x16x32_bf16 v[72:75], v[156:159], v[40:43], v[76:79]
	v_mfma_f32_16x16x32_bf16 v[76:79], v[152:155], v[40:43], v[80:83]
	v_mfma_f32_16x16x32_bf16 v[80:83], v[148:151], v[40:43], v[84:87]
	v_mfma_f32_16x16x32_bf16 v[84:87], v[144:147], v[40:43], v[88:91]
	v_mfma_f32_16x16x32_bf16 v[88:91], v[140:143], v[40:43], v[92:95]
	s_nop 2
	ds_read_b128 v[92:95], v49 offset:33792
	ds_read_b128 v[140:143], v49 offset:35840
	ds_read_b128 v[144:147], v49 offset:37888
	ds_read_b128 v[148:151], v49 offset:39936
	v_mfma_f32_16x16x32_bf16 v[104:107], v[136:139], v[40:43], v[104:107]
	ds_read_b128 v[136:139], v49 offset:41984
	ds_read_b128 v[152:155], v49 offset:44032
	ds_read_b128 v[156:159], v49 offset:46080
	ds_read_b128 v[160:163], v49 offset:48128
	v_mfma_f32_16x16x32_bf16 v[108:111], v[132:135], v[40:43], v[108:111]
	s_add_u32 s100, s10, 0x11600280
	s_addc_u32 s101, s11, 0
	s_mov_b32 m0, s20
	s_nop 0
	global_load_lds_dwordx4 v240, s[100:101]
	s_waitcnt lgkmcnt(0)
	v_mfma_f32_16x16x32_bf16 v[92:95], v[92:95], v[40:43], v[96:99]
	v_mfma_f32_16x16x32_bf16 v[96:99], v[140:143], v[40:43], v[100:103]
	v_mfma_f32_16x16x32_bf16 v[100:103], v[144:147], v[40:43], v[112:115]
	v_mfma_f32_16x16x32_bf16 v[112:115], v[148:151], v[40:43], v[116:119]
	v_mfma_f32_16x16x32_bf16 v[116:119], v[136:139], v[40:43], v[120:123]
	v_mfma_f32_16x16x32_bf16 v[120:123], v[152:155], v[40:43], v[124:127]
	s_nop 2
	ds_read_b128 v[124:127], v49 offset:30720
	ds_read_b128 v[132:135], v49 offset:28672
	ds_read_b128 v[136:139], v49 offset:26624
	ds_read_b128 v[140:143], v49 offset:24576
	v_mfma_f32_16x16x32_bf16 v[128:131], v[156:159], v[40:43], v[128:131]
	ds_read_b128 v[144:147], v49 offset:22528
	ds_read_b128 v[148:151], v49 offset:20480
	ds_read_b128 v[152:155], v49 offset:18432
	ds_read_b128 v[156:159], v49 offset:16384
	v_mfma_f32_16x16x32_bf16 v[40:43], v[160:163], v[40:43], v[44:47]
	s_add_u32 s100, s10, 0x11610280
	s_addc_u32 s101, s11, 0
	s_mov_b32 m0, s23
	s_nop 0
	global_load_lds_dwordx4 v240, s[100:101]
	s_waitcnt lgkmcnt(0)
	v_mfma_f32_16x16x32_bf16 v[44:47], v[156:159], v[36:39], v[50:53]
	v_mfma_f32_16x16x32_bf16 v[50:53], v[152:155], v[36:39], v[72:75]
	v_mfma_f32_16x16x32_bf16 v[72:75], v[148:151], v[36:39], v[76:79]
	v_mfma_f32_16x16x32_bf16 v[76:79], v[144:147], v[36:39], v[80:83]
	v_mfma_f32_16x16x32_bf16 v[80:83], v[140:143], v[36:39], v[84:87]
	v_mfma_f32_16x16x32_bf16 v[84:87], v[136:139], v[36:39], v[88:91]
	s_nop 2
	ds_read_b128 v[88:91], v49 offset:49152
	ds_read_b128 v[136:139], v49 offset:51200
	ds_read_b128 v[140:143], v49 offset:53248
	ds_read_b128 v[144:147], v49 offset:55296
	v_mfma_f32_16x16x32_bf16 v[104:107], v[132:135], v[36:39], v[104:107]
	ds_read_b128 v[132:135], v49 offset:57344
	ds_read_b128 v[148:151], v49 offset:59392
	ds_read_b128 v[152:155], v49 offset:61440
	ds_read_b128 v[156:159], v49 offset:63488
	v_mfma_f32_16x16x32_bf16 v[108:111], v[124:127], v[36:39], v[108:111]
	s_add_u32 s100, s10, 0x11620200
	s_addc_u32 s101, s11, 0
	s_mov_b32 m0, s24
	s_nop 0
	global_load_lds_dwordx4 v240, s[100:101]
	s_waitcnt lgkmcnt(0)
	v_mfma_f32_16x16x32_bf16 v[88:91], v[88:91], v[36:39], v[92:95]
	v_mfma_f32_16x16x32_bf16 v[92:95], v[136:139], v[36:39], v[96:99]
	v_mfma_f32_16x16x32_bf16 v[96:99], v[140:143], v[36:39], v[100:103]
	v_mfma_f32_16x16x32_bf16 v[100:103], v[144:147], v[36:39], v[112:115]
	v_mfma_f32_16x16x32_bf16 v[112:115], v[132:135], v[36:39], v[116:119]
	v_mfma_f32_16x16x32_bf16 v[116:119], v[148:151], v[36:39], v[120:123]
	s_nop 2
	ds_read_b128 v[120:123], v49 offset:31744
	ds_read_b128 v[124:127], v49 offset:29696
	ds_read_b128 v[132:135], v49 offset:27648
	ds_read_b128 v[136:139], v49 offset:25600
	v_mfma_f32_16x16x32_bf16 v[128:131], v[152:155], v[36:39], v[128:131]
	ds_read_b128 v[140:143], v49 offset:23552
	ds_read_b128 v[144:147], v49 offset:21504
	ds_read_b128 v[148:151], v49 offset:19456
	ds_read_b128 v[152:155], v49 offset:17408
	v_mfma_f32_16x16x32_bf16 v[36:39], v[156:159], v[36:39], v[40:43]
	s_add_u32 s100, s10, 0x11630200
	s_addc_u32 s101, s11, 0
	s_mov_b32 m0, s25
	s_nop 0
	global_load_lds_dwordx4 v240, s[100:101]
	s_waitcnt lgkmcnt(0)
	v_mfma_f32_16x16x32_bf16 v[40:43], v[152:155], v[32:35], v[44:47]
	v_mfma_f32_16x16x32_bf16 v[44:47], v[148:151], v[32:35], v[50:53]
	v_mfma_f32_16x16x32_bf16 v[50:53], v[144:147], v[32:35], v[72:75]
	v_mfma_f32_16x16x32_bf16 v[72:75], v[140:143], v[32:35], v[76:79]
	v_mfma_f32_16x16x32_bf16 v[76:79], v[136:139], v[32:35], v[80:83]
	v_mfma_f32_16x16x32_bf16 v[80:83], v[132:135], v[32:35], v[84:87]
	s_nop 2
	ds_read_b128 v[84:87], v49 offset:50176
	ds_read_b128 v[132:135], v49 offset:52224
	ds_read_b128 v[136:139], v49 offset:54272
	ds_read_b128 v[140:143], v49 offset:56320
	v_mfma_f32_16x16x32_bf16 v[104:107], v[124:127], v[32:35], v[104:107]
	ds_read_b128 v[124:127], v49 offset:58368
	ds_read_b128 v[144:147], v49 offset:60416
	ds_read_b128 v[148:151], v49 offset:62464
	ds_read_b128 v[152:155], v49 offset:64512
	v_mfma_f32_16x16x32_bf16 v[108:111], v[120:123], v[32:35], v[108:111]
	s_add_u32 s100, s10, 0x11620280
	s_addc_u32 s101, s11, 0
	s_mov_b32 m0, s26
	s_nop 0
	global_load_lds_dwordx4 v240, s[100:101]
	s_waitcnt lgkmcnt(0)
	v_mfma_f32_16x16x32_bf16 v[84:87], v[84:87], v[32:35], v[88:91]
	v_mfma_f32_16x16x32_bf16 v[88:91], v[132:135], v[32:35], v[92:95]
	v_mfma_f32_16x16x32_bf16 v[92:95], v[136:139], v[32:35], v[96:99]
	v_mfma_f32_16x16x32_bf16 v[96:99], v[140:143], v[32:35], v[100:103]
	v_mfma_f32_16x16x32_bf16 v[100:103], v[124:127], v[32:35], v[112:115]
	v_mfma_f32_16x16x32_bf16 v[112:115], v[144:147], v[32:35], v[116:119]
	v_mfma_f32_16x16x32_bf16 v[116:119], v[148:151], v[32:35], v[128:131]
	v_mfma_f32_16x16x32_bf16 v[32:35], v[152:155], v[32:35], v[36:39]
	s_add_u32 s100, s10, 0x11630280
	s_addc_u32 s101, s11, 0
	s_mov_b32 m0, s27
	s_nop 0
	global_load_lds_dwordx4 v240, s[100:101]
	s_nop 0
	s_waitcnt vmcnt(0)
	s_waitcnt vmcnt(0)
	s_barrier
	v_mov_b32_e32 v49, v65
	ds_read_b128 v[36:39], v49
	ds_read_b128 v[66:69], v49 offset:2048
	s_waitcnt lgkmcnt(0)
	v_mfma_f32_16x16x32_bf16 v[36:39], v[36:39], v[28:31], v[40:43]
	s_nop 2
	ds_read_b128 v[40:43], v49 offset:4096
	v_mfma_f32_16x16x32_bf16 v[44:47], v[66:69], v[28:31], v[44:47]
	ds_read_b128 v[66:69], v49 offset:6144
	s_waitcnt lgkmcnt(0)
	v_mfma_f32_16x16x32_bf16 v[40:43], v[40:43], v[28:31], v[50:53]
	s_nop 2
	ds_read_b128 v[50:53], v49 offset:8192
	v_mfma_f32_16x16x32_bf16 v[66:69], v[66:69], v[28:31], v[72:75]
	s_nop 2
	ds_read_b128 v[72:75], v49 offset:10240
	s_waitcnt lgkmcnt(0)
	v_mfma_f32_16x16x32_bf16 v[50:53], v[50:53], v[28:31], v[76:79]
	s_nop 2
	ds_read_b128 v[76:79], v49 offset:12288
	ds_read_b128 v[120:123], v49 offset:14336
	v_mfma_f32_16x16x32_bf16 v[72:75], v[72:75], v[28:31], v[80:83]
	s_nop 2
	ds_read_b128 v[80:83], v49 offset:32768
	ds_read_b128 v[124:127], v49 offset:34816
	ds_read_b128 v[128:131], v49 offset:36864
	ds_read_b128 v[132:135], v49 offset:38912
	s_waitcnt lgkmcnt(0)
	v_mfma_f32_16x16x32_bf16 v[76:79], v[76:79], v[28:31], v[104:107]
	s_nop 2
	ds_read_b128 v[104:107], v49 offset:40960
	ds_read_b128 v[136:139], v49 offset:43008
	ds_read_b128 v[140:143], v49 offset:45056
	ds_read_b128 v[144:147], v49 offset:47104
	v_mfma_f32_16x16x32_bf16 v[108:111], v[120:123], v[28:31], v[108:111]
	s_add_u32 s100, s10, 0x11600300
	s_addc_u32 s101, s11, 0
	s_mov_b32 m0, s19
	s_nop 0
	global_load_lds_dwordx4 v240, s[100:101]
	v_mfma_f32_16x16x32_bf16 v[80:83], v[80:83], v[28:31], v[84:87]
	v_mfma_f32_16x16x32_bf16 v[84:87], v[124:127], v[28:31], v[88:91]
	v_mfma_f32_16x16x32_bf16 v[88:91], v[128:131], v[28:31], v[92:95]
	v_mfma_f32_16x16x32_bf16 v[92:95], v[132:135], v[28:31], v[96:99]
	s_waitcnt lgkmcnt(0)
	v_mfma_f32_16x16x32_bf16 v[96:99], v[104:107], v[28:31], v[100:103]
	v_mfma_f32_16x16x32_bf16 v[100:103], v[136:139], v[28:31], v[112:115]
	ds_read_b128 v[104:107], v49 offset:15360
	s_nop 1
	ds_read_b128 v[112:115], v49 offset:13312
	ds_read_b128 v[120:123], v49 offset:11264
	ds_read_b128 v[124:127], v49 offset:9216
	v_mfma_f32_16x16x32_bf16 v[116:119], v[140:143], v[28:31], v[116:119]
	ds_read_b128 v[128:131], v49 offset:7168
	ds_read_b128 v[132:135], v49 offset:5120
	ds_read_b128 v[136:139], v49 offset:3072
	ds_read_b128 v[140:143], v49 offset:1024
	v_mfma_f32_16x16x32_bf16 v[28:31], v[144:147], v[28:31], v[32:35]
	s_add_u32 s100, s10, 0x11610300
	s_addc_u32 s101, s11, 0
	s_mov_b32 m0, s13
	s_nop 0
	global_load_lds_dwordx4 v240, s[100:101]
	s_waitcnt lgkmcnt(0)
	v_mfma_f32_16x16x32_bf16 v[32:35], v[140:143], v[24:27], v[36:39]
	v_mfma_f32_16x16x32_bf16 v[36:39], v[136:139], v[24:27], v[44:47]
	v_mfma_f32_16x16x32_bf16 v[40:43], v[132:135], v[24:27], v[40:43]
	v_mfma_f32_16x16x32_bf16 v[44:47], v[128:131], v[24:27], v[66:69]
	v_mfma_f32_16x16x32_bf16 v[50:53], v[124:127], v[24:27], v[50:53]
	v_mfma_f32_16x16x32_bf16 v[66:69], v[120:123], v[24:27], v[72:75]
	s_nop 2
	ds_read_b128 v[72:75], v49 offset:33792
	ds_read_b128 v[120:123], v49 offset:35840
	ds_read_b128 v[124:127], v49 offset:37888
	ds_read_b128 v[128:131], v49 offset:39936
	v_mfma_f32_16x16x32_bf16 v[76:79], v[112:115], v[24:27], v[76:79]
	ds_read_b128 v[112:115], v49 offset:41984
	ds_read_b128 v[132:135], v49 offset:44032
	ds_read_b128 v[136:139], v49 offset:46080
	ds_read_b128 v[140:143], v49 offset:48128
	v_mfma_f32_16x16x32_bf16 v[104:107], v[104:107], v[24:27], v[108:111]
	s_add_u32 s100, s10, 0x11600380
	s_addc_u32 s101, s11, 0
	s_mov_b32 m0, s12
	s_nop 0
	global_load_lds_dwordx4 v240, s[100:101]
	s_waitcnt lgkmcnt(0)
	v_mfma_f32_16x16x32_bf16 v[72:75], v[72:75], v[24:27], v[80:83]
	v_mfma_f32_16x16x32_bf16 v[80:83], v[120:123], v[24:27], v[84:87]
	v_mfma_f32_16x16x32_bf16 v[84:87], v[124:127], v[24:27], v[88:91]
	v_mfma_f32_16x16x32_bf16 v[88:91], v[128:131], v[24:27], v[92:95]
	v_mfma_f32_16x16x32_bf16 v[92:95], v[112:115], v[24:27], v[96:99]
	v_mfma_f32_16x16x32_bf16 v[96:99], v[132:135], v[24:27], v[100:103]
	s_nop 2
	ds_read_b128 v[100:103], v49 offset:30720
	ds_read_b128 v[108:111], v49 offset:28672
	ds_read_b128 v[112:115], v49 offset:26624
	ds_read_b128 v[120:123], v49 offset:24576
	v_mfma_f32_16x16x32_bf16 v[116:119], v[136:139], v[24:27], v[116:119]
	ds_read_b128 v[124:127], v49 offset:22528
	ds_read_b128 v[128:131], v49 offset:20480
	ds_read_b128 v[132:135], v49 offset:18432
	ds_read_b128 v[136:139], v49 offset:16384
	v_mfma_f32_16x16x32_bf16 v[24:27], v[140:143], v[24:27], v[28:31]
	s_add_u32 s100, s10, 0x11610380
	s_addc_u32 s101, s11, 0
	s_mov_b32 m0, s14
	s_nop 0
	global_load_lds_dwordx4 v240, s[100:101]
	s_waitcnt lgkmcnt(0)
	v_mfma_f32_16x16x32_bf16 v[28:31], v[136:139], v[20:23], v[32:35]
	v_mfma_f32_16x16x32_bf16 v[32:35], v[132:135], v[20:23], v[36:39]
	v_mfma_f32_16x16x32_bf16 v[36:39], v[128:131], v[20:23], v[40:43]
	v_mfma_f32_16x16x32_bf16 v[40:43], v[124:127], v[20:23], v[44:47]
	v_mfma_f32_16x16x32_bf16 v[44:47], v[120:123], v[20:23], v[50:53]
	v_mfma_f32_16x16x32_bf16 v[50:53], v[112:115], v[20:23], v[66:69]
	s_nop 2
	ds_read_b128 v[66:69], v49 offset:49152
	ds_read_b128 v[112:115], v49 offset:51200
	ds_read_b128 v[120:123], v49 offset:53248
	ds_read_b128 v[124:127], v49 offset:55296
	v_mfma_f32_16x16x32_bf16 v[76:79], v[108:111], v[20:23], v[76:79]
	ds_read_b128 v[108:111], v49 offset:57344
	ds_read_b128 v[128:131], v49 offset:59392
	ds_read_b128 v[132:135], v49 offset:61440
	ds_read_b128 v[136:139], v49 offset:63488
	v_mfma_f32_16x16x32_bf16 v[100:103], v[100:103], v[20:23], v[104:107]
	s_add_u32 s100, s10, 0x11620300
	s_addc_u32 s101, s11, 0
	s_mov_b32 m0, s15
	s_nop 0
	global_load_lds_dwordx4 v240, s[100:101]
	s_waitcnt lgkmcnt(0)
	v_mfma_f32_16x16x32_bf16 v[66:69], v[66:69], v[20:23], v[72:75]
	v_mfma_f32_16x16x32_bf16 v[72:75], v[112:115], v[20:23], v[80:83]
	v_mfma_f32_16x16x32_bf16 v[80:83], v[120:123], v[20:23], v[84:87]
	v_mfma_f32_16x16x32_bf16 v[84:87], v[124:127], v[20:23], v[88:91]
	v_mfma_f32_16x16x32_bf16 v[88:91], v[108:111], v[20:23], v[92:95]
	v_mfma_f32_16x16x32_bf16 v[92:95], v[128:131], v[20:23], v[96:99]
	s_nop 2
	ds_read_b128 v[96:99], v49 offset:31744
	ds_read_b128 v[104:107], v49 offset:29696
	ds_read_b128 v[108:111], v49 offset:27648
	ds_read_b128 v[112:115], v49 offset:25600
	v_mfma_f32_16x16x32_bf16 v[116:119], v[132:135], v[20:23], v[116:119]
	ds_read_b128 v[120:123], v49 offset:23552
	ds_read_b128 v[124:127], v49 offset:21504
	ds_read_b128 v[128:131], v49 offset:19456
	ds_read_b128 v[132:135], v49 offset:17408
	v_mfma_f32_16x16x32_bf16 v[20:23], v[136:139], v[20:23], v[24:27]
	s_add_u32 s100, s10, 0x11630300
	s_addc_u32 s101, s11, 0
	s_mov_b32 m0, s16
	s_nop 0
	global_load_lds_dwordx4 v240, s[100:101]
	s_waitcnt lgkmcnt(0)
	v_mfma_f32_16x16x32_bf16 v[24:27], v[132:135], v[16:19], v[28:31]
	v_mfma_f32_16x16x32_bf16 v[28:31], v[128:131], v[16:19], v[32:35]
	v_mfma_f32_16x16x32_bf16 v[32:35], v[124:127], v[16:19], v[36:39]
	v_mfma_f32_16x16x32_bf16 v[36:39], v[120:123], v[16:19], v[40:43]
	v_mfma_f32_16x16x32_bf16 v[40:43], v[112:115], v[16:19], v[44:47]
	v_mfma_f32_16x16x32_bf16 v[50:53], v[108:111], v[16:19], v[50:53]
	s_nop 1
	ds_read_b128 v[44:47], v49 offset:50176
	ds_read_b128 v[108:111], v49 offset:52224
	ds_read_b128 v[112:115], v49 offset:54272
	ds_read_b128 v[120:123], v49 offset:56320
	v_mfma_f32_16x16x32_bf16 v[76:79], v[104:107], v[16:19], v[76:79]
	ds_read_b128 v[104:107], v49 offset:58368
	ds_read_b128 v[124:127], v49 offset:60416
	ds_read_b128 v[128:131], v49 offset:62464
	ds_read_b128 v[132:135], v49 offset:64512
	v_mfma_f32_16x16x32_bf16 v[96:99], v[96:99], v[16:19], v[100:103]
	s_add_u32 s100, s10, 0x11620380
	s_addc_u32 s101, s11, 0
	s_mov_b32 m0, s17
	s_nop 0
	global_load_lds_dwordx4 v240, s[100:101]
	s_waitcnt lgkmcnt(0)
	v_mfma_f32_16x16x32_bf16 v[66:69], v[44:47], v[16:19], v[66:69]
	v_mfma_f32_16x16x32_bf16 v[72:75], v[108:111], v[16:19], v[72:75]
	v_mfma_f32_16x16x32_bf16 v[80:83], v[112:115], v[16:19], v[80:83]
	v_mfma_f32_16x16x32_bf16 v[84:87], v[120:123], v[16:19], v[84:87]
	v_mfma_f32_16x16x32_bf16 v[88:91], v[104:107], v[16:19], v[88:91]
	v_mfma_f32_16x16x32_bf16 v[92:95], v[124:127], v[16:19], v[92:95]
	v_mfma_f32_16x16x32_bf16 v[100:103], v[128:131], v[16:19], v[116:119]
	v_mfma_f32_16x16x32_bf16 v[16:19], v[132:135], v[16:19], v[20:23]
	s_add_u32 s100, s10, 0x11630380
	s_addc_u32 s101, s11, 0
	s_mov_b32 m0, s18
	s_nop 0
	global_load_lds_dwordx4 v240, s[100:101]
	s_waitcnt vmcnt(0)
	s_waitcnt vmcnt(0)
	s_barrier
	v_mov_b32_e32 v49, v48
	ds_read_b128 v[20:23], v49
	ds_read_b128 v[104:107], v49 offset:2048
	s_waitcnt lgkmcnt(0)
	v_mfma_f32_16x16x32_bf16 v[20:23], v[20:23], v[12:15], v[24:27]
	s_nop 2
	ds_read_b128 v[24:27], v49 offset:4096
	v_mfma_f32_16x16x32_bf16 v[28:31], v[104:107], v[12:15], v[28:31]
	ds_read_b128 v[104:107], v49 offset:6144
	s_waitcnt lgkmcnt(0)
	v_mfma_f32_16x16x32_bf16 v[24:27], v[24:27], v[12:15], v[32:35]
	s_nop 2
	ds_read_b128 v[32:35], v49 offset:8192
	v_mfma_f32_16x16x32_bf16 v[36:39], v[104:107], v[12:15], v[36:39]
	ds_read_b128 v[104:107], v49 offset:10240
	s_waitcnt lgkmcnt(0)
	v_mfma_f32_16x16x32_bf16 v[32:35], v[32:35], v[12:15], v[40:43]
	s_nop 2
	ds_read_b128 v[40:43], v49 offset:12288
	ds_read_b128 v[108:111], v49 offset:14336
	v_mfma_f32_16x16x32_bf16 v[50:53], v[104:107], v[12:15], v[50:53]
	ds_read_b128 v[104:107], v49 offset:32768
	ds_read_b128 v[112:115], v49 offset:34816
	ds_read_b128 v[116:119], v49 offset:36864
	ds_read_b128 v[120:123], v49 offset:38912
	s_waitcnt lgkmcnt(0)
	v_mfma_f32_16x16x32_bf16 v[40:43], v[40:43], v[12:15], v[76:79]
	s_nop 2
	ds_read_b128 v[76:79], v49 offset:40960
	ds_read_b128 v[124:127], v49 offset:43008
	ds_read_b128 v[128:131], v49 offset:45056
	ds_read_b128 v[132:135], v49 offset:47104
	v_mfma_f32_16x16x32_bf16 v[96:99], v[108:111], v[12:15], v[96:99]
	s_add_u32 s100, s10, 0x11e00000
	s_addc_u32 s101, s11, 0
	s_mov_b32 m0, s22
	s_nop 0
	global_load_lds_dwordx4 v241, s[100:101]
	v_mfma_f32_16x16x32_bf16 v[66:69], v[104:107], v[12:15], v[66:69]
	v_mfma_f32_16x16x32_bf16 v[72:75], v[112:115], v[12:15], v[72:75]
	v_mfma_f32_16x16x32_bf16 v[80:83], v[116:119], v[12:15], v[80:83]
	v_mfma_f32_16x16x32_bf16 v[84:87], v[120:123], v[12:15], v[84:87]
	s_waitcnt lgkmcnt(0)
	v_mfma_f32_16x16x32_bf16 v[76:79], v[76:79], v[12:15], v[88:91]
	v_mfma_f32_16x16x32_bf16 v[88:91], v[124:127], v[12:15], v[92:95]
	s_nop 2
	ds_read_b128 v[92:95], v49 offset:15360
	ds_read_b128 v[104:107], v49 offset:13312
	ds_read_b128 v[108:111], v49 offset:11264
	ds_read_b128 v[112:115], v49 offset:9216
	v_mfma_f32_16x16x32_bf16 v[100:103], v[128:131], v[12:15], v[100:103]
	ds_read_b128 v[116:119], v49 offset:7168
	ds_read_b128 v[120:123], v49 offset:5120
	ds_read_b128 v[124:127], v49 offset:3072
	ds_read_b128 v[128:131], v49 offset:1024
	v_mfma_f32_16x16x32_bf16 v[12:15], v[132:135], v[12:15], v[16:19]
	s_add_u32 s100, s10, 0x11e08000
	s_addc_u32 s101, s11, 0
	s_mov_b32 m0, s21
	s_nop 0
	global_load_lds_dwordx4 v241, s[100:101]
	s_waitcnt lgkmcnt(0)
	v_mfma_f32_16x16x32_bf16 v[16:19], v[128:131], v[8:11], v[20:23]
	v_mfma_f32_16x16x32_bf16 v[20:23], v[124:127], v[8:11], v[28:31]
	v_mfma_f32_16x16x32_bf16 v[24:27], v[120:123], v[8:11], v[24:27]
	v_mfma_f32_16x16x32_bf16 v[28:31], v[116:119], v[8:11], v[36:39]
	v_mfma_f32_16x16x32_bf16 v[32:35], v[112:115], v[8:11], v[32:35]
	v_mfma_f32_16x16x32_bf16 v[36:39], v[108:111], v[8:11], v[50:53]
	s_nop 2
	ds_read_b128 v[50:53], v49 offset:33792
	ds_read_b128 v[108:111], v49 offset:35840
	ds_read_b128 v[112:115], v49 offset:37888
	ds_read_b128 v[116:119], v49 offset:39936
	v_mfma_f32_16x16x32_bf16 v[40:43], v[104:107], v[8:11], v[40:43]
	ds_read_b128 v[104:107], v49 offset:41984
	ds_read_b128 v[120:123], v49 offset:44032
	ds_read_b128 v[124:127], v49 offset:46080
	ds_read_b128 v[128:131], v49 offset:48128
	v_mfma_f32_16x16x32_bf16 v[92:95], v[92:95], v[8:11], v[96:99]
	s_add_u32 s100, s10, 0x11e00080
	s_addc_u32 s101, s11, 0
	s_mov_b32 m0, s20
	s_nop 0
	global_load_lds_dwordx4 v241, s[100:101]
	s_waitcnt lgkmcnt(0)
	v_mfma_f32_16x16x32_bf16 v[50:53], v[50:53], v[8:11], v[66:69]
	v_mfma_f32_16x16x32_bf16 v[66:69], v[108:111], v[8:11], v[72:75]
	v_mfma_f32_16x16x32_bf16 v[72:75], v[112:115], v[8:11], v[80:83]
	v_mfma_f32_16x16x32_bf16 v[80:83], v[116:119], v[8:11], v[84:87]
	v_mfma_f32_16x16x32_bf16 v[76:79], v[104:107], v[8:11], v[76:79]
	v_mfma_f32_16x16x32_bf16 v[84:87], v[120:123], v[8:11], v[88:91]
	s_nop 2
	ds_read_b128 v[88:91], v49 offset:30720
	ds_read_b128 v[96:99], v49 offset:28672
	ds_read_b128 v[104:107], v49 offset:26624
	ds_read_b128 v[108:111], v49 offset:24576
	v_mfma_f32_16x16x32_bf16 v[100:103], v[124:127], v[8:11], v[100:103]
	ds_read_b128 v[112:115], v49 offset:22528
	ds_read_b128 v[116:119], v49 offset:20480
	ds_read_b128 v[120:123], v49 offset:18432
	ds_read_b128 v[124:127], v49 offset:16384
	v_mfma_f32_16x16x32_bf16 v[8:11], v[128:131], v[8:11], v[12:15]
	s_add_u32 s100, s10, 0x11e08080
	s_addc_u32 s101, s11, 0
	s_mov_b32 m0, s23
	s_nop 0
	global_load_lds_dwordx4 v241, s[100:101]
	s_waitcnt lgkmcnt(0)
	v_mfma_f32_16x16x32_bf16 v[12:15], v[124:127], v[4:7], v[16:19]
	v_mfma_f32_16x16x32_bf16 v[16:19], v[120:123], v[4:7], v[20:23]
	v_mfma_f32_16x16x32_bf16 v[20:23], v[116:119], v[4:7], v[24:27]
	v_mfma_f32_16x16x32_bf16 v[24:27], v[112:115], v[4:7], v[28:31]
	v_mfma_f32_16x16x32_bf16 v[28:31], v[108:111], v[4:7], v[32:35]
	v_mfma_f32_16x16x32_bf16 v[32:35], v[104:107], v[4:7], v[36:39]
	s_nop 2
	ds_read_b128 v[36:39], v49 offset:49152
	ds_read_b128 v[104:107], v49 offset:51200
	ds_read_b128 v[108:111], v49 offset:53248
	ds_read_b128 v[112:115], v49 offset:55296
	v_mfma_f32_16x16x32_bf16 v[96:99], v[96:99], v[4:7], v[40:43]
	s_nop 2
	ds_read_b128 v[40:43], v49 offset:57344
	ds_read_b128 v[116:119], v49 offset:59392
	ds_read_b128 v[120:123], v49 offset:61440
	ds_read_b128 v[124:127], v49 offset:63488
	v_mfma_f32_16x16x32_bf16 v[88:91], v[88:91], v[4:7], v[92:95]
	s_add_u32 s100, s10, 0x11e10000
	s_addc_u32 s101, s11, 0
	s_mov_b32 m0, s24
	s_nop 0
	global_load_lds_dwordx4 v241, s[100:101]
	s_waitcnt lgkmcnt(0)
	v_mfma_f32_16x16x32_bf16 v[50:53], v[36:39], v[4:7], v[50:53]
	v_mfma_f32_16x16x32_bf16 v[66:69], v[104:107], v[4:7], v[66:69]
	v_mfma_f32_16x16x32_bf16 v[72:75], v[108:111], v[4:7], v[72:75]
	v_mfma_f32_16x16x32_bf16 v[80:83], v[112:115], v[4:7], v[80:83]
	v_mfma_f32_16x16x32_bf16 v[76:79], v[40:43], v[4:7], v[76:79]
	ds_read_b128 v[92:95], v49 offset:31744
	ds_read_b128 v[36:39], v49 offset:29696
	ds_read_b128 v[40:43], v49 offset:27648
	ds_read_b128 v[104:107], v49 offset:25600
	v_mfma_f32_16x16x32_bf16 v[84:87], v[116:119], v[4:7], v[84:87]
	v_mfma_f32_16x16x32_bf16 v[100:103], v[120:123], v[4:7], v[100:103]
	ds_read_b128 v[108:111], v49 offset:23552
	ds_read_b128 v[112:115], v49 offset:21504
	ds_read_b128 v[116:119], v49 offset:19456
	ds_read_b128 v[120:123], v49 offset:17408
	v_mfma_f32_16x16x32_bf16 v[124:127], v[124:127], v[4:7], v[8:11]
	s_add_u32 s100, s10, 0x11e18000
	s_addc_u32 s101, s11, 0
	s_mov_b32 m0, s25
	s_nop 0
	global_load_lds_dwordx4 v241, s[100:101]
	s_waitcnt lgkmcnt(0)
	v_mfma_f32_16x16x32_bf16 v[120:123], v[120:123], v[0:3], v[12:15]
	v_mfma_f32_16x16x32_bf16 v[116:119], v[116:119], v[0:3], v[16:19]
	ds_read_b128 v[4:7], v49 offset:50176
	ds_read_b128 v[8:11], v49 offset:52224
	ds_read_b128 v[12:15], v49 offset:54272
	ds_read_b128 v[16:19], v49 offset:56320
	v_mfma_f32_16x16x32_bf16 v[36:39], v[36:39], v[0:3], v[96:99]
	s_nop 2
	ds_read_b128 v[96:99], v49 offset:58368
	ds_read_b128 v[128:131], v49 offset:60416
	ds_read_b128 v[132:135], v49 offset:62464
	ds_read_b128 v[136:139], v49 offset:64512
	v_mfma_f32_16x16x32_bf16 v[112:115], v[112:115], v[0:3], v[20:23]
	v_mfma_f32_16x16x32_bf16 v[108:111], v[108:111], v[0:3], v[24:27]
	v_mfma_f32_16x16x32_bf16 v[104:107], v[104:107], v[0:3], v[28:31]
	v_mfma_f32_16x16x32_bf16 v[40:43], v[40:43], v[0:3], v[32:35]
	v_mfma_f32_16x16x32_bf16 v[32:35], v[92:95], v[0:3], v[88:91]
	s_add_u32 s100, s10, 0x11e10080
	s_addc_u32 s101, s11, 0
	s_mov_b32 m0, s26
	s_nop 0
	global_load_lds_dwordx4 v241, s[100:101]
	s_waitcnt lgkmcnt(0)
	v_mfma_f32_16x16x32_bf16 v[28:31], v[4:7], v[0:3], v[50:53]
	v_mfma_f32_16x16x32_bf16 v[24:27], v[8:11], v[0:3], v[66:69]
	v_mfma_f32_16x16x32_bf16 v[20:23], v[12:15], v[0:3], v[72:75]
	v_mfma_f32_16x16x32_bf16 v[16:19], v[16:19], v[0:3], v[80:83]
	v_mfma_f32_16x16x32_bf16 v[12:15], v[96:99], v[0:3], v[76:79]
	v_mfma_f32_16x16x32_bf16 v[8:11], v[128:131], v[0:3], v[84:87]
	v_mfma_f32_16x16x32_bf16 v[4:7], v[132:135], v[0:3], v[100:103]
	v_mfma_f32_16x16x32_bf16 v[0:3], v[136:139], v[0:3], v[124:127]
	s_add_u32 s100, s10, 0x11e18080
	s_addc_u32 s101, s11, 0
	s_mov_b32 m0, s27
	s_nop 0
	global_load_lds_dwordx4 v241, s[100:101]
	v_max_f32_e32 v49, v123, v123
	v_max_f32_e32 v50, v122, v122
	v_max_f32_e32 v49, v50, v49
	v_max_f32_e32 v50, v117, v117
	v_max_f32_e32 v51, v116, v116
	v_max_f32_e32 v50, v51, v50
	v_max_f32_e32 v51, v119, v119
	v_max_f32_e32 v52, v118, v118
	v_max3_f32 v49, v120, v121, v49
	v_max_f32_e32 v51, v52, v51
	v_max3_f32 v49, v49, v50, v51
	v_max_f32_e32 v50, v113, v113
	v_max_f32_e32 v51, v112, v112
	v_max_f32_e32 v50, v51, v50
	v_max_f32_e32 v51, v115, v115
	v_max_f32_e32 v52, v114, v114
	v_max_f32_e32 v51, v52, v51
	v_max3_f32 v49, v49, v50, v51
	v_max_f32_e32 v50, v109, v109
	v_max_f32_e32 v51, v108, v108
	v_max_f32_e32 v50, v51, v50
	v_max_f32_e32 v51, v111, v111
	v_max_f32_e32 v52, v110, v110
	v_max_f32_e32 v51, v52, v51
	v_max3_f32 v49, v49, v50, v51
	v_max_f32_e32 v50, v105, v105
	v_max_f32_e32 v51, v104, v104
	v_max_f32_e32 v50, v51, v50
	v_max_f32_e32 v51, v107, v107
	v_max_f32_e32 v52, v106, v106
	v_max_f32_e32 v51, v52, v51
	v_max3_f32 v49, v49, v50, v51
	v_max_f32_e32 v50, v41, v41
	v_max_f32_e32 v51, v40, v40
	v_max_f32_e32 v50, v51, v50
	v_max_f32_e32 v51, v43, v43
	v_max_f32_e32 v52, v42, v42
	v_max_f32_e32 v51, v52, v51
	v_max3_f32 v49, v49, v50, v51
	v_max_f32_e32 v50, v37, v37
	v_max_f32_e32 v51, v36, v36
	v_max_f32_e32 v50, v51, v50
	v_max_f32_e32 v51, v39, v39
	v_max_f32_e32 v52, v38, v38
	v_max_f32_e32 v51, v52, v51
	v_max3_f32 v49, v49, v50, v51
	v_max_f32_e32 v50, v33, v33
	v_max_f32_e32 v51, v32, v32
	v_max_f32_e32 v50, v51, v50
	v_max_f32_e32 v51, v35, v35
	v_max_f32_e32 v52, v34, v34
	v_max_f32_e32 v51, v52, v51
	v_max3_f32 v49, v49, v50, v51
	v_max_f32_e32 v50, v29, v29
	v_max_f32_e32 v51, v28, v28
	v_max_f32_e32 v50, v51, v50
	v_max_f32_e32 v51, v31, v31
	v_max_f32_e32 v52, v30, v30
	v_max_f32_e32 v51, v52, v51
	v_max3_f32 v49, v49, v50, v51
	v_max_f32_e32 v50, v25, v25
	v_max_f32_e32 v51, v24, v24
	v_max_f32_e32 v50, v51, v50
	v_max_f32_e32 v51, v27, v27
	v_max_f32_e32 v52, v26, v26
	v_max_f32_e32 v51, v52, v51
	v_max3_f32 v49, v49, v50, v51
	v_max_f32_e32 v50, v21, v21
	v_max_f32_e32 v51, v20, v20
	v_max_f32_e32 v50, v51, v50
	v_max_f32_e32 v51, v23, v23
	v_max_f32_e32 v52, v22, v22
	v_max_f32_e32 v51, v52, v51
	v_max3_f32 v49, v49, v50, v51
	v_max_f32_e32 v50, v17, v17
	v_max_f32_e32 v51, v16, v16
	v_max_f32_e32 v50, v51, v50
	v_max_f32_e32 v51, v19, v19
	v_max_f32_e32 v52, v18, v18
	v_max_f32_e32 v51, v52, v51
	v_max3_f32 v49, v49, v50, v51
	v_max_f32_e32 v50, v13, v13
	v_max_f32_e32 v51, v12, v12
	v_max_f32_e32 v50, v51, v50
	v_max_f32_e32 v51, v15, v15
	v_max_f32_e32 v52, v14, v14
	v_max_f32_e32 v51, v52, v51
	v_max3_f32 v49, v49, v50, v51
	v_max_f32_e32 v50, v9, v9
	v_max_f32_e32 v51, v8, v8
	v_max_f32_e32 v50, v51, v50
	v_max_f32_e32 v51, v11, v11
	v_max_f32_e32 v52, v10, v10
	v_max_f32_e32 v51, v52, v51
	v_max3_f32 v49, v49, v50, v51
	v_max_f32_e32 v50, v5, v5
	v_max_f32_e32 v51, v4, v4
	v_max_f32_e32 v50, v51, v50
	v_max_f32_e32 v51, v7, v7
	v_max_f32_e32 v52, v6, v6
	v_max_f32_e32 v51, v52, v51
	v_max3_f32 v49, v49, v50, v51
	v_max_f32_e32 v50, v1, v1
	v_max_f32_e32 v51, v0, v0
	v_max_f32_e32 v50, v51, v50
	v_max_f32_e32 v51, v3, v3
	v_max_f32_e32 v52, v2, v2
	v_max_f32_e32 v51, v52, v51
	v_max3_f32 v49, v49, v50, v51
	v_mbcnt_lo_u32_b32 v50, -1, 0
	v_mbcnt_hi_u32_b32 v50, -1, v50
	v_and_b32_e32 v52, 64, v50
	v_xor_b32_e32 v51, 16, v50
	v_add_u32_e32 v52, 64, v52
	v_cmp_lt_i32_e32 vcc, v51, v52
	s_nop 1
	v_cndmask_b32_e32 v51, v50, v51, vcc
	v_lshlrev_b32_e32 v51, 2, v51
	v_mov_b32_e32 v53, v49
	s_nop 1
	v_permlane16_swap_b32_e32 v53, v49
	s_waitcnt lgkmcnt(0)
	v_max_f32_e32 v53, v53, v53
	v_max_f32_e32 v49, v49, v53
	v_xor_b32_e32 v53, 32, v50
	v_cmp_lt_i32_e32 vcc, v53, v52
	s_nop 1
	v_cndmask_b32_e32 v50, v50, v53, vcc
	v_lshlrev_b32_e32 v50, 2, v50
	v_mov_b32_e32 v52, v49
	s_nop 1
	v_permlane32_swap_b32_e32 v52, v49
	s_waitcnt lgkmcnt(0)
	v_max_f32_e32 v52, v52, v52
	v_max_f32_e32 v49, v49, v52
	v_sub_f32_e32 v52, v120, v49
	v_exp_f32_e32 v52, v52
	v_sub_f32_e32 v53, v121, v49
	v_exp_f32_e32 v53, v53
	v_sub_f32_e32 v54, v122, v49
	v_exp_f32_e32 v54, v54
	v_sub_f32_e32 v55, v123, v49
	v_exp_f32_e32 v55, v55
	v_sub_f32_e32 v59, v116, v49
	v_add_f32_e32 v57, 0, v52
	v_exp_f32_e32 v59, v59
	v_sub_f32_e32 v62, v117, v49
	v_add_f32_e32 v57, v53, v57
	v_exp_f32_e32 v62, v62
	v_sub_f32_e32 v63, v118, v49
	v_add_f32_e32 v57, v54, v57
	v_exp_f32_e32 v63, v63
	v_sub_f32_e32 v64, v119, v49
	v_add_f32_e32 v57, v55, v57
	v_exp_f32_e32 v64, v64
	v_sub_f32_e32 v66, v112, v49
	v_add_f32_e32 v57, v59, v57
	v_exp_f32_e32 v66, v66
	v_sub_f32_e32 v67, v113, v49
	v_add_f32_e32 v57, v62, v57
	v_exp_f32_e32 v67, v67
	v_sub_f32_e32 v68, v114, v49
	v_add_f32_e32 v57, v63, v57
	v_exp_f32_e32 v68, v68
	v_sub_f32_e32 v69, v115, v49
	v_add_f32_e32 v57, v64, v57
	v_exp_f32_e32 v69, v69
	v_sub_f32_e32 v71, v108, v49
	v_add_f32_e32 v57, v66, v57
	v_exp_f32_e32 v71, v71
	v_sub_f32_e32 v72, v109, v49
	v_add_f32_e32 v57, v67, v57
	v_exp_f32_e32 v72, v72
	v_sub_f32_e32 v73, v110, v49
	v_add_f32_e32 v57, v68, v57
	v_exp_f32_e32 v73, v73
	v_sub_f32_e32 v74, v111, v49
	v_add_f32_e32 v57, v69, v57
	v_exp_f32_e32 v74, v74
	v_sub_f32_e32 v75, v104, v49
	v_add_f32_e32 v57, v71, v57
	v_exp_f32_e32 v75, v75
	v_sub_f32_e32 v76, v105, v49
	v_add_f32_e32 v57, v72, v57
	v_exp_f32_e32 v76, v76
	v_sub_f32_e32 v77, v106, v49
	v_add_f32_e32 v57, v73, v57
	v_exp_f32_e32 v77, v77
	v_sub_f32_e32 v78, v107, v49
	v_add_f32_e32 v57, v74, v57
	v_exp_f32_e32 v78, v78
	v_sub_f32_e32 v40, v40, v49
	v_add_f32_e32 v57, v75, v57
	v_exp_f32_e32 v40, v40
	v_sub_f32_e32 v41, v41, v49
	v_add_f32_e32 v57, v76, v57
	v_exp_f32_e32 v41, v41
	v_sub_f32_e32 v42, v42, v49
	v_add_f32_e32 v57, v77, v57
	v_exp_f32_e32 v42, v42
	v_sub_f32_e32 v43, v43, v49
	v_add_f32_e32 v57, v78, v57
	v_exp_f32_e32 v43, v43
	v_sub_f32_e32 v36, v36, v49
	v_add_f32_e32 v57, v40, v57
	v_exp_f32_e32 v36, v36
	v_sub_f32_e32 v37, v37, v49
	v_add_f32_e32 v57, v41, v57
	v_exp_f32_e32 v37, v37
	v_sub_f32_e32 v38, v38, v49
	v_add_f32_e32 v57, v42, v57
	v_exp_f32_e32 v38, v38
	v_sub_f32_e32 v39, v39, v49
	v_add_f32_e32 v57, v43, v57
	v_exp_f32_e32 v39, v39
	v_sub_f32_e32 v32, v32, v49
	v_add_f32_e32 v57, v36, v57
	v_exp_f32_e32 v32, v32
	v_sub_f32_e32 v33, v33, v49
	v_add_f32_e32 v57, v37, v57
	v_exp_f32_e32 v33, v33
	v_sub_f32_e32 v34, v34, v49
	v_add_f32_e32 v57, v38, v57
	v_exp_f32_e32 v34, v34
	v_sub_f32_e32 v35, v35, v49
	v_add_f32_e32 v57, v39, v57
	v_exp_f32_e32 v35, v35
	v_sub_f32_e32 v28, v28, v49
	v_add_f32_e32 v57, v32, v57
	v_exp_f32_e32 v79, v28
	v_sub_f32_e32 v28, v29, v49
	v_add_f32_e32 v57, v33, v57
	v_exp_f32_e32 v80, v28
	v_sub_f32_e32 v28, v30, v49
	v_add_f32_e32 v57, v34, v57
	v_exp_f32_e32 v81, v28
	v_sub_f32_e32 v28, v31, v49
	v_add_f32_e32 v57, v35, v57
	v_exp_f32_e32 v82, v28
	v_sub_f32_e32 v24, v24, v49
	v_add_f32_e32 v28, v79, v57
	v_exp_f32_e32 v57, v24
	v_sub_f32_e32 v24, v25, v49
	v_add_f32_e32 v28, v80, v28
	v_exp_f32_e32 v83, v24
	v_sub_f32_e32 v24, v26, v49
	v_add_f32_e32 v28, v81, v28
	v_exp_f32_e32 v84, v24
	v_sub_f32_e32 v24, v27, v49
	v_add_f32_e32 v28, v82, v28
	v_exp_f32_e32 v85, v24
	v_sub_f32_e32 v20, v20, v49
	v_add_f32_e32 v24, v57, v28
	v_exp_f32_e32 v86, v20
	v_sub_f32_e32 v20, v21, v49
	v_add_f32_e32 v24, v83, v24
	v_exp_f32_e32 v87, v20
	v_sub_f32_e32 v20, v22, v49
	v_add_f32_e32 v24, v84, v24
	v_exp_f32_e32 v88, v20
	v_sub_f32_e32 v20, v23, v49
	v_add_f32_e32 v24, v85, v24
	v_exp_f32_e32 v89, v20
	v_sub_f32_e32 v16, v16, v49
	v_add_f32_e32 v20, v86, v24
	v_exp_f32_e32 v90, v16
	v_sub_f32_e32 v16, v17, v49
	v_add_f32_e32 v20, v87, v20
	v_exp_f32_e32 v91, v16
	v_sub_f32_e32 v16, v18, v49
	v_add_f32_e32 v20, v88, v20
	v_exp_f32_e32 v92, v16
	v_sub_f32_e32 v16, v19, v49
	v_add_f32_e32 v20, v89, v20
	v_exp_f32_e32 v93, v16
	v_sub_f32_e32 v12, v12, v49
	v_add_f32_e32 v16, v90, v20
	v_exp_f32_e32 v94, v12
	v_sub_f32_e32 v12, v13, v49
	v_add_f32_e32 v16, v91, v16
	v_exp_f32_e32 v95, v12
	v_sub_f32_e32 v12, v14, v49
	v_add_f32_e32 v16, v92, v16
	v_exp_f32_e32 v96, v12
	v_sub_f32_e32 v12, v15, v49
	v_add_f32_e32 v16, v93, v16
	v_exp_f32_e32 v97, v12
	v_sub_f32_e32 v8, v8, v49
	v_add_f32_e32 v12, v94, v16
	v_exp_f32_e32 v98, v8
	v_sub_f32_e32 v8, v9, v49
	v_add_f32_e32 v12, v95, v12
	v_exp_f32_e32 v99, v8
	v_sub_f32_e32 v8, v10, v49
	v_add_f32_e32 v12, v96, v12
	v_exp_f32_e32 v100, v8
	v_sub_f32_e32 v8, v11, v49
	v_add_f32_e32 v12, v97, v12
	v_exp_f32_e32 v11, v8
	v_sub_f32_e32 v4, v4, v49
	v_add_f32_e32 v8, v98, v12
	v_exp_f32_e32 v101, v4
	v_sub_f32_e32 v4, v5, v49
	v_add_f32_e32 v8, v99, v8
	v_exp_f32_e32 v102, v4
	v_sub_f32_e32 v4, v6, v49
	v_add_f32_e32 v8, v100, v8
	v_exp_f32_e32 v103, v4
	v_sub_f32_e32 v4, v7, v49
	v_add_f32_e32 v8, v11, v8
	v_exp_f32_e32 v104, v4
	v_sub_f32_e32 v0, v0, v49
	v_add_f32_e32 v4, v101, v8
	v_exp_f32_e32 v105, v0
	v_sub_f32_e32 v0, v1, v49
	v_add_f32_e32 v4, v102, v4
	v_exp_f32_e32 v106, v0
	v_sub_f32_e32 v0, v2, v49
	v_add_f32_e32 v4, v103, v4
	v_exp_f32_e32 v107, v0
	v_sub_f32_e32 v0, v3, v49
	v_add_f32_e32 v4, v104, v4
	v_exp_f32_e32 v3, v0
	v_add_f32_e32 v0, v105, v4
	v_add_f32_e32 v0, v106, v0
	v_add_f32_e32 v0, v107, v0
	v_add_f32_e32 v0, v3, v0
	v_mov_b32_e32 v1, v0
	s_nop 1
	v_permlane16_swap_b32_e32 v1, v0
	v_cvt_pk_bf16_f32 v28, v52, v53
	v_cvt_pk_bf16_f32 v29, v54, v55
	v_cvt_pk_bf16_f32 v30, v59, v62
	v_cvt_pk_bf16_f32 v31, v63, v64
	s_waitcnt lgkmcnt(0)
	v_add_f32_e32 v0, v0, v1
	v_mov_b32_e32 v1, v0
	s_nop 1
	v_permlane32_swap_b32_e32 v1, v0
	v_cvt_pk_bf16_f32 v20, v66, v67
	v_cvt_pk_bf16_f32 v21, v68, v69
	v_cvt_pk_bf16_f32 v22, v71, v72
	v_cvt_pk_bf16_f32 v23, v73, v74
	s_waitcnt lgkmcnt(0)
	v_add_f32_e32 v49, v0, v1
	v_cvt_pk_bf16_f32 v24, v75, v76
	v_cvt_pk_bf16_f32 v25, v77, v78
	v_cvt_pk_bf16_f32 v26, v40, v41
	v_cvt_pk_bf16_f32 v27, v42, v43
	v_cvt_pk_bf16_f32 v16, v36, v37
	v_cvt_pk_bf16_f32 v17, v38, v39
	v_cvt_pk_bf16_f32 v18, v32, v33
	v_cvt_pk_bf16_f32 v19, v34, v35
	v_cvt_pk_bf16_f32 v12, v79, v80
	v_cvt_pk_bf16_f32 v13, v81, v82
	v_cvt_pk_bf16_f32 v14, v57, v83
	v_cvt_pk_bf16_f32 v15, v84, v85
	v_cvt_pk_bf16_f32 v4, v86, v87
	v_cvt_pk_bf16_f32 v5, v88, v89
	v_cvt_pk_bf16_f32 v6, v90, v91
	v_cvt_pk_bf16_f32 v7, v92, v93
	v_cvt_pk_bf16_f32 v8, v94, v95
	v_cvt_pk_bf16_f32 v9, v96, v97
	v_cvt_pk_bf16_f32 v10, v98, v99
	v_cvt_pk_bf16_f32 v11, v100, v11
	v_cvt_pk_bf16_f32 v0, v101, v102
	v_cvt_pk_bf16_f32 v1, v103, v104
	v_cvt_pk_bf16_f32 v2, v105, v106
	v_cvt_pk_bf16_f32 v3, v107, v3
	s_waitcnt vmcnt(0)
	s_waitcnt vmcnt(0)
	s_barrier
	v_mov_b32_e32 v64, v65
	v_div_scale_f32 v62, vcc, 1.0, v49, 1.0
	v_lshlrev_b32_e32 v54, 2, v70
	v_ashrrev_i32_e32 v55, 31, v54
	ds_read_b128 v[32:35], v64
	ds_read_b128 v[36:39], v64 offset:2048
	v_div_scale_f32 v57, s[0:1], v49, v49, 1.0
	v_rcp_f32_e32 v59, v57
	s_waitcnt lgkmcnt(0)
	v_mfma_f32_16x16x32_bf16 v[44:47], v[32:35], v[28:31], 0
	v_fma_f32 v40, -v57, v59, 1.0
	v_fmac_f32_e32 v59, v40, v59
	ds_read_b128 v[40:43], v64 offset:4096
	ds_read_b128 v[32:35], v64 offset:6144
	v_mul_f32_e32 v63, v62, v59
	v_fma_f32 v66, -v57, v63, v62
	v_fmac_f32_e32 v63, v66, v59
	v_mfma_f32_16x16x32_bf16 v[50:53], v[36:39], v[28:31], 0
	v_fma_f32 v36, -v57, v63, v62
	ds_read_b128 v[66:69], v64 offset:8192
	ds_read_b128 v[70:73], v64 offset:10240
	v_div_fmas_f32 v36, v36, v59, v63
	s_waitcnt lgkmcnt(0)
	v_mfma_f32_16x16x32_bf16 v[74:77], v[32:35], v[28:31], 0
	v_lshl_add_u64 v[34:35], v[54:55], 1, v[60:61]
	ds_read_b128 v[60:63], v64 offset:12288
	ds_read_b128 v[78:81], v64 offset:14336
	ds_read_b128 v[82:85], v64 offset:32768
	ds_read_b128 v[86:89], v64 offset:34816
	ds_read_b128 v[90:93], v64 offset:36864
	ds_read_b128 v[94:97], v64 offset:38912
	ds_read_b128 v[98:101], v64 offset:40960
	ds_read_b128 v[102:105], v64 offset:43008
	ds_read_b128 v[106:109], v64 offset:45056
	ds_read_b128 v[110:113], v64 offset:47104
	s_mov_b64 s[0:1], 0x1000000
	v_mfma_f32_16x16x32_bf16 v[38:41], v[40:43], v[28:31], 0
	v_div_fixup_f32 v36, v36, v49, 1.0
	v_lshl_add_u64 v[32:33], v[34:35], 0, s[0:1]
	v_mfma_f32_16x16x32_bf16 v[66:69], v[66:69], v[28:31], 0
	v_mfma_f32_16x16x32_bf16 v[70:73], v[70:73], v[28:31], 0
	s_waitcnt lgkmcnt(0)
	v_mfma_f32_16x16x32_bf16 v[60:63], v[60:63], v[28:31], 0
	v_mfma_f32_16x16x32_bf16 v[78:81], v[78:81], v[28:31], 0
	s_add_u32 s100, s10, 0x11e00100
	s_addc_u32 s101, s11, 0
	s_mov_b32 m0, s19
	s_nop 0
	global_load_lds_dwordx4 v241, s[100:101]
	ds_read_b128 v[114:117], v64 offset:30720
	ds_read_b128 v[118:121], v64 offset:28672
	ds_read_b128 v[122:125], v64 offset:26624
	ds_read_b128 v[126:129], v64 offset:24576
	ds_read_b128 v[130:133], v64 offset:22528
	ds_read_b128 v[134:137], v64 offset:20480
	ds_read_b128 v[138:141], v64 offset:18432
	ds_read_b128 v[142:145], v64 offset:16384
	v_mfma_f32_16x16x32_bf16 v[82:85], v[82:85], v[28:31], 0
	v_mfma_f32_16x16x32_bf16 v[86:89], v[86:89], v[28:31], 0
	v_mfma_f32_16x16x32_bf16 v[90:93], v[90:93], v[28:31], 0
	v_mfma_f32_16x16x32_bf16 v[94:97], v[94:97], v[28:31], 0
	v_mfma_f32_16x16x32_bf16 v[98:101], v[98:101], v[28:31], 0
	v_mfma_f32_16x16x32_bf16 v[102:105], v[102:105], v[28:31], 0
	v_mfma_f32_16x16x32_bf16 v[106:109], v[106:109], v[28:31], 0
	v_mfma_f32_16x16x32_bf16 v[110:113], v[110:113], v[28:31], 0
	s_add_u32 s100, s10, 0x11e08100
	s_addc_u32 s101, s11, 0
	s_mov_b32 m0, s13
	s_nop 0
	global_load_lds_dwordx4 v241, s[100:101]
	s_waitcnt lgkmcnt(0)
	v_mfma_f32_16x16x32_bf16 v[42:45], v[142:145], v[24:27], v[44:47]
	v_mfma_f32_16x16x32_bf16 v[50:53], v[138:141], v[24:27], v[50:53]
	v_mfma_f32_16x16x32_bf16 v[38:41], v[134:137], v[24:27], v[38:41]
	v_mfma_f32_16x16x32_bf16 v[74:77], v[130:133], v[24:27], v[74:77]
	v_mfma_f32_16x16x32_bf16 v[66:69], v[126:129], v[24:27], v[66:69]
	v_mfma_f32_16x16x32_bf16 v[70:73], v[122:125], v[24:27], v[70:73]
	ds_read_b128 v[122:125], v64 offset:49152
	ds_read_b128 v[126:129], v64 offset:51200
	ds_read_b128 v[130:133], v64 offset:53248
	ds_read_b128 v[134:137], v64 offset:55296
	v_mfma_f32_16x16x32_bf16 v[60:63], v[118:121], v[24:27], v[60:63]
	ds_read_b128 v[118:121], v64 offset:57344
	ds_read_b128 v[138:141], v64 offset:59392
	ds_read_b128 v[142:145], v64 offset:61440
	ds_read_b128 v[146:149], v64 offset:63488
	v_mfma_f32_16x16x32_bf16 v[78:81], v[114:117], v[24:27], v[78:81]
	s_add_u32 s100, s10, 0x11e00180
	s_addc_u32 s101, s11, 0
	s_mov_b32 m0, s12
	s_nop 0
	global_load_lds_dwordx4 v241, s[100:101]
	s_waitcnt lgkmcnt(0)
	v_mfma_f32_16x16x32_bf16 v[82:85], v[122:125], v[24:27], v[82:85]
	v_mfma_f32_16x16x32_bf16 v[86:89], v[126:129], v[24:27], v[86:89]
	v_mfma_f32_16x16x32_bf16 v[90:93], v[130:133], v[24:27], v[90:93]
	v_mfma_f32_16x16x32_bf16 v[94:97], v[134:137], v[24:27], v[94:97]
	v_mfma_f32_16x16x32_bf16 v[98:101], v[118:121], v[24:27], v[98:101]
	ds_read_b128 v[114:117], v64 offset:15360
	ds_read_b128 v[118:121], v64 offset:13312
	ds_read_b128 v[122:125], v64 offset:11264
	ds_read_b128 v[126:129], v64 offset:9216
	v_mfma_f32_16x16x32_bf16 v[102:105], v[138:141], v[24:27], v[102:105]
	v_mfma_f32_16x16x32_bf16 v[106:109], v[142:145], v[24:27], v[106:109]
	ds_read_b128 v[130:133], v64 offset:7168
	ds_read_b128 v[134:137], v64 offset:5120
	ds_read_b128 v[138:141], v64 offset:3072
	ds_read_b128 v[142:145], v64 offset:1024
	v_mfma_f32_16x16x32_bf16 v[110:113], v[146:149], v[24:27], v[110:113]
	s_add_u32 s100, s10, 0x11e08180
	s_addc_u32 s101, s11, 0
	s_mov_b32 m0, s14
	s_nop 0
	global_load_lds_dwordx4 v241, s[100:101]
	s_waitcnt lgkmcnt(0)
	v_mfma_f32_16x16x32_bf16 v[42:45], v[142:145], v[20:23], v[42:45]
	v_mfma_f32_16x16x32_bf16 v[50:53], v[138:141], v[20:23], v[50:53]
	v_mfma_f32_16x16x32_bf16 v[38:41], v[134:137], v[20:23], v[38:41]
	v_mfma_f32_16x16x32_bf16 v[74:77], v[130:133], v[20:23], v[74:77]
	v_mfma_f32_16x16x32_bf16 v[66:69], v[126:129], v[20:23], v[66:69]
	v_mfma_f32_16x16x32_bf16 v[70:73], v[122:125], v[20:23], v[70:73]
	ds_read_b128 v[122:125], v64 offset:33792
	ds_read_b128 v[126:129], v64 offset:35840
	ds_read_b128 v[130:133], v64 offset:37888
	ds_read_b128 v[134:137], v64 offset:39936
	v_mfma_f32_16x16x32_bf16 v[60:63], v[118:121], v[20:23], v[60:63]
	ds_read_b128 v[118:121], v64 offset:41984
	ds_read_b128 v[138:141], v64 offset:44032
	ds_read_b128 v[142:145], v64 offset:46080
	ds_read_b128 v[146:149], v64 offset:48128
	v_mfma_f32_16x16x32_bf16 v[78:81], v[114:117], v[20:23], v[78:81]
	s_add_u32 s100, s10, 0x11e10100
	s_addc_u32 s101, s11, 0
	s_mov_b32 m0, s15
	s_nop 0
	global_load_lds_dwordx4 v241, s[100:101]
	s_waitcnt lgkmcnt(0)
	v_mfma_f32_16x16x32_bf16 v[82:85], v[122:125], v[20:23], v[82:85]
	v_mfma_f32_16x16x32_bf16 v[86:89], v[126:129], v[20:23], v[86:89]
	v_mfma_f32_16x16x32_bf16 v[90:93], v[130:133], v[20:23], v[90:93]
	v_mfma_f32_16x16x32_bf16 v[94:97], v[134:137], v[20:23], v[94:97]
	v_mfma_f32_16x16x32_bf16 v[98:101], v[118:121], v[20:23], v[98:101]
	ds_read_b128 v[114:117], v64 offset:31744
	ds_read_b128 v[118:121], v64 offset:29696
	ds_read_b128 v[122:125], v64 offset:27648
	ds_read_b128 v[126:129], v64 offset:25600
	v_mfma_f32_16x16x32_bf16 v[102:105], v[138:141], v[20:23], v[102:105]
	v_mfma_f32_16x16x32_bf16 v[106:109], v[142:145], v[20:23], v[106:109]
	ds_read_b128 v[130:133], v64 offset:23552
	ds_read_b128 v[134:137], v64 offset:21504
	ds_read_b128 v[138:141], v64 offset:19456
	ds_read_b128 v[142:145], v64 offset:17408
	v_mfma_f32_16x16x32_bf16 v[110:113], v[146:149], v[20:23], v[110:113]
	s_add_u32 s100, s10, 0x11e18100
	s_addc_u32 s101, s11, 0
	s_mov_b32 m0, s16
	s_nop 0
	global_load_lds_dwordx4 v241, s[100:101]
	s_waitcnt lgkmcnt(0)
	v_mfma_f32_16x16x32_bf16 v[42:45], v[142:145], v[16:19], v[42:45]
	v_mfma_f32_16x16x32_bf16 v[50:53], v[138:141], v[16:19], v[50:53]
	v_mfma_f32_16x16x32_bf16 v[38:41], v[134:137], v[16:19], v[38:41]
	v_mfma_f32_16x16x32_bf16 v[74:77], v[130:133], v[16:19], v[74:77]
	v_mfma_f32_16x16x32_bf16 v[66:69], v[126:129], v[16:19], v[66:69]
	v_mfma_f32_16x16x32_bf16 v[70:73], v[122:125], v[16:19], v[70:73]
	ds_read_b128 v[122:125], v64 offset:50176
	ds_read_b128 v[126:129], v64 offset:52224
	ds_read_b128 v[130:133], v64 offset:54272
	ds_read_b128 v[134:137], v64 offset:56320
	v_mfma_f32_16x16x32_bf16 v[60:63], v[118:121], v[16:19], v[60:63]
	ds_read_b128 v[118:121], v64 offset:58368
	ds_read_b128 v[138:141], v64 offset:60416
	ds_read_b128 v[142:145], v64 offset:62464
	ds_read_b128 v[146:149], v64 offset:64512
	v_mfma_f32_16x16x32_bf16 v[78:81], v[114:117], v[16:19], v[78:81]
	s_add_u32 s100, s10, 0x11e10180
	s_addc_u32 s101, s11, 0
	s_mov_b32 m0, s17
	s_nop 0
	global_load_lds_dwordx4 v241, s[100:101]
	s_waitcnt lgkmcnt(0)
	v_mfma_f32_16x16x32_bf16 v[82:85], v[122:125], v[16:19], v[82:85]
	v_mfma_f32_16x16x32_bf16 v[86:89], v[126:129], v[16:19], v[86:89]
	v_mfma_f32_16x16x32_bf16 v[90:93], v[130:133], v[16:19], v[90:93]
	v_mfma_f32_16x16x32_bf16 v[94:97], v[134:137], v[16:19], v[94:97]
	v_mfma_f32_16x16x32_bf16 v[98:101], v[118:121], v[16:19], v[98:101]
	v_mfma_f32_16x16x32_bf16 v[102:105], v[138:141], v[16:19], v[102:105]
	v_mfma_f32_16x16x32_bf16 v[106:109], v[142:145], v[16:19], v[106:109]
	v_mfma_f32_16x16x32_bf16 v[110:113], v[146:149], v[16:19], v[110:113]
	s_add_u32 s100, s10, 0x11e18180
	s_addc_u32 s101, s11, 0
	s_mov_b32 m0, s18
	s_nop 0
	global_load_lds_dwordx4 v241, s[100:101]
	s_waitcnt vmcnt(0)
	s_waitcnt vmcnt(0)
	s_barrier
	v_mov_b32_e32 v37, v48
	ds_read_b128 v[114:117], v37
	ds_read_b128 v[118:121], v37 offset:2048
	s_waitcnt lgkmcnt(0)
	v_mfma_f32_16x16x32_bf16 v[42:45], v[114:117], v[12:15], v[42:45]
	ds_read_b128 v[114:117], v37 offset:4096
	v_mfma_f32_16x16x32_bf16 v[50:53], v[118:121], v[12:15], v[50:53]
	ds_read_b128 v[118:121], v37 offset:6144
	s_waitcnt lgkmcnt(0)
	v_mfma_f32_16x16x32_bf16 v[38:41], v[114:117], v[12:15], v[38:41]
	ds_read_b128 v[114:117], v37 offset:8192
	v_mfma_f32_16x16x32_bf16 v[74:77], v[118:121], v[12:15], v[74:77]
	ds_read_b128 v[118:121], v37 offset:10240
	s_waitcnt lgkmcnt(0)
	v_mfma_f32_16x16x32_bf16 v[66:69], v[114:117], v[12:15], v[66:69]
	ds_read_b128 v[114:117], v37 offset:12288
	ds_read_b128 v[122:125], v37 offset:14336
	v_mfma_f32_16x16x32_bf16 v[70:73], v[118:121], v[12:15], v[70:73]
	ds_read_b128 v[118:121], v37 offset:32768
	ds_read_b128 v[126:129], v37 offset:34816
	ds_read_b128 v[130:133], v37 offset:36864
	ds_read_b128 v[134:137], v37 offset:38912
	s_waitcnt lgkmcnt(0)
	v_mfma_f32_16x16x32_bf16 v[60:63], v[114:117], v[12:15], v[60:63]
	ds_read_b128 v[114:117], v37 offset:40960
	ds_read_b128 v[138:141], v37 offset:43008
	ds_read_b128 v[142:145], v37 offset:45056
	ds_read_b128 v[146:149], v37 offset:47104
	v_mfma_f32_16x16x32_bf16 v[78:81], v[122:125], v[12:15], v[78:81]
	s_add_u32 s100, s10, 0x11e20000
	s_addc_u32 s101, s11, 0
	s_mov_b32 m0, s22
	s_nop 0
	global_load_lds_dwordx4 v241, s[100:101]
	v_mfma_f32_16x16x32_bf16 v[82:85], v[118:121], v[12:15], v[82:85]
	v_mfma_f32_16x16x32_bf16 v[86:89], v[126:129], v[12:15], v[86:89]
	v_mfma_f32_16x16x32_bf16 v[90:93], v[130:133], v[12:15], v[90:93]
	v_mfma_f32_16x16x32_bf16 v[94:97], v[134:137], v[12:15], v[94:97]
	s_waitcnt lgkmcnt(0)
	v_mfma_f32_16x16x32_bf16 v[98:101], v[114:117], v[12:15], v[98:101]
	ds_read_b128 v[114:117], v37 offset:30720
	ds_read_b128 v[118:121], v37 offset:28672
	ds_read_b128 v[122:125], v37 offset:26624
	ds_read_b128 v[126:129], v37 offset:24576
	v_mfma_f32_16x16x32_bf16 v[102:105], v[138:141], v[12:15], v[102:105]
	v_mfma_f32_16x16x32_bf16 v[106:109], v[142:145], v[12:15], v[106:109]
	ds_read_b128 v[130:133], v37 offset:22528
	ds_read_b128 v[134:137], v37 offset:20480
	ds_read_b128 v[138:141], v37 offset:18432
	ds_read_b128 v[142:145], v37 offset:16384
	v_mfma_f32_16x16x32_bf16 v[110:113], v[146:149], v[12:15], v[110:113]
	s_add_u32 s100, s10, 0x11e28000
	s_addc_u32 s101, s11, 0
	s_mov_b32 m0, s21
	s_nop 0
	global_load_lds_dwordx4 v241, s[100:101]
	s_waitcnt lgkmcnt(0)
	v_mfma_f32_16x16x32_bf16 v[42:45], v[142:145], v[8:11], v[42:45]
	v_mfma_f32_16x16x32_bf16 v[50:53], v[138:141], v[8:11], v[50:53]
	v_mfma_f32_16x16x32_bf16 v[38:41], v[134:137], v[8:11], v[38:41]
	v_mfma_f32_16x16x32_bf16 v[74:77], v[130:133], v[8:11], v[74:77]
	v_mfma_f32_16x16x32_bf16 v[66:69], v[126:129], v[8:11], v[66:69]
	v_mfma_f32_16x16x32_bf16 v[70:73], v[122:125], v[8:11], v[70:73]
	ds_read_b128 v[122:125], v37 offset:49152
	ds_read_b128 v[126:129], v37 offset:51200
	ds_read_b128 v[130:133], v37 offset:53248
	ds_read_b128 v[134:137], v37 offset:55296
	v_mfma_f32_16x16x32_bf16 v[60:63], v[118:121], v[8:11], v[60:63]
	ds_read_b128 v[118:121], v37 offset:57344
	ds_read_b128 v[138:141], v37 offset:59392
	ds_read_b128 v[142:145], v37 offset:61440
	ds_read_b128 v[146:149], v37 offset:63488
	v_mfma_f32_16x16x32_bf16 v[78:81], v[114:117], v[8:11], v[78:81]
	s_add_u32 s100, s10, 0x11e20080
	s_addc_u32 s101, s11, 0
	s_mov_b32 m0, s20
	s_nop 0
	global_load_lds_dwordx4 v241, s[100:101]
	s_waitcnt lgkmcnt(0)
	v_mfma_f32_16x16x32_bf16 v[82:85], v[122:125], v[8:11], v[82:85]
	v_mfma_f32_16x16x32_bf16 v[86:89], v[126:129], v[8:11], v[86:89]
	v_mfma_f32_16x16x32_bf16 v[90:93], v[130:133], v[8:11], v[90:93]
	v_mfma_f32_16x16x32_bf16 v[94:97], v[134:137], v[8:11], v[94:97]
	v_mfma_f32_16x16x32_bf16 v[98:101], v[118:121], v[8:11], v[98:101]
	ds_read_b128 v[114:117], v37 offset:15360
	ds_read_b128 v[118:121], v37 offset:13312
	ds_read_b128 v[122:125], v37 offset:11264
	ds_read_b128 v[126:129], v37 offset:9216
	v_mfma_f32_16x16x32_bf16 v[102:105], v[138:141], v[8:11], v[102:105]
	v_mfma_f32_16x16x32_bf16 v[106:109], v[142:145], v[8:11], v[106:109]
	ds_read_b128 v[130:133], v37 offset:7168
	ds_read_b128 v[134:137], v37 offset:5120
	ds_read_b128 v[138:141], v37 offset:3072
	ds_read_b128 v[142:145], v37 offset:1024
	v_mfma_f32_16x16x32_bf16 v[110:113], v[146:149], v[8:11], v[110:113]
	s_add_u32 s100, s10, 0x11e28080
	s_addc_u32 s101, s11, 0
	s_mov_b32 m0, s23
	s_nop 0
	global_load_lds_dwordx4 v241, s[100:101]
	s_waitcnt lgkmcnt(0)
	v_mfma_f32_16x16x32_bf16 v[42:45], v[142:145], v[4:7], v[42:45]
	v_mfma_f32_16x16x32_bf16 v[50:53], v[138:141], v[4:7], v[50:53]
	v_mfma_f32_16x16x32_bf16 v[38:41], v[134:137], v[4:7], v[38:41]
	v_mfma_f32_16x16x32_bf16 v[74:77], v[130:133], v[4:7], v[74:77]
	v_mfma_f32_16x16x32_bf16 v[66:69], v[126:129], v[4:7], v[66:69]
	v_mfma_f32_16x16x32_bf16 v[70:73], v[122:125], v[4:7], v[70:73]
	ds_read_b128 v[122:125], v37 offset:33792
	ds_read_b128 v[126:129], v37 offset:35840
	ds_read_b128 v[130:133], v37 offset:37888
	ds_read_b128 v[134:137], v37 offset:39936
	v_mfma_f32_16x16x32_bf16 v[60:63], v[118:121], v[4:7], v[60:63]
	ds_read_b128 v[118:121], v37 offset:41984
	ds_read_b128 v[138:141], v37 offset:44032
	ds_read_b128 v[142:145], v37 offset:46080
	ds_read_b128 v[146:149], v37 offset:48128
	v_mfma_f32_16x16x32_bf16 v[78:81], v[114:117], v[4:7], v[78:81]
	s_add_u32 s100, s10, 0x11e30000
	s_addc_u32 s101, s11, 0
	s_mov_b32 m0, s24
	s_nop 0
	global_load_lds_dwordx4 v241, s[100:101]
	s_waitcnt lgkmcnt(0)
	v_mfma_f32_16x16x32_bf16 v[82:85], v[122:125], v[4:7], v[82:85]
	v_mfma_f32_16x16x32_bf16 v[86:89], v[126:129], v[4:7], v[86:89]
	v_mfma_f32_16x16x32_bf16 v[90:93], v[130:133], v[4:7], v[90:93]
	v_mfma_f32_16x16x32_bf16 v[94:97], v[134:137], v[4:7], v[94:97]
	v_mfma_f32_16x16x32_bf16 v[98:101], v[118:121], v[4:7], v[98:101]
	ds_read_b128 v[114:117], v37 offset:31744
	ds_read_b128 v[118:121], v37 offset:29696
	ds_read_b128 v[122:125], v37 offset:27648
	ds_read_b128 v[126:129], v37 offset:25600
	v_mfma_f32_16x16x32_bf16 v[102:105], v[138:141], v[4:7], v[102:105]
	v_mfma_f32_16x16x32_bf16 v[106:109], v[142:145], v[4:7], v[106:109]
	ds_read_b128 v[130:133], v37 offset:23552
	ds_read_b128 v[134:137], v37 offset:21504
	ds_read_b128 v[138:141], v37 offset:19456
	ds_read_b128 v[142:145], v37 offset:17408
	v_mfma_f32_16x16x32_bf16 v[110:113], v[146:149], v[4:7], v[110:113]
	s_add_u32 s100, s10, 0x11e38000
	s_addc_u32 s101, s11, 0
	s_mov_b32 m0, s25
	s_nop 0
	global_load_lds_dwordx4 v241, s[100:101]
	s_waitcnt lgkmcnt(0)
	v_mfma_f32_16x16x32_bf16 v[42:45], v[142:145], v[0:3], v[42:45]
	v_mfma_f32_16x16x32_bf16 v[50:53], v[138:141], v[0:3], v[50:53]
	v_mfma_f32_16x16x32_bf16 v[38:41], v[134:137], v[0:3], v[38:41]
	v_mfma_f32_16x16x32_bf16 v[74:77], v[130:133], v[0:3], v[74:77]
	v_mfma_f32_16x16x32_bf16 v[66:69], v[126:129], v[0:3], v[66:69]
	v_mfma_f32_16x16x32_bf16 v[70:73], v[122:125], v[0:3], v[70:73]
	ds_read_b128 v[122:125], v37 offset:50176
	ds_read_b128 v[126:129], v37 offset:52224
	ds_read_b128 v[130:133], v37 offset:54272
	ds_read_b128 v[134:137], v37 offset:56320
	v_mfma_f32_16x16x32_bf16 v[60:63], v[118:121], v[0:3], v[60:63]
	ds_read_b128 v[118:121], v37 offset:58368
	ds_read_b128 v[138:141], v37 offset:60416
	ds_read_b128 v[142:145], v37 offset:62464
	ds_read_b128 v[146:149], v37 offset:64512
	v_mfma_f32_16x16x32_bf16 v[78:81], v[114:117], v[0:3], v[78:81]
	s_add_u32 s100, s10, 0x11e30080
	s_addc_u32 s101, s11, 0
	s_mov_b32 m0, s26
	s_nop 0
	global_load_lds_dwordx4 v241, s[100:101]
	s_waitcnt lgkmcnt(0)
	v_mfma_f32_16x16x32_bf16 v[82:85], v[122:125], v[0:3], v[82:85]
	v_mfma_f32_16x16x32_bf16 v[86:89], v[126:129], v[0:3], v[86:89]
	v_mfma_f32_16x16x32_bf16 v[90:93], v[130:133], v[0:3], v[90:93]
	v_mfma_f32_16x16x32_bf16 v[94:97], v[134:137], v[0:3], v[94:97]
	v_mfma_f32_16x16x32_bf16 v[98:101], v[118:121], v[0:3], v[98:101]
	v_mfma_f32_16x16x32_bf16 v[102:105], v[138:141], v[0:3], v[102:105]
	v_mfma_f32_16x16x32_bf16 v[106:109], v[142:145], v[0:3], v[106:109]
	v_mfma_f32_16x16x32_bf16 v[110:113], v[146:149], v[0:3], v[110:113]
	s_add_u32 s100, s10, 0x11e38080
	s_addc_u32 s101, s11, 0
	s_mov_b32 m0, s27
	s_nop 0
	global_load_lds_dwordx4 v241, s[100:101]
	s_mov_b32 s0, 0x1000000
	v_add_co_u32_e32 v34, vcc, s0, v34
	v_addc_co_u32_e32 v35, vcc, 0, v35, vcc
	v_mbcnt_lo_u32_b32 v212, -1, 0
	v_mbcnt_hi_u32_b32 v212, -1, v212
	v_lshrrev_b32_e32 v212, 4, v212
	v_and_b32_e32 v212, 1, v212
	v_mul_u32_u24_e32 v212, 24, v212
	v_mov_b32_e32 v213, 0
	v_lshl_add_u64 v[214:215], v[32:33], 0, v[212:213]
	v_mul_f32_e32 v200, v36, v42
	v_mul_f32_e32 v204, v36, v43
	v_cvt_pk_bf16_f32 v200, v200, v204
	v_mul_f32_e32 v201, v36, v44
	v_mul_f32_e32 v204, v36, v45
	v_cvt_pk_bf16_f32 v201, v201, v204
	v_mul_f32_e32 v202, v36, v50
	v_mul_f32_e32 v204, v36, v51
	v_cvt_pk_bf16_f32 v202, v202, v204
	v_mul_f32_e32 v203, v36, v52
	v_mul_f32_e32 v204, v36, v53
	v_cvt_pk_bf16_f32 v203, v203, v204
	s_nop 1
	v_permlane16_swap_b32_e32 v200, v202
	v_permlane16_swap_b32_e32 v201, v203
	global_store_dwordx4 v[214:215], v[200:203], off offset:0
	v_mul_f32_e32 v206, v36, v38
	v_mul_f32_e32 v210, v36, v39
	v_cvt_pk_bf16_f32 v206, v206, v210
	v_mul_f32_e32 v207, v36, v40
	v_mul_f32_e32 v210, v36, v41
	v_cvt_pk_bf16_f32 v207, v207, v210
	v_mul_f32_e32 v208, v36, v74
	v_mul_f32_e32 v210, v36, v75
	v_cvt_pk_bf16_f32 v208, v208, v210
	v_mul_f32_e32 v209, v36, v76
	v_mul_f32_e32 v210, v36, v77
	v_cvt_pk_bf16_f32 v209, v209, v210
	s_nop 1
	v_permlane16_swap_b32_e32 v206, v208
	v_permlane16_swap_b32_e32 v207, v209
	global_store_dwordx4 v[214:215], v[206:209], off offset:64
	v_mul_f32_e32 v200, v36, v66
	v_mul_f32_e32 v204, v36, v67
	v_cvt_pk_bf16_f32 v200, v200, v204
	v_mul_f32_e32 v201, v36, v68
	v_mul_f32_e32 v204, v36, v69
	v_cvt_pk_bf16_f32 v201, v201, v204
	v_mul_f32_e32 v202, v36, v70
	v_mul_f32_e32 v204, v36, v71
	v_cvt_pk_bf16_f32 v202, v202, v204
	v_mul_f32_e32 v203, v36, v72
	v_mul_f32_e32 v204, v36, v73
	v_cvt_pk_bf16_f32 v203, v203, v204
	s_nop 1
	v_permlane16_swap_b32_e32 v200, v202
	v_permlane16_swap_b32_e32 v201, v203
	global_store_dwordx4 v[214:215], v[200:203], off offset:128
	v_mul_f32_e32 v206, v36, v60
	v_mul_f32_e32 v210, v36, v61
	v_cvt_pk_bf16_f32 v206, v206, v210
	v_mul_f32_e32 v207, v36, v62
	v_mul_f32_e32 v210, v36, v63
	v_cvt_pk_bf16_f32 v207, v207, v210
	v_mul_f32_e32 v208, v36, v78
	v_mul_f32_e32 v210, v36, v79
	v_cvt_pk_bf16_f32 v208, v208, v210
	v_mul_f32_e32 v209, v36, v80
	v_mul_f32_e32 v210, v36, v81
	v_cvt_pk_bf16_f32 v209, v209, v210
	s_nop 1
	v_permlane16_swap_b32_e32 v206, v208
	v_permlane16_swap_b32_e32 v207, v209
	global_store_dwordx4 v[214:215], v[206:209], off offset:192
	v_mul_f32_e32 v200, v36, v82
	v_mul_f32_e32 v204, v36, v83
	v_cvt_pk_bf16_f32 v200, v200, v204
	v_mul_f32_e32 v201, v36, v84
	v_mul_f32_e32 v204, v36, v85
	v_cvt_pk_bf16_f32 v201, v201, v204
	v_mul_f32_e32 v202, v36, v86
	v_mul_f32_e32 v204, v36, v87
	v_cvt_pk_bf16_f32 v202, v202, v204
	v_mul_f32_e32 v203, v36, v88
	v_mul_f32_e32 v204, v36, v89
	v_cvt_pk_bf16_f32 v203, v203, v204
	s_nop 1
	v_permlane16_swap_b32_e32 v200, v202
	v_permlane16_swap_b32_e32 v201, v203
	global_store_dwordx4 v[214:215], v[200:203], off offset:256
	v_mul_f32_e32 v206, v36, v90
	v_mul_f32_e32 v210, v36, v91
	v_cvt_pk_bf16_f32 v206, v206, v210
	v_mul_f32_e32 v207, v36, v92
	v_mul_f32_e32 v210, v36, v93
	v_cvt_pk_bf16_f32 v207, v207, v210
	v_mul_f32_e32 v208, v36, v94
	v_mul_f32_e32 v210, v36, v95
	v_cvt_pk_bf16_f32 v208, v208, v210
	v_mul_f32_e32 v209, v36, v96
	v_mul_f32_e32 v210, v36, v97
	v_cvt_pk_bf16_f32 v209, v209, v210
	s_nop 1
	v_permlane16_swap_b32_e32 v206, v208
	v_permlane16_swap_b32_e32 v207, v209
	global_store_dwordx4 v[214:215], v[206:209], off offset:320
	v_mul_f32_e32 v200, v36, v98
	v_mul_f32_e32 v204, v36, v99
	v_cvt_pk_bf16_f32 v200, v200, v204
	v_mul_f32_e32 v201, v36, v100
	v_mul_f32_e32 v204, v36, v101
	v_cvt_pk_bf16_f32 v201, v201, v204
	v_mul_f32_e32 v202, v36, v102
	v_mul_f32_e32 v204, v36, v103
	v_cvt_pk_bf16_f32 v202, v202, v204
	v_mul_f32_e32 v203, v36, v104
	v_mul_f32_e32 v204, v36, v105
	v_cvt_pk_bf16_f32 v203, v203, v204
	s_nop 1
	v_permlane16_swap_b32_e32 v200, v202
	v_permlane16_swap_b32_e32 v201, v203
	global_store_dwordx4 v[214:215], v[200:203], off offset:384
	v_mul_f32_e32 v206, v36, v106
	v_mul_f32_e32 v210, v36, v107
	v_cvt_pk_bf16_f32 v206, v206, v210
	v_mul_f32_e32 v207, v36, v108
	v_mul_f32_e32 v210, v36, v109
	v_cvt_pk_bf16_f32 v207, v207, v210
	v_mul_f32_e32 v208, v36, v110
	v_mul_f32_e32 v210, v36, v111
	v_cvt_pk_bf16_f32 v208, v208, v210
	v_mul_f32_e32 v209, v36, v112
	v_mul_f32_e32 v210, v36, v113
	v_cvt_pk_bf16_f32 v209, v209, v210
	s_nop 1
	v_permlane16_swap_b32_e32 v206, v208
	v_permlane16_swap_b32_e32 v207, v209
	global_store_dwordx4 v[214:215], v[206:209], off offset:448
	s_waitcnt vmcnt(0)
	s_waitcnt vmcnt(0)
	s_barrier
	ds_read_b128 v[38:41], v65
	ds_read_b128 v[42:45], v65 offset:2048
	ds_read_b128 v[50:53], v65 offset:4096
	ds_read_b128 v[54:57], v65 offset:6144
	ds_read_b128 v[58:61], v65 offset:8192
	ds_read_b128 v[66:69], v65 offset:10240
	ds_read_b128 v[70:73], v65 offset:12288
	ds_read_b128 v[74:77], v65 offset:14336
	ds_read_b128 v[78:81], v65 offset:32768
	ds_read_b128 v[82:85], v65 offset:34816
	ds_read_b128 v[86:89], v65 offset:36864
	ds_read_b128 v[90:93], v65 offset:38912
	ds_read_b128 v[94:97], v65 offset:40960
	ds_read_b128 v[98:101], v65 offset:43008
	ds_read_b128 v[102:105], v65 offset:45056
	ds_read_b128 v[106:109], v65 offset:47104
	s_waitcnt lgkmcnt(0)
	v_mfma_f32_16x16x32_bf16 v[38:41], v[38:41], v[28:31], 0
	v_mfma_f32_16x16x32_bf16 v[42:45], v[42:45], v[28:31], 0
	v_mfma_f32_16x16x32_bf16 v[50:53], v[50:53], v[28:31], 0
	v_mfma_f32_16x16x32_bf16 v[54:57], v[54:57], v[28:31], 0
	v_mfma_f32_16x16x32_bf16 v[58:61], v[58:61], v[28:31], 0
	v_mfma_f32_16x16x32_bf16 v[66:69], v[66:69], v[28:31], 0
	v_mfma_f32_16x16x32_bf16 v[70:73], v[70:73], v[28:31], 0
	v_mfma_f32_16x16x32_bf16 v[74:77], v[74:77], v[28:31], 0
	s_add_u32 s100, s10, 0x11e20100
	s_addc_u32 s101, s11, 0
	s_mov_b32 m0, s19
	s_nop 0
	global_load_lds_dwordx4 v241, s[100:101]
	ds_read_b128 v[110:113], v65 offset:30720
	ds_read_b128 v[114:117], v65 offset:28672
	ds_read_b128 v[118:121], v65 offset:26624
	ds_read_b128 v[122:125], v65 offset:24576
	ds_read_b128 v[126:129], v65 offset:22528
	ds_read_b128 v[130:133], v65 offset:20480
	ds_read_b128 v[134:137], v65 offset:18432
	ds_read_b128 v[138:141], v65 offset:16384
	v_mfma_f32_16x16x32_bf16 v[78:81], v[78:81], v[28:31], 0
	v_mfma_f32_16x16x32_bf16 v[82:85], v[82:85], v[28:31], 0
	v_mfma_f32_16x16x32_bf16 v[86:89], v[86:89], v[28:31], 0
	v_mfma_f32_16x16x32_bf16 v[90:93], v[90:93], v[28:31], 0
	v_mfma_f32_16x16x32_bf16 v[94:97], v[94:97], v[28:31], 0
	v_mfma_f32_16x16x32_bf16 v[98:101], v[98:101], v[28:31], 0
	v_mfma_f32_16x16x32_bf16 v[102:105], v[102:105], v[28:31], 0
	v_mfma_f32_16x16x32_bf16 v[28:31], v[106:109], v[28:31], 0
	s_add_u32 s100, s10, 0x11e28100
	s_addc_u32 s101, s11, 0
	s_mov_b32 m0, s13
	s_nop 0
	global_load_lds_dwordx4 v241, s[100:101]
	s_waitcnt lgkmcnt(0)
	v_mfma_f32_16x16x32_bf16 v[38:41], v[138:141], v[24:27], v[38:41]
	v_mfma_f32_16x16x32_bf16 v[42:45], v[134:137], v[24:27], v[42:45]
	v_mfma_f32_16x16x32_bf16 v[50:53], v[130:133], v[24:27], v[50:53]
	v_mfma_f32_16x16x32_bf16 v[54:57], v[126:129], v[24:27], v[54:57]
	v_mfma_f32_16x16x32_bf16 v[58:61], v[122:125], v[24:27], v[58:61]
	v_mfma_f32_16x16x32_bf16 v[66:69], v[118:121], v[24:27], v[66:69]
	ds_read_b128 v[106:109], v65 offset:49152
	ds_read_b128 v[118:121], v65 offset:51200
	ds_read_b128 v[122:125], v65 offset:53248
	ds_read_b128 v[126:129], v65 offset:55296
	v_mfma_f32_16x16x32_bf16 v[70:73], v[114:117], v[24:27], v[70:73]
	ds_read_b128 v[114:117], v65 offset:57344
	ds_read_b128 v[130:133], v65 offset:59392
	ds_read_b128 v[134:137], v65 offset:61440
	ds_read_b128 v[138:141], v65 offset:63488
	v_mfma_f32_16x16x32_bf16 v[74:77], v[110:113], v[24:27], v[74:77]
	s_add_u32 s100, s10, 0x11e20180
	s_addc_u32 s101, s11, 0
	s_mov_b32 m0, s12
	s_nop 0
	global_load_lds_dwordx4 v241, s[100:101]
	s_waitcnt lgkmcnt(0)
	v_mfma_f32_16x16x32_bf16 v[78:81], v[106:109], v[24:27], v[78:81]
	v_mfma_f32_16x16x32_bf16 v[82:85], v[118:121], v[24:27], v[82:85]
	v_mfma_f32_16x16x32_bf16 v[86:89], v[122:125], v[24:27], v[86:89]
	v_mfma_f32_16x16x32_bf16 v[90:93], v[126:129], v[24:27], v[90:93]
	v_mfma_f32_16x16x32_bf16 v[94:97], v[114:117], v[24:27], v[94:97]
	ds_read_b128 v[106:109], v65 offset:15360
	ds_read_b128 v[110:113], v65 offset:13312
	ds_read_b128 v[114:117], v65 offset:11264
	ds_read_b128 v[118:121], v65 offset:9216
	v_mfma_f32_16x16x32_bf16 v[98:101], v[130:133], v[24:27], v[98:101]
	v_mfma_f32_16x16x32_bf16 v[102:105], v[134:137], v[24:27], v[102:105]
	ds_read_b128 v[122:125], v65 offset:7168
	ds_read_b128 v[126:129], v65 offset:5120
	ds_read_b128 v[130:133], v65 offset:3072
	ds_read_b128 v[134:137], v65 offset:1024
	v_mfma_f32_16x16x32_bf16 v[24:27], v[138:141], v[24:27], v[28:31]
	s_add_u32 s100, s10, 0x11e28180
	s_addc_u32 s101, s11, 0
	s_mov_b32 m0, s14
	s_nop 0
	global_load_lds_dwordx4 v241, s[100:101]
	s_waitcnt lgkmcnt(0)
	v_mfma_f32_16x16x32_bf16 v[28:31], v[134:137], v[20:23], v[38:41]
	v_mfma_f32_16x16x32_bf16 v[38:41], v[130:133], v[20:23], v[42:45]
	v_mfma_f32_16x16x32_bf16 v[42:45], v[126:129], v[20:23], v[50:53]
	v_mfma_f32_16x16x32_bf16 v[50:53], v[122:125], v[20:23], v[54:57]
	v_mfma_f32_16x16x32_bf16 v[54:57], v[118:121], v[20:23], v[58:61]
	v_mfma_f32_16x16x32_bf16 v[58:61], v[114:117], v[20:23], v[66:69]
	s_nop 2
	ds_read_b128 v[66:69], v65 offset:33792
	ds_read_b128 v[114:117], v65 offset:35840
	ds_read_b128 v[118:121], v65 offset:37888
	ds_read_b128 v[122:125], v65 offset:39936
	v_mfma_f32_16x16x32_bf16 v[70:73], v[110:113], v[20:23], v[70:73]
	ds_read_b128 v[110:113], v65 offset:41984
	ds_read_b128 v[126:129], v65 offset:44032
	ds_read_b128 v[130:133], v65 offset:46080
	ds_read_b128 v[134:137], v65 offset:48128
	v_mfma_f32_16x16x32_bf16 v[74:77], v[106:109], v[20:23], v[74:77]
	s_add_u32 s100, s10, 0x11e30100
	s_addc_u32 s101, s11, 0
	s_mov_b32 m0, s15
	s_nop 0
	global_load_lds_dwordx4 v241, s[100:101]
	s_waitcnt lgkmcnt(0)
	v_mfma_f32_16x16x32_bf16 v[66:69], v[66:69], v[20:23], v[78:81]
	v_mfma_f32_16x16x32_bf16 v[78:81], v[114:117], v[20:23], v[82:85]
	v_mfma_f32_16x16x32_bf16 v[82:85], v[118:121], v[20:23], v[86:89]
	v_mfma_f32_16x16x32_bf16 v[86:89], v[122:125], v[20:23], v[90:93]
	v_mfma_f32_16x16x32_bf16 v[90:93], v[110:113], v[20:23], v[94:97]
	v_mfma_f32_16x16x32_bf16 v[94:97], v[126:129], v[20:23], v[98:101]
	s_nop 2
	ds_read_b128 v[98:101], v65 offset:31744
	ds_read_b128 v[106:109], v65 offset:29696
	ds_read_b128 v[110:113], v65 offset:27648
	ds_read_b128 v[114:117], v65 offset:25600
	v_mfma_f32_16x16x32_bf16 v[102:105], v[130:133], v[20:23], v[102:105]
	ds_read_b128 v[118:121], v65 offset:23552
	ds_read_b128 v[122:125], v65 offset:21504
	ds_read_b128 v[126:129], v65 offset:19456
	ds_read_b128 v[130:133], v65 offset:17408
	v_mfma_f32_16x16x32_bf16 v[20:23], v[134:137], v[20:23], v[24:27]
	s_add_u32 s100, s10, 0x11e38100
	s_addc_u32 s101, s11, 0
	s_mov_b32 m0, s16
	s_nop 0
	global_load_lds_dwordx4 v241, s[100:101]
	s_waitcnt lgkmcnt(0)
	v_mfma_f32_16x16x32_bf16 v[24:27], v[130:133], v[16:19], v[28:31]
	v_mfma_f32_16x16x32_bf16 v[28:31], v[126:129], v[16:19], v[38:41]
	v_mfma_f32_16x16x32_bf16 v[38:41], v[122:125], v[16:19], v[42:45]
	v_mfma_f32_16x16x32_bf16 v[42:45], v[118:121], v[16:19], v[50:53]
	v_mfma_f32_16x16x32_bf16 v[50:53], v[114:117], v[16:19], v[54:57]
	v_mfma_f32_16x16x32_bf16 v[54:57], v[110:113], v[16:19], v[58:61]
	s_nop 2
	ds_read_b128 v[58:61], v65 offset:50176
	ds_read_b128 v[110:113], v65 offset:52224
	ds_read_b128 v[114:117], v65 offset:54272
	ds_read_b128 v[118:121], v65 offset:56320
	v_mfma_f32_16x16x32_bf16 v[70:73], v[106:109], v[16:19], v[70:73]
	ds_read_b128 v[106:109], v65 offset:58368
	ds_read_b128 v[122:125], v65 offset:60416
	ds_read_b128 v[126:129], v65 offset:62464
	ds_read_b128 v[62:65], v65 offset:64512
	v_mfma_f32_16x16x32_bf16 v[74:77], v[98:101], v[16:19], v[74:77]
	s_add_u32 s100, s10, 0x11e30180
	s_addc_u32 s101, s11, 0
	s_mov_b32 m0, s17
	s_nop 0
	global_load_lds_dwordx4 v241, s[100:101]
	s_waitcnt lgkmcnt(0)
	v_mfma_f32_16x16x32_bf16 v[58:61], v[58:61], v[16:19], v[66:69]
	v_mfma_f32_16x16x32_bf16 v[66:69], v[110:113], v[16:19], v[78:81]
	v_mfma_f32_16x16x32_bf16 v[78:81], v[114:117], v[16:19], v[82:85]
	v_mfma_f32_16x16x32_bf16 v[82:85], v[118:121], v[16:19], v[86:89]
	v_mfma_f32_16x16x32_bf16 v[86:89], v[106:109], v[16:19], v[90:93]
	v_mfma_f32_16x16x32_bf16 v[90:93], v[122:125], v[16:19], v[94:97]
	v_mfma_f32_16x16x32_bf16 v[94:97], v[126:129], v[16:19], v[102:105]
	v_mfma_f32_16x16x32_bf16 v[16:19], v[62:65], v[16:19], v[20:23]
	s_add_u32 s100, s10, 0x11e38180
	s_addc_u32 s101, s11, 0
	s_mov_b32 m0, s18
	s_nop 0
	global_load_lds_dwordx4 v241, s[100:101]
	s_waitcnt vmcnt(0)
	s_waitcnt vmcnt(0)
	s_barrier
	s_nop 0
	ds_read_b128 v[20:23], v48
	ds_read_b128 v[62:65], v48 offset:2048
	s_waitcnt lgkmcnt(1)
	v_mfma_f32_16x16x32_bf16 v[20:23], v[20:23], v[12:15], v[24:27]
	s_nop 2
	ds_read_b128 v[24:27], v48 offset:4096
	s_waitcnt lgkmcnt(1)
	v_mfma_f32_16x16x32_bf16 v[28:31], v[62:65], v[12:15], v[28:31]
	ds_read_b128 v[62:65], v48 offset:6144
	s_waitcnt lgkmcnt(1)
	v_mfma_f32_16x16x32_bf16 v[24:27], v[24:27], v[12:15], v[38:41]
	s_nop 2
	ds_read_b128 v[38:41], v48 offset:8192
	s_waitcnt lgkmcnt(1)
	v_mfma_f32_16x16x32_bf16 v[42:45], v[62:65], v[12:15], v[42:45]
	ds_read_b128 v[62:65], v48 offset:10240
	s_waitcnt lgkmcnt(1)
	v_mfma_f32_16x16x32_bf16 v[38:41], v[38:41], v[12:15], v[50:53]
	s_nop 2
	ds_read_b128 v[50:53], v48 offset:12288
	ds_read_b128 v[98:101], v48 offset:14336
	s_waitcnt lgkmcnt(2)
	v_mfma_f32_16x16x32_bf16 v[54:57], v[62:65], v[12:15], v[54:57]
	ds_read_b128 v[62:65], v48 offset:32768
	ds_read_b128 v[102:105], v48 offset:34816
	ds_read_b128 v[106:109], v48 offset:36864
	ds_read_b128 v[110:113], v48 offset:38912
	s_waitcnt lgkmcnt(5)
	v_mfma_f32_16x16x32_bf16 v[50:53], v[50:53], v[12:15], v[70:73]
	s_nop 2
	ds_read_b128 v[70:73], v48 offset:40960
	ds_read_b128 v[114:117], v48 offset:43008
	ds_read_b128 v[118:121], v48 offset:45056
	ds_read_b128 v[122:125], v48 offset:47104
	s_waitcnt lgkmcnt(8)
	v_mfma_f32_16x16x32_bf16 v[74:77], v[98:101], v[12:15], v[74:77]
	s_waitcnt lgkmcnt(7)
	v_mfma_f32_16x16x32_bf16 v[58:61], v[62:65], v[12:15], v[58:61]
	s_waitcnt lgkmcnt(6)
	v_mfma_f32_16x16x32_bf16 v[62:65], v[102:105], v[12:15], v[66:69]
	s_waitcnt lgkmcnt(5)
	v_mfma_f32_16x16x32_bf16 v[66:69], v[106:109], v[12:15], v[78:81]
	s_waitcnt lgkmcnt(4)
	v_mfma_f32_16x16x32_bf16 v[78:81], v[110:113], v[12:15], v[82:85]
	s_waitcnt lgkmcnt(3)
	v_mfma_f32_16x16x32_bf16 v[70:73], v[70:73], v[12:15], v[86:89]
	s_waitcnt lgkmcnt(2)
	v_mfma_f32_16x16x32_bf16 v[82:85], v[114:117], v[12:15], v[90:93]
	s_nop 0
	ds_read_b128 v[86:89], v48 offset:30720
	s_nop 0
	ds_read_b128 v[90:93], v48 offset:28672
	ds_read_b128 v[98:101], v48 offset:26624
	ds_read_b128 v[102:105], v48 offset:24576
	s_waitcnt lgkmcnt(5)
	v_mfma_f32_16x16x32_bf16 v[94:97], v[118:121], v[12:15], v[94:97]
	ds_read_b128 v[106:109], v48 offset:22528
	ds_read_b128 v[110:113], v48 offset:20480
	ds_read_b128 v[114:117], v48 offset:18432
	ds_read_b128 v[118:121], v48 offset:16384
	s_waitcnt lgkmcnt(8)
	v_mfma_f32_16x16x32_bf16 v[12:15], v[122:125], v[12:15], v[16:19]
	s_waitcnt lgkmcnt(0)
	v_mfma_f32_16x16x32_bf16 v[16:19], v[118:121], v[8:11], v[20:23]
	v_mfma_f32_16x16x32_bf16 v[20:23], v[114:117], v[8:11], v[28:31]
	v_mfma_f32_16x16x32_bf16 v[24:27], v[110:113], v[8:11], v[24:27]
	v_mfma_f32_16x16x32_bf16 v[28:31], v[106:109], v[8:11], v[42:45]
	v_mfma_f32_16x16x32_bf16 v[38:41], v[102:105], v[8:11], v[38:41]
	v_mfma_f32_16x16x32_bf16 v[42:45], v[98:101], v[8:11], v[54:57]
	s_nop 2
	ds_read_b128 v[54:57], v48 offset:49152
	ds_read_b128 v[98:101], v48 offset:51200
	ds_read_b128 v[102:105], v48 offset:53248
	ds_read_b128 v[106:109], v48 offset:55296
	v_mfma_f32_16x16x32_bf16 v[50:53], v[90:93], v[8:11], v[50:53]
	ds_read_b128 v[90:93], v48 offset:57344
	ds_read_b128 v[110:113], v48 offset:59392
	ds_read_b128 v[114:117], v48 offset:61440
	ds_read_b128 v[118:121], v48 offset:63488
	v_mfma_f32_16x16x32_bf16 v[74:77], v[86:89], v[8:11], v[74:77]
	s_waitcnt lgkmcnt(7)
	v_mfma_f32_16x16x32_bf16 v[54:57], v[54:57], v[8:11], v[58:61]
	s_waitcnt lgkmcnt(6)
	v_mfma_f32_16x16x32_bf16 v[58:61], v[98:101], v[8:11], v[62:65]
	s_waitcnt lgkmcnt(5)
	v_mfma_f32_16x16x32_bf16 v[62:65], v[102:105], v[8:11], v[66:69]
	s_waitcnt lgkmcnt(4)
	v_mfma_f32_16x16x32_bf16 v[66:69], v[106:109], v[8:11], v[78:81]
	s_waitcnt lgkmcnt(3)
	v_mfma_f32_16x16x32_bf16 v[70:73], v[90:93], v[8:11], v[70:73]
	s_waitcnt lgkmcnt(2)
	v_mfma_f32_16x16x32_bf16 v[78:81], v[110:113], v[8:11], v[82:85]
	s_nop 2
	ds_read_b128 v[82:85], v48 offset:15360
	ds_read_b128 v[86:89], v48 offset:13312
	ds_read_b128 v[90:93], v48 offset:11264
	ds_read_b128 v[98:101], v48 offset:9216
	s_waitcnt lgkmcnt(5)
	v_mfma_f32_16x16x32_bf16 v[94:97], v[114:117], v[8:11], v[94:97]
	ds_read_b128 v[102:105], v48 offset:7168
	ds_read_b128 v[106:109], v48 offset:5120
	ds_read_b128 v[110:113], v48 offset:3072
	ds_read_b128 v[114:117], v48 offset:1024
	s_waitcnt lgkmcnt(8)
	v_mfma_f32_16x16x32_bf16 v[8:11], v[118:121], v[8:11], v[12:15]
	s_waitcnt lgkmcnt(0)
	v_mfma_f32_16x16x32_bf16 v[12:15], v[114:117], v[4:7], v[16:19]
	v_mfma_f32_16x16x32_bf16 v[16:19], v[110:113], v[4:7], v[20:23]
	v_mfma_f32_16x16x32_bf16 v[20:23], v[106:109], v[4:7], v[24:27]
	v_mfma_f32_16x16x32_bf16 v[24:27], v[102:105], v[4:7], v[28:31]
	v_mfma_f32_16x16x32_bf16 v[28:31], v[98:101], v[4:7], v[38:41]
	v_mfma_f32_16x16x32_bf16 v[38:41], v[90:93], v[4:7], v[42:45]
	s_nop 2
	ds_read_b128 v[42:45], v48 offset:33792
	ds_read_b128 v[90:93], v48 offset:35840
	ds_read_b128 v[98:101], v48 offset:37888
	ds_read_b128 v[102:105], v48 offset:39936
	v_mfma_f32_16x16x32_bf16 v[50:53], v[86:89], v[4:7], v[50:53]
	ds_read_b128 v[86:89], v48 offset:41984
	ds_read_b128 v[106:109], v48 offset:44032
	ds_read_b128 v[110:113], v48 offset:46080
	ds_read_b128 v[114:117], v48 offset:48128
	v_mfma_f32_16x16x32_bf16 v[74:77], v[82:85], v[4:7], v[74:77]
	s_waitcnt lgkmcnt(7)
	v_mfma_f32_16x16x32_bf16 v[42:45], v[42:45], v[4:7], v[54:57]
	s_waitcnt lgkmcnt(6)
	v_mfma_f32_16x16x32_bf16 v[54:57], v[90:93], v[4:7], v[58:61]
	s_waitcnt lgkmcnt(5)
	v_mfma_f32_16x16x32_bf16 v[58:61], v[98:101], v[4:7], v[62:65]
	s_waitcnt lgkmcnt(4)
	v_mfma_f32_16x16x32_bf16 v[62:65], v[102:105], v[4:7], v[66:69]
	s_waitcnt lgkmcnt(3)
	v_mfma_f32_16x16x32_bf16 v[66:69], v[86:89], v[4:7], v[70:73]
	s_waitcnt lgkmcnt(2)
	v_mfma_f32_16x16x32_bf16 v[70:73], v[106:109], v[4:7], v[78:81]
	s_nop 2
	ds_read_b128 v[78:81], v48 offset:31744
	ds_read_b128 v[82:85], v48 offset:29696
	ds_read_b128 v[86:89], v48 offset:27648
	ds_read_b128 v[90:93], v48 offset:25600
	s_waitcnt lgkmcnt(5)
	v_mfma_f32_16x16x32_bf16 v[94:97], v[110:113], v[4:7], v[94:97]
	ds_read_b128 v[98:101], v48 offset:23552
	ds_read_b128 v[102:105], v48 offset:21504
	ds_read_b128 v[106:109], v48 offset:19456
	ds_read_b128 v[110:113], v48 offset:17408
	s_waitcnt lgkmcnt(8)
	v_mfma_f32_16x16x32_bf16 v[4:7], v[114:117], v[4:7], v[8:11]
	s_waitcnt lgkmcnt(0)
	v_mfma_f32_16x16x32_bf16 v[8:11], v[110:113], v[0:3], v[12:15]
	v_mfma_f32_16x16x32_bf16 v[12:15], v[106:109], v[0:3], v[16:19]
	v_mfma_f32_16x16x32_bf16 v[16:19], v[102:105], v[0:3], v[20:23]
	v_mfma_f32_16x16x32_bf16 v[20:23], v[98:101], v[0:3], v[24:27]
	v_mfma_f32_16x16x32_bf16 v[24:27], v[90:93], v[0:3], v[28:31]
	v_mfma_f32_16x16x32_bf16 v[28:31], v[86:89], v[0:3], v[38:41]
	s_nop 2
	ds_read_b128 v[38:41], v48 offset:50176
	ds_read_b128 v[86:89], v48 offset:52224
	ds_read_b128 v[90:93], v48 offset:54272
	ds_read_b128 v[98:101], v48 offset:56320
	v_mfma_f32_16x16x32_bf16 v[50:53], v[82:85], v[0:3], v[50:53]
	ds_read_b128 v[82:85], v48 offset:58368
	ds_read_b128 v[102:105], v48 offset:60416
	ds_read_b128 v[106:109], v48 offset:62464
	ds_read_b128 v[46:49], v48 offset:64512
	v_mfma_f32_16x16x32_bf16 v[74:77], v[78:81], v[0:3], v[74:77]
	s_waitcnt lgkmcnt(7)
	v_mfma_f32_16x16x32_bf16 v[38:41], v[38:41], v[0:3], v[42:45]
	s_waitcnt lgkmcnt(6)
	v_mfma_f32_16x16x32_bf16 v[42:45], v[86:89], v[0:3], v[54:57]
	s_waitcnt lgkmcnt(5)
	v_mfma_f32_16x16x32_bf16 v[54:57], v[90:93], v[0:3], v[58:61]
	s_waitcnt lgkmcnt(4)
	v_mfma_f32_16x16x32_bf16 v[58:61], v[98:101], v[0:3], v[62:65]
	s_waitcnt lgkmcnt(3)
	v_mfma_f32_16x16x32_bf16 v[62:65], v[82:85], v[0:3], v[66:69]
	s_waitcnt lgkmcnt(2)
	v_mfma_f32_16x16x32_bf16 v[66:69], v[102:105], v[0:3], v[70:73]
	s_waitcnt lgkmcnt(1)
	v_mfma_f32_16x16x32_bf16 v[70:73], v[106:109], v[0:3], v[94:97]
	s_waitcnt lgkmcnt(0)
	v_mfma_f32_16x16x32_bf16 v[0:3], v[46:49], v[0:3], v[4:7]
	s_nop 2
	v_mul_f32_e32 v200, v36, v8
	v_mul_f32_e32 v204, v36, v9
	v_cvt_pk_bf16_f32 v200, v200, v204
	v_mul_f32_e32 v201, v36, v10
	v_mul_f32_e32 v204, v36, v11
	v_cvt_pk_bf16_f32 v201, v201, v204
	v_mul_f32_e32 v202, v36, v12
	v_mul_f32_e32 v204, v36, v13
	v_cvt_pk_bf16_f32 v202, v202, v204
	v_mul_f32_e32 v203, v36, v14
	v_mul_f32_e32 v204, v36, v15
	v_cvt_pk_bf16_f32 v203, v203, v204
	s_nop 1
	v_permlane16_swap_b32_e32 v200, v202
	v_permlane16_swap_b32_e32 v201, v203
	global_store_dwordx4 v[214:215], v[200:203], off offset:512
	v_mul_f32_e32 v206, v36, v16
	v_mul_f32_e32 v210, v36, v17
	v_cvt_pk_bf16_f32 v206, v206, v210
	v_mul_f32_e32 v207, v36, v18
	v_mul_f32_e32 v210, v36, v19
	v_cvt_pk_bf16_f32 v207, v207, v210
	v_mul_f32_e32 v208, v36, v20
	v_mul_f32_e32 v210, v36, v21
	v_cvt_pk_bf16_f32 v208, v208, v210
	v_mul_f32_e32 v209, v36, v22
	v_mul_f32_e32 v210, v36, v23
	v_cvt_pk_bf16_f32 v209, v209, v210
	s_nop 1
	v_permlane16_swap_b32_e32 v206, v208
	v_permlane16_swap_b32_e32 v207, v209
	global_store_dwordx4 v[214:215], v[206:209], off offset:576
	v_mul_f32_e32 v200, v36, v24
	v_mul_f32_e32 v204, v36, v25
	v_cvt_pk_bf16_f32 v200, v200, v204
	v_mul_f32_e32 v201, v36, v26
	v_mul_f32_e32 v204, v36, v27
	v_cvt_pk_bf16_f32 v201, v201, v204
	v_mul_f32_e32 v202, v36, v28
	v_mul_f32_e32 v204, v36, v29
	v_cvt_pk_bf16_f32 v202, v202, v204
	v_mul_f32_e32 v203, v36, v30
	v_mul_f32_e32 v204, v36, v31
	v_cvt_pk_bf16_f32 v203, v203, v204
	s_nop 1
	v_permlane16_swap_b32_e32 v200, v202
	v_permlane16_swap_b32_e32 v201, v203
	global_store_dwordx4 v[214:215], v[200:203], off offset:640
	v_mul_f32_e32 v206, v36, v50
	v_mul_f32_e32 v210, v36, v51
	v_cvt_pk_bf16_f32 v206, v206, v210
	v_mul_f32_e32 v207, v36, v52
	v_mul_f32_e32 v210, v36, v53
	v_cvt_pk_bf16_f32 v207, v207, v210
	v_mul_f32_e32 v208, v36, v74
	v_mul_f32_e32 v210, v36, v75
	v_cvt_pk_bf16_f32 v208, v208, v210
	v_mul_f32_e32 v209, v36, v76
	v_mul_f32_e32 v210, v36, v77
	v_cvt_pk_bf16_f32 v209, v209, v210
	s_nop 1
	v_permlane16_swap_b32_e32 v206, v208
	v_permlane16_swap_b32_e32 v207, v209
	global_store_dwordx4 v[214:215], v[206:209], off offset:704
	v_mul_f32_e32 v200, v36, v38
	v_mul_f32_e32 v204, v36, v39
	v_cvt_pk_bf16_f32 v200, v200, v204
	v_mul_f32_e32 v201, v36, v40
	v_mul_f32_e32 v204, v36, v41
	v_cvt_pk_bf16_f32 v201, v201, v204
	v_mul_f32_e32 v202, v36, v42
	v_mul_f32_e32 v204, v36, v43
	v_cvt_pk_bf16_f32 v202, v202, v204
	v_mul_f32_e32 v203, v36, v44
	v_mul_f32_e32 v204, v36, v45
	v_cvt_pk_bf16_f32 v203, v203, v204
	s_nop 1
	v_permlane16_swap_b32_e32 v200, v202
	v_permlane16_swap_b32_e32 v201, v203
	global_store_dwordx4 v[214:215], v[200:203], off offset:768
	v_mul_f32_e32 v206, v36, v54
	v_mul_f32_e32 v210, v36, v55
	v_cvt_pk_bf16_f32 v206, v206, v210
	v_mul_f32_e32 v207, v36, v56
	v_mul_f32_e32 v210, v36, v57
	v_cvt_pk_bf16_f32 v207, v207, v210
	v_mul_f32_e32 v208, v36, v58
	v_mul_f32_e32 v210, v36, v59
	v_cvt_pk_bf16_f32 v208, v208, v210
	v_mul_f32_e32 v209, v36, v60
	v_mul_f32_e32 v210, v36, v61
	v_cvt_pk_bf16_f32 v209, v209, v210
	s_nop 1
	v_permlane16_swap_b32_e32 v206, v208
	v_permlane16_swap_b32_e32 v207, v209
	global_store_dwordx4 v[214:215], v[206:209], off offset:832
	v_mul_f32_e32 v200, v36, v62
	v_mul_f32_e32 v204, v36, v63
	v_cvt_pk_bf16_f32 v200, v200, v204
	v_mul_f32_e32 v201, v36, v64
	v_mul_f32_e32 v204, v36, v65
	v_cvt_pk_bf16_f32 v201, v201, v204
	v_mul_f32_e32 v202, v36, v66
	v_mul_f32_e32 v204, v36, v67
	v_cvt_pk_bf16_f32 v202, v202, v204
	v_mul_f32_e32 v203, v36, v68
	v_mul_f32_e32 v204, v36, v69
	v_cvt_pk_bf16_f32 v203, v203, v204
	s_nop 1
	v_permlane16_swap_b32_e32 v200, v202
	v_permlane16_swap_b32_e32 v201, v203
	global_store_dwordx4 v[214:215], v[200:203], off offset:896
	v_mul_f32_e32 v206, v36, v70
	v_mul_f32_e32 v210, v36, v71
	v_cvt_pk_bf16_f32 v206, v206, v210
	v_mul_f32_e32 v207, v36, v72
	v_mul_f32_e32 v210, v36, v73
	v_cvt_pk_bf16_f32 v207, v207, v210
	v_mul_f32_e32 v208, v36, v0
	v_mul_f32_e32 v210, v36, v1
	v_cvt_pk_bf16_f32 v208, v208, v210
	v_mul_f32_e32 v209, v36, v2
	v_mul_f32_e32 v210, v36, v3
	v_cvt_pk_bf16_f32 v209, v209, v210
	s_nop 1
	v_permlane16_swap_b32_e32 v206, v208
	v_permlane16_swap_b32_e32 v207, v209
	global_store_dwordx4 v[214:215], v[206:209], off offset:960
	s_waitcnt vmcnt(0)
	s_barrier
